# as v40 but GEMM K-loops run at one flat priority: per-segment s_setprio flips deleted and no static raise for either wave group
# baseline (speedup 1.0000x reference)
; #define PG8_STAGE(bufoff, gbase, voff) do { _Pragma("unroll") for (int _i = 0; _i < 2; ++_i) \
;         __builtin_amdgcn_global_load_lds((const unsigned*)((const char*)(gbase) + (voff)[_i]), (LAS unsigned*)(lds + (bufoff) + ldsw + _i * 8192), 16, 0, 0); } while (0)
; #define PG8_LDA(dst, b, h) do { _Pragma("unroll") for (int m = 0; m < 4; ++m) _Pragma("unroll") for (int k = 0; k < 2; ++k) dst[m][k] = *(const LAS bf16x8*)(lds + PG8_SA(b, h) + aoff + m * 2048 + k * 1024); } while (0)
; #define PG8_LDB(dst, b, h) do { _Pragma("unroll") for (int n = 0; n < 2; ++n) _Pragma("unroll") for (int k = 0; k < 2; ++k) dst[n][k] = *(const LAS bf16x8*)(lds + PG8_SB(b, h) + boff + n * 2048 + k * 1024); } while (0)
; #define PG8_MMA(ai, bj, At, Bt) do { __builtin_amdgcn_s_setprio(1); _Pragma("unroll") for (int m = 0; m < 4; ++m) _Pragma("unroll") for (int n = 0; n < 2; ++n) _Pragma("unroll") for (int k = 0; k < 2; ++k) \
;         acc[ai][bj][m][n] = __builtin_amdgcn_mfma_f32_16x16x32_bf16(Bt[n][k], At[m][k], acc[ai][bj][m][n], 0, 0, 0); __builtin_amdgcn_s_setprio(0); } while (0)
; #define PG8_WAIT_V(n) asm volatile("s_waitcnt vmcnt(" #n ")" ::: "memory")
; #define PG8_WAIT_L(n) asm volatile("s_waitcnt lgkmcnt(" #n ")" ::: "memory")
; #define PG8_BAR __builtin_amdgcn_s_barrier()
; #define PG8_SCHED __builtin_amdgcn_sched_barrier(0)
; template <class Epi, bool ALIGN_EPI>
; __device__ __forceinline__ void gemm_phase(LAS unsigned char* lds, const Gemm g, const StaticOrder S, const Epi E) {
;     ...
;             const bool last = (t == nt - 2);
;             const char* a1 = cA + (size_t)(t + 1) * kstep;
;             const char* a2 = last ? nA : cA + (size_t)(t + 2) * kstep; const char* b2 = last ? nB : cB + (size_t)(t + 2) * kstep;
;             const char* a3 = a2 + kstep; const char* b3 = b2 + kstep;
;             PG8_LDB(B0, 0, 0); PG8_LDB(B1, 0, 1); PG8_SCHED; PG8_LDA(At, 0, 0); PG8_STAGE(PG8_SA(1, 1), a1 + hstepA, voffA);
;             PG8_WAIT_V(8); PG8_WAIT_L(0); PG8_BAR; PG8_MMA(0, 0, At, B0); PG8_MMA(0, 1, At, B1); PG8_BAR; PG8_SCHED;
;             PG8_LDA(At, 0, 1); PG8_STAGE(PG8_SB(0, 0), b2, voffB); PG8_STAGE(PG8_SB(0, 1), b2 + hstepB, voffB); PG8_STAGE(PG8_SA(0, 0), a2, voffA);
;             PG8_WAIT_V(8); PG8_WAIT_L(0); PG8_BAR; PG8_MMA(1, 0, At, B0); PG8_MMA(1, 1, At, B1); PG8_BAR; PG8_SCHED;
.LBB0_604:
	s_add_u32 s0, s40, 0xfffc0080
	s_addc_u32 s1, s41, -1
	s_add_i32 s12, 0, 0x10000
	s_cmp_eq_u32 s54, 12
	s_cselect_b32 s49, s34, s1
	s_cselect_b32 s48, s35, s0
	v_add_u32_e32 v130, s12, v172
	s_cselect_b32 s47, s50, s53
	s_cselect_b32 s46, s51, s52
	s_add_i32 s15, 0, 0x14000
	ds_read_b128 v[182:185], v130
	ds_read_b128 v[186:189], v130 offset:1024
	ds_read_b128 v[190:193], v130 offset:2048
	ds_read_b128 v[194:197], v130 offset:3072
	v_add_u32_e32 v130, s15, v172
	ds_read_b128 v[198:201], v130
	ds_read_b128 v[202:205], v130 offset:1024
	ds_read_b128 v[206:209], v130 offset:2048
	ds_read_b128 v[210:213], v130 offset:3072
	v_lshl_add_u64 v[164:165], s[40:41], 0, v[150:151]
	s_add_i32 m0, s24, 0xc000
	ds_read_b128 v[214:217], v173
	ds_read_b128 v[218:221], v173 offset:1024
	ds_read_b128 v[222:225], v173 offset:2048
	ds_read_b128 v[226:229], v173 offset:3072
	ds_read_b128 v[230:233], v173 offset:4096
	ds_read_b128 v[234:237], v173 offset:5120
	ds_read_b128 v[238:241], v173 offset:6144
	ds_read_b128 v[242:245], v173 offset:7168
	global_load_lds_dwordx4 v[164:165], off
	v_lshl_add_u64 v[164:165], s[40:41], 0, v[152:153]
	s_add_i32 m0, s24, 0xe000
	s_nop 0
	global_load_lds_dwordx4 v[164:165], off
	s_waitcnt vmcnt(8)
	s_waitcnt lgkmcnt(0)
	s_barrier
	s_waitcnt lgkmcnt(0)
	v_mfma_f32_16x16x32_bf16 v[126:129], v[182:185], v[214:217], v[126:129]
	v_mfma_f32_16x16x32_bf16 v[118:121], v[190:193], v[214:217], v[118:121]
	v_mfma_f32_16x16x32_bf16 v[110:113], v[182:185], v[222:225], v[110:113]
	v_mfma_f32_16x16x32_bf16 v[106:109], v[190:193], v[222:225], v[106:109]
	v_mfma_f32_16x16x32_bf16 v[94:97], v[182:185], v[230:233], v[94:97]
	v_mfma_f32_16x16x32_bf16 v[86:89], v[190:193], v[230:233], v[86:89]
	v_mfma_f32_16x16x32_bf16 v[76:79], v[182:185], v[238:241], v[76:79]
	v_mfma_f32_16x16x32_bf16 v[72:75], v[190:193], v[238:241], v[72:75]
	v_mfma_f32_16x16x32_bf16 v[126:129], v[186:189], v[218:221], v[126:129]
	v_mfma_f32_16x16x32_bf16 v[118:121], v[194:197], v[218:221], v[118:121]
	v_mfma_f32_16x16x32_bf16 v[110:113], v[186:189], v[226:229], v[110:113]
	v_mfma_f32_16x16x32_bf16 v[106:109], v[194:197], v[226:229], v[106:109]
	v_mfma_f32_16x16x32_bf16 v[94:97], v[186:189], v[234:237], v[94:97]
	v_mfma_f32_16x16x32_bf16 v[86:89], v[194:197], v[234:237], v[86:89]
	v_mfma_f32_16x16x32_bf16 v[76:79], v[186:189], v[242:245], v[76:79]
	v_mfma_f32_16x16x32_bf16 v[72:75], v[194:197], v[242:245], v[72:75]
	v_mfma_f32_16x16x32_bf16 v[122:125], v[198:201], v[214:217], v[122:125]
	v_mfma_f32_16x16x32_bf16 v[114:117], v[206:209], v[214:217], v[114:117]
	v_mfma_f32_16x16x32_bf16 v[102:105], v[198:201], v[222:225], v[102:105]
	v_mfma_f32_16x16x32_bf16 v[98:101], v[206:209], v[222:225], v[98:101]
	v_mfma_f32_16x16x32_bf16 v[90:93], v[198:201], v[230:233], v[90:93]
	v_mfma_f32_16x16x32_bf16 v[82:85], v[206:209], v[230:233], v[82:85]
	v_mfma_f32_16x16x32_bf16 v[68:71], v[198:201], v[238:241], v[68:71]
	v_mfma_f32_16x16x32_bf16 v[64:67], v[206:209], v[238:241], v[64:67]
	v_mfma_f32_16x16x32_bf16 v[122:125], v[202:205], v[218:221], v[122:125]
	v_mfma_f32_16x16x32_bf16 v[114:117], v[210:213], v[218:221], v[114:117]
	v_mfma_f32_16x16x32_bf16 v[102:105], v[202:205], v[226:229], v[102:105]
	v_mfma_f32_16x16x32_bf16 v[98:101], v[210:213], v[226:229], v[98:101]
	v_mfma_f32_16x16x32_bf16 v[90:93], v[202:205], v[234:237], v[90:93]
	v_mfma_f32_16x16x32_bf16 v[82:85], v[210:213], v[234:237], v[82:85]
	v_mfma_f32_16x16x32_bf16 v[68:71], v[202:205], v[242:245], v[68:71]
	v_mfma_f32_16x16x32_bf16 v[64:67], v[210:213], v[242:245], v[64:67]
	s_barrier
	s_add_i32 s0, s12, s73
	v_lshl_add_u64 v[164:165], s[46:47], 0, v[80:81]
	s_mov_b32 m0, s0
	ds_read_b128 v[214:217], v173 offset:16384
	ds_read_b128 v[218:221], v173 offset:17408
	ds_read_b128 v[222:225], v173 offset:18432
	ds_read_b128 v[226:229], v173 offset:19456
	ds_read_b128 v[230:233], v173 offset:20480
	ds_read_b128 v[234:237], v173 offset:21504
	ds_read_b128 v[238:241], v173 offset:22528
	ds_read_b128 v[242:245], v173 offset:23552
	global_load_lds_dwordx4 v[164:165], off
	s_add_i32 m0, s0, 0x2000
	s_add_u32 s0, s46, 0x40000
	v_lshl_add_u64 v[176:177], s[46:47], 0, v[136:137]
	s_addc_u32 s1, s47, 0
	s_add_i32 s12, s15, s73
	global_load_lds_dwordx4 v[176:177], off
	v_lshl_add_u64 v[178:179], s[0:1], 0, v[80:81]
	s_mov_b32 m0, s12
	v_lshl_add_u64 v[246:247], s[48:49], 0, v[138:139]
	global_load_lds_dwordx4 v[178:179], off
	v_lshl_add_u64 v[178:179], s[0:1], 0, v[136:137]
	s_add_i32 m0, s12, 0x2000
	s_nop 0
	global_load_lds_dwordx4 v[178:179], off
	v_lshl_add_u64 v[178:179], s[48:49], 0, v[140:141]
	s_mov_b32 m0, s24
	s_nop 0
	global_load_lds_dwordx4 v[178:179], off
	s_mov_b32 m0, s25
	s_nop 0
	global_load_lds_dwordx4 v[246:247], off
	s_waitcnt vmcnt(8)
	s_waitcnt lgkmcnt(0)
	s_barrier
; #define PG8_STAGE(bufoff, gbase, voff) do { _Pragma("unroll") for (int _i = 0; _i < 2; ++_i) \
;         __builtin_amdgcn_global_load_lds((const unsigned*)((const char*)(gbase) + (voff)[_i]), (LAS unsigned*)(lds + (bufoff) + ldsw + _i * 8192), 16, 0, 0); } while (0)
; #define PG8_LDA(dst, b, h) do { _Pragma("unroll") for (int m = 0; m < 4; ++m) _Pragma("unroll") for (int k = 0; k < 2; ++k) dst[m][k] = *(const LAS bf16x8*)(lds + PG8_SA(b, h) + aoff + m * 2048 + k * 1024); } while (0)
; #define PG8_LDB(dst, b, h) do { _Pragma("unroll") for (int n = 0; n < 2; ++n) _Pragma("unroll") for (int k = 0; k < 2; ++k) dst[n][k] = *(const LAS bf16x8*)(lds + PG8_SB(b, h) + boff + n * 2048 + k * 1024); } while (0)
; #define PG8_MMA(ai, bj, At, Bt) do { __builtin_amdgcn_s_setprio(1); _Pragma("unroll") for (int m = 0; m < 4; ++m) _Pragma("unroll") for (int n = 0; n < 2; ++n) _Pragma("unroll") for (int k = 0; k < 2; ++k) \
;         acc[ai][bj][m][n] = __builtin_amdgcn_mfma_f32_16x16x32_bf16(Bt[n][k], At[m][k], acc[ai][bj][m][n], 0, 0, 0); __builtin_amdgcn_s_setprio(0); } while (0)
; #define PG8_WAIT_V(n) asm volatile("s_waitcnt vmcnt(" #n ")" ::: "memory")
; #define PG8_WAIT_L(n) asm volatile("s_waitcnt lgkmcnt(" #n ")" ::: "memory")
; #define PG8_BAR __builtin_amdgcn_s_barrier()
; #define PG8_SCHED __builtin_amdgcn_sched_barrier(0)
; template <class Epi, bool ALIGN_EPI>
; __device__ __forceinline__ void gemm_phase(LAS unsigned char* lds, const Gemm g, const StaticOrder S, const Epi E) {
;     ...
;             PG8_WAIT_V(8); PG8_WAIT_L(0); PG8_BAR; PG8_MMA(1, 0, At, B0); PG8_MMA(1, 1, At, B1); PG8_BAR; PG8_SCHED;
;             PG8_LDB(B0, 1, 0); PG8_LDB(B1, 1, 1); PG8_SCHED; PG8_LDA(At, 1, 0); PG8_STAGE(PG8_SA(0, 1), a2 + hstepA, voffA);
;             PG8_WAIT_V(8); PG8_WAIT_L(0); PG8_BAR; PG8_MMA(0, 0, At, B0); PG8_MMA(0, 1, At, B1); PG8_BAR; PG8_SCHED;
	s_waitcnt lgkmcnt(0)
	v_mfma_f32_16x16x32_bf16 v[60:63], v[182:185], v[214:217], v[60:63]
	v_mfma_f32_16x16x32_bf16 v[52:55], v[190:193], v[214:217], v[52:55]
	v_mfma_f32_16x16x32_bf16 v[44:47], v[182:185], v[222:225], v[44:47]
	v_mfma_f32_16x16x32_bf16 v[40:43], v[190:193], v[222:225], v[40:43]
	v_mfma_f32_16x16x32_bf16 v[28:31], v[182:185], v[230:233], v[28:31]
	v_mfma_f32_16x16x32_bf16 v[20:23], v[190:193], v[230:233], v[20:23]
	v_mfma_f32_16x16x32_bf16 v[12:15], v[182:185], v[238:241], v[12:15]
	v_mfma_f32_16x16x32_bf16 v[8:11], v[190:193], v[238:241], v[8:11]
	v_mfma_f32_16x16x32_bf16 v[60:63], v[186:189], v[218:221], v[60:63]
	v_mfma_f32_16x16x32_bf16 v[52:55], v[194:197], v[218:221], v[52:55]
	v_mfma_f32_16x16x32_bf16 v[44:47], v[186:189], v[226:229], v[44:47]
	v_mfma_f32_16x16x32_bf16 v[40:43], v[194:197], v[226:229], v[40:43]
	v_mfma_f32_16x16x32_bf16 v[28:31], v[186:189], v[234:237], v[28:31]
	v_mfma_f32_16x16x32_bf16 v[20:23], v[194:197], v[234:237], v[20:23]
	v_mfma_f32_16x16x32_bf16 v[12:15], v[186:189], v[242:245], v[12:15]
	v_mfma_f32_16x16x32_bf16 v[8:11], v[194:197], v[242:245], v[8:11]
	v_mfma_f32_16x16x32_bf16 v[56:59], v[198:201], v[214:217], v[56:59]
	v_mfma_f32_16x16x32_bf16 v[48:51], v[206:209], v[214:217], v[48:51]
	v_mfma_f32_16x16x32_bf16 v[36:39], v[198:201], v[222:225], v[36:39]
	v_mfma_f32_16x16x32_bf16 v[32:35], v[206:209], v[222:225], v[32:35]
	v_mfma_f32_16x16x32_bf16 v[24:27], v[198:201], v[230:233], v[24:27]
	v_mfma_f32_16x16x32_bf16 v[16:19], v[206:209], v[230:233], v[16:19]
	v_mfma_f32_16x16x32_bf16 v[4:7], v[198:201], v[238:241], v[4:7]
	v_mfma_f32_16x16x32_bf16 v[0:3], v[206:209], v[238:241], v[0:3]
	v_mfma_f32_16x16x32_bf16 v[56:59], v[202:205], v[218:221], v[56:59]
	v_mfma_f32_16x16x32_bf16 v[48:51], v[210:213], v[218:221], v[48:51]
	v_mfma_f32_16x16x32_bf16 v[36:39], v[202:205], v[226:229], v[36:39]
	v_mfma_f32_16x16x32_bf16 v[32:35], v[210:213], v[226:229], v[32:35]
	v_mfma_f32_16x16x32_bf16 v[24:27], v[202:205], v[234:237], v[24:27]
	v_mfma_f32_16x16x32_bf16 v[16:19], v[210:213], v[234:237], v[16:19]
	v_mfma_f32_16x16x32_bf16 v[4:7], v[202:205], v[242:245], v[4:7]
	v_mfma_f32_16x16x32_bf16 v[0:3], v[210:213], v[242:245], v[0:3]
	s_barrier
	s_add_i32 s12, 0, 0x18000
	v_add_u32_e32 v130, s12, v172
	s_add_i32 s15, 0, 0x1c000
	ds_read_b128 v[182:185], v130
	ds_read_b128 v[186:189], v130 offset:1024
	ds_read_b128 v[190:193], v130 offset:2048
	ds_read_b128 v[194:197], v130 offset:3072
	v_add_u32_e32 v130, s15, v172
	ds_read_b128 v[198:201], v130
	ds_read_b128 v[202:205], v130 offset:1024
	ds_read_b128 v[206:209], v130 offset:2048
	ds_read_b128 v[210:213], v130 offset:3072
	s_add_u32 s0, s48, 0x40000
	s_addc_u32 s1, s49, 0
	s_mov_b32 m0, s26
	v_lshl_add_u64 v[248:249], s[0:1], 0, v[140:141]
	ds_read_b128 v[214:217], v173 offset:32768
	ds_read_b128 v[218:221], v173 offset:33792
	ds_read_b128 v[222:225], v173 offset:34816
	ds_read_b128 v[226:229], v173 offset:35840
	ds_read_b128 v[230:233], v173 offset:36864
	ds_read_b128 v[234:237], v173 offset:37888
	ds_read_b128 v[238:241], v173 offset:38912
	ds_read_b128 v[242:245], v173 offset:39936
	global_load_lds_dwordx4 v[248:249], off
	v_lshl_add_u64 v[248:249], s[0:1], 0, v[138:139]
	s_mov_b32 m0, s27
	s_nop 0
	global_load_lds_dwordx4 v[248:249], off
	s_waitcnt vmcnt(8)
	s_waitcnt lgkmcnt(0)
	s_barrier
	s_waitcnt lgkmcnt(0)
	v_mfma_f32_16x16x32_bf16 v[126:129], v[182:185], v[214:217], v[126:129]
	v_mfma_f32_16x16x32_bf16 v[118:121], v[190:193], v[214:217], v[118:121]
	v_mfma_f32_16x16x32_bf16 v[110:113], v[182:185], v[222:225], v[110:113]
	v_mfma_f32_16x16x32_bf16 v[106:109], v[190:193], v[222:225], v[106:109]
	v_mfma_f32_16x16x32_bf16 v[94:97], v[182:185], v[230:233], v[94:97]
	v_mfma_f32_16x16x32_bf16 v[86:89], v[190:193], v[230:233], v[86:89]
	v_mfma_f32_16x16x32_bf16 v[76:79], v[182:185], v[238:241], v[76:79]
	v_mfma_f32_16x16x32_bf16 v[72:75], v[190:193], v[238:241], v[72:75]
	v_mfma_f32_16x16x32_bf16 v[126:129], v[186:189], v[218:221], v[126:129]
	v_mfma_f32_16x16x32_bf16 v[118:121], v[194:197], v[218:221], v[118:121]
	v_mfma_f32_16x16x32_bf16 v[110:113], v[186:189], v[226:229], v[110:113]
	v_mfma_f32_16x16x32_bf16 v[106:109], v[194:197], v[226:229], v[106:109]
	v_mfma_f32_16x16x32_bf16 v[94:97], v[186:189], v[234:237], v[94:97]
	v_mfma_f32_16x16x32_bf16 v[86:89], v[194:197], v[234:237], v[86:89]
	v_mfma_f32_16x16x32_bf16 v[76:79], v[186:189], v[242:245], v[76:79]
	v_mfma_f32_16x16x32_bf16 v[72:75], v[194:197], v[242:245], v[72:75]
	v_mfma_f32_16x16x32_bf16 v[122:125], v[198:201], v[214:217], v[122:125]
	v_mfma_f32_16x16x32_bf16 v[114:117], v[206:209], v[214:217], v[114:117]
	v_mfma_f32_16x16x32_bf16 v[102:105], v[198:201], v[222:225], v[102:105]
	v_mfma_f32_16x16x32_bf16 v[98:101], v[206:209], v[222:225], v[98:101]
	v_mfma_f32_16x16x32_bf16 v[90:93], v[198:201], v[230:233], v[90:93]
	v_mfma_f32_16x16x32_bf16 v[82:85], v[206:209], v[230:233], v[82:85]
	v_mfma_f32_16x16x32_bf16 v[68:71], v[198:201], v[238:241], v[68:71]
	v_mfma_f32_16x16x32_bf16 v[64:67], v[206:209], v[238:241], v[64:67]
	v_mfma_f32_16x16x32_bf16 v[122:125], v[202:205], v[218:221], v[122:125]
	v_mfma_f32_16x16x32_bf16 v[114:117], v[210:213], v[218:221], v[114:117]
	v_mfma_f32_16x16x32_bf16 v[102:105], v[202:205], v[226:229], v[102:105]
	v_mfma_f32_16x16x32_bf16 v[98:101], v[210:213], v[226:229], v[98:101]
	v_mfma_f32_16x16x32_bf16 v[90:93], v[202:205], v[234:237], v[90:93]
	v_mfma_f32_16x16x32_bf16 v[82:85], v[210:213], v[234:237], v[82:85]
	v_mfma_f32_16x16x32_bf16 v[68:71], v[202:205], v[242:245], v[68:71]
	v_mfma_f32_16x16x32_bf16 v[64:67], v[210:213], v[242:245], v[64:67]
	s_barrier
; #define PG8_STAGE(bufoff, gbase, voff) do { _Pragma("unroll") for (int _i = 0; _i < 2; ++_i) \
;         __builtin_amdgcn_global_load_lds((const unsigned*)((const char*)(gbase) + (voff)[_i]), (LAS unsigned*)(lds + (bufoff) + ldsw + _i * 8192), 16, 0, 0); } while (0)
; #define PG8_LDA(dst, b, h) do { _Pragma("unroll") for (int m = 0; m < 4; ++m) _Pragma("unroll") for (int k = 0; k < 2; ++k) dst[m][k] = *(const LAS bf16x8*)(lds + PG8_SA(b, h) + aoff + m * 2048 + k * 1024); } while (0)
; #define PG8_MMA(ai, bj, At, Bt) do { __builtin_amdgcn_s_setprio(1); _Pragma("unroll") for (int m = 0; m < 4; ++m) _Pragma("unroll") for (int n = 0; n < 2; ++n) _Pragma("unroll") for (int k = 0; k < 2; ++k) \
;         acc[ai][bj][m][n] = __builtin_amdgcn_mfma_f32_16x16x32_bf16(Bt[n][k], At[m][k], acc[ai][bj][m][n], 0, 0, 0); __builtin_amdgcn_s_setprio(0); } while (0)
; #define PG8_WAIT_V(n) asm volatile("s_waitcnt vmcnt(" #n ")" ::: "memory")
; #define PG8_WAIT_L(n) asm volatile("s_waitcnt lgkmcnt(" #n ")" ::: "memory")
; #define PG8_BAR __builtin_amdgcn_s_barrier()
; #define PG8_SCHED __builtin_amdgcn_sched_barrier(0)
; template <class Epi, bool ALIGN_EPI>
; __device__ __forceinline__ void gemm_phase(LAS unsigned char* lds, const Gemm g, const StaticOrder S, const Epi E) {
;     ...
;             PG8_LDA(At, 1, 1); PG8_STAGE(PG8_SB(1, 0), b3, voffB); PG8_STAGE(PG8_SB(1, 1), b3 + hstepB, voffB); PG8_STAGE(PG8_SA(1, 0), a3, voffA);
;             PG8_WAIT_V(8); PG8_WAIT_L(0); PG8_BAR; PG8_MMA(1, 0, At, B0); PG8_MMA(1, 1, At, B1); PG8_BAR; PG8_SCHED;
;         }
;         if constexpr (ALIGN_EPI) { if (wr == 0) PG8_BAR; }
	s_add_i32 s0, s12, s73
	v_lshl_add_u64 v[164:165], v[164:165], 0, s[80:81]
	s_mov_b32 m0, s0
	ds_read_b128 v[214:217], v173 offset:49152
	ds_read_b128 v[218:221], v173 offset:50176
	ds_read_b128 v[222:225], v173 offset:51200
	ds_read_b128 v[226:229], v173 offset:52224
	ds_read_b128 v[230:233], v173 offset:53248
	ds_read_b128 v[234:237], v173 offset:54272
	ds_read_b128 v[238:241], v173 offset:55296
	ds_read_b128 v[242:245], v173 offset:56320
	global_load_lds_dwordx4 v[164:165], off
	s_add_i32 m0, s0, 0x2000
	s_add_u32 s0, s46, 0x40080
	v_lshl_add_u64 v[164:165], v[176:177], 0, s[80:81]
	s_addc_u32 s1, s47, 0
	s_add_i32 s12, s15, s73
	global_load_lds_dwordx4 v[164:165], off
	v_lshl_add_u64 v[164:165], s[0:1], 0, v[80:81]
	s_mov_b32 m0, s12
	s_nop 0
	global_load_lds_dwordx4 v[164:165], off
	v_lshl_add_u64 v[164:165], s[0:1], 0, v[136:137]
	s_add_i32 m0, s12, 0x2000
	s_nop 0
	global_load_lds_dwordx4 v[164:165], off
	v_lshl_add_u64 v[164:165], v[178:179], 0, s[80:81]
	s_mov_b32 m0, s29
	s_nop 0
	global_load_lds_dwordx4 v[164:165], off
	v_lshl_add_u64 v[164:165], v[246:247], 0, s[80:81]
	s_mov_b32 m0, s30
	s_nop 0
	global_load_lds_dwordx4 v[164:165], off
	s_waitcnt vmcnt(8)
	s_waitcnt lgkmcnt(0)
	s_barrier
	s_waitcnt lgkmcnt(0)
	v_mfma_f32_16x16x32_bf16 v[60:63], v[182:185], v[214:217], v[60:63]
	v_mfma_f32_16x16x32_bf16 v[52:55], v[190:193], v[214:217], v[52:55]
	v_mfma_f32_16x16x32_bf16 v[44:47], v[182:185], v[222:225], v[44:47]
	v_mfma_f32_16x16x32_bf16 v[40:43], v[190:193], v[222:225], v[40:43]
	v_mfma_f32_16x16x32_bf16 v[28:31], v[182:185], v[230:233], v[28:31]
	v_mfma_f32_16x16x32_bf16 v[20:23], v[190:193], v[230:233], v[20:23]
	v_mfma_f32_16x16x32_bf16 v[12:15], v[182:185], v[238:241], v[12:15]
	v_mfma_f32_16x16x32_bf16 v[8:11], v[190:193], v[238:241], v[8:11]
	v_mfma_f32_16x16x32_bf16 v[60:63], v[186:189], v[218:221], v[60:63]
	v_mfma_f32_16x16x32_bf16 v[52:55], v[194:197], v[218:221], v[52:55]
	v_mfma_f32_16x16x32_bf16 v[44:47], v[186:189], v[226:229], v[44:47]
	v_mfma_f32_16x16x32_bf16 v[40:43], v[194:197], v[226:229], v[40:43]
	v_mfma_f32_16x16x32_bf16 v[28:31], v[186:189], v[234:237], v[28:31]
	v_mfma_f32_16x16x32_bf16 v[20:23], v[194:197], v[234:237], v[20:23]
	v_mfma_f32_16x16x32_bf16 v[12:15], v[186:189], v[242:245], v[12:15]
	v_mfma_f32_16x16x32_bf16 v[8:11], v[194:197], v[242:245], v[8:11]
	v_mfma_f32_16x16x32_bf16 v[56:59], v[198:201], v[214:217], v[56:59]
	v_mfma_f32_16x16x32_bf16 v[48:51], v[206:209], v[214:217], v[48:51]
	v_mfma_f32_16x16x32_bf16 v[36:39], v[198:201], v[222:225], v[36:39]
	v_mfma_f32_16x16x32_bf16 v[32:35], v[206:209], v[222:225], v[32:35]
	v_mfma_f32_16x16x32_bf16 v[24:27], v[198:201], v[230:233], v[24:27]
	v_mfma_f32_16x16x32_bf16 v[16:19], v[206:209], v[230:233], v[16:19]
	v_mfma_f32_16x16x32_bf16 v[4:7], v[198:201], v[238:241], v[4:7]
	v_mfma_f32_16x16x32_bf16 v[0:3], v[206:209], v[238:241], v[0:3]
	v_mfma_f32_16x16x32_bf16 v[56:59], v[202:205], v[218:221], v[56:59]
	v_mfma_f32_16x16x32_bf16 v[48:51], v[210:213], v[218:221], v[48:51]
	v_mfma_f32_16x16x32_bf16 v[36:39], v[202:205], v[226:229], v[36:39]
	v_mfma_f32_16x16x32_bf16 v[32:35], v[210:213], v[226:229], v[32:35]
	v_mfma_f32_16x16x32_bf16 v[24:27], v[202:205], v[234:237], v[24:27]
	v_mfma_f32_16x16x32_bf16 v[16:19], v[210:213], v[234:237], v[16:19]
	v_mfma_f32_16x16x32_bf16 v[4:7], v[202:205], v[242:245], v[4:7]
	v_mfma_f32_16x16x32_bf16 v[0:3], v[210:213], v[242:245], v[0:3]
	s_barrier
	s_add_i32 s54, s54, 2
	s_add_u32 s40, s40, 0x100
	s_addc_u32 s41, s41, 0
	s_add_u32 s52, s52, 0x100
	s_addc_u32 s53, s53, 0
	s_cmp_gt_u32 s54, 13
	s_cbranch_scc0 .LBB0_604
	s_and_b64 vcc, exec, s[2:3]
	s_cbranch_vccz .LBB0_607
	s_barrier

; #define PG8_STAGE(bufoff, gbase, voff) do { _Pragma("unroll") for (int _i = 0; _i < 2; ++_i) \
;         __builtin_amdgcn_global_load_lds((const unsigned*)((const char*)(gbase) + (voff)[_i]), (LAS unsigned*)(lds + (bufoff) + ldsw + _i * 8192), 16, 0, 0); } while (0)
; #define PG8_LDA(dst, b, h) do { _Pragma("unroll") for (int m = 0; m < 4; ++m) _Pragma("unroll") for (int k = 0; k < 2; ++k) dst[m][k] = *(const LAS bf16x8*)(lds + PG8_SA(b, h) + aoff + m * 2048 + k * 1024); } while (0)
; #define PG8_LDB(dst, b, h) do { _Pragma("unroll") for (int n = 0; n < 2; ++n) _Pragma("unroll") for (int k = 0; k < 2; ++k) dst[n][k] = *(const LAS bf16x8*)(lds + PG8_SB(b, h) + boff + n * 2048 + k * 1024); } while (0)
; #define PG8_MMA(ai, bj, At, Bt) do { __builtin_amdgcn_s_setprio(1); _Pragma("unroll") for (int m = 0; m < 4; ++m) _Pragma("unroll") for (int n = 0; n < 2; ++n) _Pragma("unroll") for (int k = 0; k < 2; ++k) \
;         acc[ai][bj][m][n] = __builtin_amdgcn_mfma_f32_16x16x32_bf16(Bt[n][k], At[m][k], acc[ai][bj][m][n], 0, 0, 0); __builtin_amdgcn_s_setprio(0); } while (0)
; #define PG8_WAIT_V(n) asm volatile("s_waitcnt vmcnt(" #n ")" ::: "memory")
; #define PG8_WAIT_L(n) asm volatile("s_waitcnt lgkmcnt(" #n ")" ::: "memory")
; #define PG8_BAR __builtin_amdgcn_s_barrier()
; #define PG8_SCHED __builtin_amdgcn_sched_barrier(0)
; template <class Epi, bool ALIGN_EPI>
; __device__ __forceinline__ void gemm_phase(LAS unsigned char* lds, const Gemm g, const StaticOrder S, const Epi E) {
;     ...
;             const bool last = (t == nt - 2);
;             const char* a1 = cA + (size_t)(t + 1) * kstep;
;             const char* a2 = last ? nA : cA + (size_t)(t + 2) * kstep; const char* b2 = last ? nB : cB + (size_t)(t + 2) * kstep;
;             const char* a3 = a2 + kstep; const char* b3 = b2 + kstep;
;             PG8_LDB(B0, 0, 0); PG8_LDB(B1, 0, 1); PG8_SCHED; PG8_LDA(At, 0, 0); PG8_STAGE(PG8_SA(1, 1), a1 + hstepA, voffA);
;             PG8_WAIT_V(8); PG8_WAIT_L(0); PG8_BAR; PG8_MMA(0, 0, At, B0); PG8_MMA(0, 1, At, B1); PG8_BAR; PG8_SCHED;
;             PG8_LDA(At, 0, 1); PG8_STAGE(PG8_SB(0, 0), b2, voffB); PG8_STAGE(PG8_SB(0, 1), b2 + hstepB, voffB); PG8_STAGE(PG8_SA(0, 0), a2, voffA);
;             PG8_WAIT_V(8); PG8_WAIT_L(0); PG8_BAR; PG8_MMA(1, 0, At, B0); PG8_MMA(1, 1, At, B1); PG8_BAR; PG8_SCHED;
.LBB0_728:
	s_add_u32 s50, s48, 0x100
	s_addc_u32 s51, s49, 0
	s_add_i32 s0, 0, 0x10000
	s_cmp_eq_u32 s30, 40
	s_cselect_b32 s55, s43, s51
	s_cselect_b32 s54, s42, s50
	v_add_u32_e32 v130, s0, v152
	s_cselect_b32 s53, s47, s29
	s_cselect_b32 s52, s46, s28
	s_add_i32 s12, 0, 0x14000
	ds_read_b128 v[146:149], v130
	ds_read_b128 v[154:157], v130 offset:1024
	ds_read_b128 v[158:161], v130 offset:2048
	ds_read_b128 v[162:165], v130 offset:3072
	v_add_u32_e32 v130, s12, v152
	ds_read_b128 v[182:185], v130
	ds_read_b128 v[186:189], v130 offset:1024
	ds_read_b128 v[190:193], v130 offset:2048
	ds_read_b128 v[194:197], v130 offset:3072
	v_lshl_add_u64 v[168:169], s[48:49], 0, v[142:143]
	s_add_i32 m0, s66, 0xc000
	ds_read_b128 v[198:201], v153
	ds_read_b128 v[202:205], v153 offset:1024
	ds_read_b128 v[206:209], v153 offset:2048
	ds_read_b128 v[210:213], v153 offset:3072
	ds_read_b128 v[214:217], v153 offset:4096
	ds_read_b128 v[218:221], v153 offset:5120
	ds_read_b128 v[222:225], v153 offset:6144
	ds_read_b128 v[226:229], v153 offset:7168
	global_load_lds_dwordx4 v[168:169], off
	v_lshl_add_u64 v[168:169], s[48:49], 0, v[144:145]
	s_add_i32 m0, s66, 0xe000
	s_nop 0
	global_load_lds_dwordx4 v[168:169], off
	s_waitcnt vmcnt(8)
	s_waitcnt lgkmcnt(0)
	s_barrier
	s_waitcnt lgkmcnt(0)
	v_mfma_f32_16x16x32_bf16 v[126:129], v[146:149], v[198:201], v[126:129]
	v_mfma_f32_16x16x32_bf16 v[122:125], v[158:161], v[198:201], v[122:125]
	v_mfma_f32_16x16x32_bf16 v[110:113], v[146:149], v[206:209], v[110:113]
	v_mfma_f32_16x16x32_bf16 v[106:109], v[158:161], v[206:209], v[106:109]
	v_mfma_f32_16x16x32_bf16 v[94:97], v[146:149], v[214:217], v[94:97]
	v_mfma_f32_16x16x32_bf16 v[90:93], v[158:161], v[214:217], v[90:93]
	v_mfma_f32_16x16x32_bf16 v[76:79], v[146:149], v[222:225], v[76:79]
	v_mfma_f32_16x16x32_bf16 v[72:75], v[158:161], v[222:225], v[72:75]
	v_mfma_f32_16x16x32_bf16 v[126:129], v[154:157], v[202:205], v[126:129]
	v_mfma_f32_16x16x32_bf16 v[122:125], v[162:165], v[202:205], v[122:125]
	v_mfma_f32_16x16x32_bf16 v[110:113], v[154:157], v[210:213], v[110:113]
	v_mfma_f32_16x16x32_bf16 v[106:109], v[162:165], v[210:213], v[106:109]
	v_mfma_f32_16x16x32_bf16 v[94:97], v[154:157], v[218:221], v[94:97]
	v_mfma_f32_16x16x32_bf16 v[90:93], v[162:165], v[218:221], v[90:93]
	v_mfma_f32_16x16x32_bf16 v[76:79], v[154:157], v[226:229], v[76:79]
	v_mfma_f32_16x16x32_bf16 v[72:75], v[162:165], v[226:229], v[72:75]
	v_mfma_f32_16x16x32_bf16 v[118:121], v[182:185], v[198:201], v[118:121]
	v_mfma_f32_16x16x32_bf16 v[114:117], v[190:193], v[198:201], v[114:117]
	v_mfma_f32_16x16x32_bf16 v[102:105], v[182:185], v[206:209], v[102:105]
	v_mfma_f32_16x16x32_bf16 v[98:101], v[190:193], v[206:209], v[98:101]
	v_mfma_f32_16x16x32_bf16 v[86:89], v[182:185], v[214:217], v[86:89]
	v_mfma_f32_16x16x32_bf16 v[82:85], v[190:193], v[214:217], v[82:85]
	v_mfma_f32_16x16x32_bf16 v[68:71], v[182:185], v[222:225], v[68:71]
	v_mfma_f32_16x16x32_bf16 v[64:67], v[190:193], v[222:225], v[64:67]
	v_mfma_f32_16x16x32_bf16 v[118:121], v[186:189], v[202:205], v[118:121]
	v_mfma_f32_16x16x32_bf16 v[114:117], v[194:197], v[202:205], v[114:117]
	v_mfma_f32_16x16x32_bf16 v[102:105], v[186:189], v[210:213], v[102:105]
	v_mfma_f32_16x16x32_bf16 v[98:101], v[194:197], v[210:213], v[98:101]
	v_mfma_f32_16x16x32_bf16 v[86:89], v[186:189], v[218:221], v[86:89]
	v_mfma_f32_16x16x32_bf16 v[82:85], v[194:197], v[218:221], v[82:85]
	v_mfma_f32_16x16x32_bf16 v[68:71], v[186:189], v[226:229], v[68:71]
	v_mfma_f32_16x16x32_bf16 v[64:67], v[194:197], v[226:229], v[64:67]
	s_barrier
	s_add_i32 s0, s0, s65
	v_lshl_add_u64 v[168:169], s[52:53], 0, v[80:81]
	s_mov_b32 m0, s0
	ds_read_b128 v[198:201], v153 offset:16384
	ds_read_b128 v[202:205], v153 offset:17408
	ds_read_b128 v[206:209], v153 offset:18432
	ds_read_b128 v[210:213], v153 offset:19456
	ds_read_b128 v[214:217], v153 offset:20480
	ds_read_b128 v[218:221], v153 offset:21504
	ds_read_b128 v[222:225], v153 offset:22528
	ds_read_b128 v[226:229], v153 offset:23552
	global_load_lds_dwordx4 v[168:169], off
	s_add_i32 m0, s0, 0x2000
	s_add_u32 s0, s52, 0xb0000
	v_lshl_add_u64 v[170:171], s[52:53], 0, v[140:141]
	s_addc_u32 s1, s53, 0
	s_add_i32 s12, s12, s65
	global_load_lds_dwordx4 v[170:171], off
	v_lshl_add_u64 v[172:173], s[0:1], 0, v[80:81]
	s_mov_b32 m0, s12
	v_lshl_add_u64 v[176:177], s[54:55], 0, v[138:139]
	global_load_lds_dwordx4 v[172:173], off
	v_lshl_add_u64 v[172:173], s[0:1], 0, v[140:141]
	s_add_i32 m0, s12, 0x2000
	s_nop 0
	global_load_lds_dwordx4 v[172:173], off
	v_lshl_add_u64 v[172:173], s[54:55], 0, v[136:137]
	s_mov_b32 m0, s66
	s_nop 0
	global_load_lds_dwordx4 v[172:173], off
	s_mov_b32 m0, s67
	s_nop 0
	global_load_lds_dwordx4 v[176:177], off
	s_waitcnt vmcnt(8)
	s_waitcnt lgkmcnt(0)
	s_barrier
; #define PG8_STAGE(bufoff, gbase, voff) do { _Pragma("unroll") for (int _i = 0; _i < 2; ++_i) \
;         __builtin_amdgcn_global_load_lds((const unsigned*)((const char*)(gbase) + (voff)[_i]), (LAS unsigned*)(lds + (bufoff) + ldsw + _i * 8192), 16, 0, 0); } while (0)
; #define PG8_LDA(dst, b, h) do { _Pragma("unroll") for (int m = 0; m < 4; ++m) _Pragma("unroll") for (int k = 0; k < 2; ++k) dst[m][k] = *(const LAS bf16x8*)(lds + PG8_SA(b, h) + aoff + m * 2048 + k * 1024); } while (0)
; #define PG8_LDB(dst, b, h) do { _Pragma("unroll") for (int n = 0; n < 2; ++n) _Pragma("unroll") for (int k = 0; k < 2; ++k) dst[n][k] = *(const LAS bf16x8*)(lds + PG8_SB(b, h) + boff + n * 2048 + k * 1024); } while (0)
; #define PG8_MMA(ai, bj, At, Bt) do { __builtin_amdgcn_s_setprio(1); _Pragma("unroll") for (int m = 0; m < 4; ++m) _Pragma("unroll") for (int n = 0; n < 2; ++n) _Pragma("unroll") for (int k = 0; k < 2; ++k) \
;         acc[ai][bj][m][n] = __builtin_amdgcn_mfma_f32_16x16x32_bf16(Bt[n][k], At[m][k], acc[ai][bj][m][n], 0, 0, 0); __builtin_amdgcn_s_setprio(0); } while (0)
; #define PG8_WAIT_V(n) asm volatile("s_waitcnt vmcnt(" #n ")" ::: "memory")
; #define PG8_WAIT_L(n) asm volatile("s_waitcnt lgkmcnt(" #n ")" ::: "memory")
; #define PG8_BAR __builtin_amdgcn_s_barrier()
; #define PG8_SCHED __builtin_amdgcn_sched_barrier(0)
; template <class Epi, bool ALIGN_EPI>
; __device__ __forceinline__ void gemm_phase(LAS unsigned char* lds, const Gemm g, const StaticOrder S, const Epi E) {
;     ...
;             PG8_WAIT_V(8); PG8_WAIT_L(0); PG8_BAR; PG8_MMA(1, 0, At, B0); PG8_MMA(1, 1, At, B1); PG8_BAR; PG8_SCHED;
;             PG8_LDB(B0, 1, 0); PG8_LDB(B1, 1, 1); PG8_SCHED; PG8_LDA(At, 1, 0); PG8_STAGE(PG8_SA(0, 1), a2 + hstepA, voffA);
;             PG8_WAIT_V(8); PG8_WAIT_L(0); PG8_BAR; PG8_MMA(0, 0, At, B0); PG8_MMA(0, 1, At, B1); PG8_BAR; PG8_SCHED;
	s_waitcnt lgkmcnt(0)
	v_mfma_f32_16x16x32_bf16 v[60:63], v[146:149], v[198:201], v[60:63]
	v_mfma_f32_16x16x32_bf16 v[56:59], v[158:161], v[198:201], v[56:59]
	v_mfma_f32_16x16x32_bf16 v[44:47], v[146:149], v[206:209], v[44:47]
	v_mfma_f32_16x16x32_bf16 v[40:43], v[158:161], v[206:209], v[40:43]
	v_mfma_f32_16x16x32_bf16 v[28:31], v[146:149], v[214:217], v[28:31]
	v_mfma_f32_16x16x32_bf16 v[24:27], v[158:161], v[214:217], v[24:27]
	v_mfma_f32_16x16x32_bf16 v[12:15], v[146:149], v[222:225], v[12:15]
	v_mfma_f32_16x16x32_bf16 v[8:11], v[158:161], v[222:225], v[8:11]
	v_mfma_f32_16x16x32_bf16 v[60:63], v[154:157], v[202:205], v[60:63]
	v_mfma_f32_16x16x32_bf16 v[56:59], v[162:165], v[202:205], v[56:59]
	v_mfma_f32_16x16x32_bf16 v[44:47], v[154:157], v[210:213], v[44:47]
	v_mfma_f32_16x16x32_bf16 v[40:43], v[162:165], v[210:213], v[40:43]
	v_mfma_f32_16x16x32_bf16 v[28:31], v[154:157], v[218:221], v[28:31]
	v_mfma_f32_16x16x32_bf16 v[24:27], v[162:165], v[218:221], v[24:27]
	v_mfma_f32_16x16x32_bf16 v[12:15], v[154:157], v[226:229], v[12:15]
	v_mfma_f32_16x16x32_bf16 v[8:11], v[162:165], v[226:229], v[8:11]
	v_mfma_f32_16x16x32_bf16 v[52:55], v[182:185], v[198:201], v[52:55]
	v_mfma_f32_16x16x32_bf16 v[48:51], v[190:193], v[198:201], v[48:51]
	v_mfma_f32_16x16x32_bf16 v[36:39], v[182:185], v[206:209], v[36:39]
	v_mfma_f32_16x16x32_bf16 v[32:35], v[190:193], v[206:209], v[32:35]
	v_mfma_f32_16x16x32_bf16 v[20:23], v[182:185], v[214:217], v[20:23]
	v_mfma_f32_16x16x32_bf16 v[16:19], v[190:193], v[214:217], v[16:19]
	v_mfma_f32_16x16x32_bf16 v[4:7], v[182:185], v[222:225], v[4:7]
	v_mfma_f32_16x16x32_bf16 v[0:3], v[190:193], v[222:225], v[0:3]
	v_mfma_f32_16x16x32_bf16 v[52:55], v[186:189], v[202:205], v[52:55]
	v_mfma_f32_16x16x32_bf16 v[48:51], v[194:197], v[202:205], v[48:51]
	v_mfma_f32_16x16x32_bf16 v[36:39], v[186:189], v[210:213], v[36:39]
	v_mfma_f32_16x16x32_bf16 v[32:35], v[194:197], v[210:213], v[32:35]
	v_mfma_f32_16x16x32_bf16 v[20:23], v[186:189], v[218:221], v[20:23]
	v_mfma_f32_16x16x32_bf16 v[16:19], v[194:197], v[218:221], v[16:19]
	v_mfma_f32_16x16x32_bf16 v[4:7], v[186:189], v[226:229], v[4:7]
	v_mfma_f32_16x16x32_bf16 v[0:3], v[194:197], v[226:229], v[0:3]
	s_barrier
	s_add_i32 s12, 0, 0x18000
	v_add_u32_e32 v130, s12, v152
	s_add_i32 s15, 0, 0x1c000
	ds_read_b128 v[146:149], v130
	ds_read_b128 v[154:157], v130 offset:1024
	ds_read_b128 v[158:161], v130 offset:2048
	ds_read_b128 v[162:165], v130 offset:3072
	v_add_u32_e32 v130, s15, v152
	ds_read_b128 v[182:185], v130
	ds_read_b128 v[186:189], v130 offset:1024
	ds_read_b128 v[190:193], v130 offset:2048
	ds_read_b128 v[194:197], v130 offset:3072
	s_add_u32 s0, s54, 0xb0000
	s_addc_u32 s1, s55, 0
	s_mov_b32 m0, s68
	v_lshl_add_u64 v[178:179], s[0:1], 0, v[136:137]
	ds_read_b128 v[198:201], v153 offset:32768
	ds_read_b128 v[202:205], v153 offset:33792
	ds_read_b128 v[206:209], v153 offset:34816
	ds_read_b128 v[210:213], v153 offset:35840
	ds_read_b128 v[214:217], v153 offset:36864
	ds_read_b128 v[218:221], v153 offset:37888
	ds_read_b128 v[222:225], v153 offset:38912
	ds_read_b128 v[226:229], v153 offset:39936
	global_load_lds_dwordx4 v[178:179], off
	v_lshl_add_u64 v[178:179], s[0:1], 0, v[138:139]
	s_mov_b32 m0, s69
	s_nop 0
	global_load_lds_dwordx4 v[178:179], off
	s_waitcnt vmcnt(8)
	s_waitcnt lgkmcnt(0)
	s_barrier
	s_waitcnt lgkmcnt(0)
	v_mfma_f32_16x16x32_bf16 v[126:129], v[146:149], v[198:201], v[126:129]
	v_mfma_f32_16x16x32_bf16 v[122:125], v[158:161], v[198:201], v[122:125]
	v_mfma_f32_16x16x32_bf16 v[110:113], v[146:149], v[206:209], v[110:113]
	v_mfma_f32_16x16x32_bf16 v[106:109], v[158:161], v[206:209], v[106:109]
	v_mfma_f32_16x16x32_bf16 v[94:97], v[146:149], v[214:217], v[94:97]
	v_mfma_f32_16x16x32_bf16 v[90:93], v[158:161], v[214:217], v[90:93]
	v_mfma_f32_16x16x32_bf16 v[76:79], v[146:149], v[222:225], v[76:79]
	v_mfma_f32_16x16x32_bf16 v[72:75], v[158:161], v[222:225], v[72:75]
	v_mfma_f32_16x16x32_bf16 v[126:129], v[154:157], v[202:205], v[126:129]
	v_mfma_f32_16x16x32_bf16 v[122:125], v[162:165], v[202:205], v[122:125]
	v_mfma_f32_16x16x32_bf16 v[110:113], v[154:157], v[210:213], v[110:113]
	v_mfma_f32_16x16x32_bf16 v[106:109], v[162:165], v[210:213], v[106:109]
	v_mfma_f32_16x16x32_bf16 v[94:97], v[154:157], v[218:221], v[94:97]
	v_mfma_f32_16x16x32_bf16 v[90:93], v[162:165], v[218:221], v[90:93]
	v_mfma_f32_16x16x32_bf16 v[76:79], v[154:157], v[226:229], v[76:79]
	v_mfma_f32_16x16x32_bf16 v[72:75], v[162:165], v[226:229], v[72:75]
	v_mfma_f32_16x16x32_bf16 v[118:121], v[182:185], v[198:201], v[118:121]
	v_mfma_f32_16x16x32_bf16 v[114:117], v[190:193], v[198:201], v[114:117]
	v_mfma_f32_16x16x32_bf16 v[102:105], v[182:185], v[206:209], v[102:105]
	v_mfma_f32_16x16x32_bf16 v[98:101], v[190:193], v[206:209], v[98:101]
	v_mfma_f32_16x16x32_bf16 v[86:89], v[182:185], v[214:217], v[86:89]
	v_mfma_f32_16x16x32_bf16 v[82:85], v[190:193], v[214:217], v[82:85]
	v_mfma_f32_16x16x32_bf16 v[68:71], v[182:185], v[222:225], v[68:71]
	v_mfma_f32_16x16x32_bf16 v[64:67], v[190:193], v[222:225], v[64:67]
	v_mfma_f32_16x16x32_bf16 v[118:121], v[186:189], v[202:205], v[118:121]
	v_mfma_f32_16x16x32_bf16 v[114:117], v[194:197], v[202:205], v[114:117]
	v_mfma_f32_16x16x32_bf16 v[102:105], v[186:189], v[210:213], v[102:105]
	v_mfma_f32_16x16x32_bf16 v[98:101], v[194:197], v[210:213], v[98:101]
	v_mfma_f32_16x16x32_bf16 v[86:89], v[186:189], v[218:221], v[86:89]
	v_mfma_f32_16x16x32_bf16 v[82:85], v[194:197], v[218:221], v[82:85]
	v_mfma_f32_16x16x32_bf16 v[68:71], v[186:189], v[226:229], v[68:71]
	v_mfma_f32_16x16x32_bf16 v[64:67], v[194:197], v[226:229], v[64:67]
	s_barrier
; #define PG8_STAGE(bufoff, gbase, voff) do { _Pragma("unroll") for (int _i = 0; _i < 2; ++_i) \
;         __builtin_amdgcn_global_load_lds((const unsigned*)((const char*)(gbase) + (voff)[_i]), (LAS unsigned*)(lds + (bufoff) + ldsw + _i * 8192), 16, 0, 0); } while (0)
; #define PG8_LDA(dst, b, h) do { _Pragma("unroll") for (int m = 0; m < 4; ++m) _Pragma("unroll") for (int k = 0; k < 2; ++k) dst[m][k] = *(const LAS bf16x8*)(lds + PG8_SA(b, h) + aoff + m * 2048 + k * 1024); } while (0)
; #define PG8_MMA(ai, bj, At, Bt) do { __builtin_amdgcn_s_setprio(1); _Pragma("unroll") for (int m = 0; m < 4; ++m) _Pragma("unroll") for (int n = 0; n < 2; ++n) _Pragma("unroll") for (int k = 0; k < 2; ++k) \
;         acc[ai][bj][m][n] = __builtin_amdgcn_mfma_f32_16x16x32_bf16(Bt[n][k], At[m][k], acc[ai][bj][m][n], 0, 0, 0); __builtin_amdgcn_s_setprio(0); } while (0)
; #define PG8_WAIT_V(n) asm volatile("s_waitcnt vmcnt(" #n ")" ::: "memory")
; #define PG8_WAIT_L(n) asm volatile("s_waitcnt lgkmcnt(" #n ")" ::: "memory")
; #define PG8_BAR __builtin_amdgcn_s_barrier()
; #define PG8_SCHED __builtin_amdgcn_sched_barrier(0)
; template <class Epi, bool ALIGN_EPI>
; __device__ __forceinline__ void gemm_phase(LAS unsigned char* lds, const Gemm g, const StaticOrder S, const Epi E) {
;     ...
;             PG8_LDA(At, 1, 1); PG8_STAGE(PG8_SB(1, 0), b3, voffB); PG8_STAGE(PG8_SB(1, 1), b3 + hstepB, voffB); PG8_STAGE(PG8_SA(1, 0), a3, voffA);
;             PG8_WAIT_V(8); PG8_WAIT_L(0); PG8_BAR; PG8_MMA(1, 0, At, B0); PG8_MMA(1, 1, At, B1); PG8_BAR; PG8_SCHED;
;         }
;         if constexpr (ALIGN_EPI) { if (wr == 0) PG8_BAR; }
	s_add_i32 s0, s12, s65
	v_lshl_add_u64 v[168:169], v[168:169], 0, s[80:81]
	s_mov_b32 m0, s0
	ds_read_b128 v[198:201], v153 offset:49152
	ds_read_b128 v[202:205], v153 offset:50176
	ds_read_b128 v[206:209], v153 offset:51200
	ds_read_b128 v[210:213], v153 offset:52224
	ds_read_b128 v[214:217], v153 offset:53248
	ds_read_b128 v[218:221], v153 offset:54272
	ds_read_b128 v[222:225], v153 offset:55296
	ds_read_b128 v[226:229], v153 offset:56320
	global_load_lds_dwordx4 v[168:169], off
	s_add_i32 m0, s0, 0x2000
	s_add_u32 s0, s52, 0xb0080
	v_lshl_add_u64 v[168:169], v[170:171], 0, s[80:81]
	s_addc_u32 s1, s53, 0
	s_add_i32 s12, s15, s65
	global_load_lds_dwordx4 v[168:169], off
	v_lshl_add_u64 v[168:169], s[0:1], 0, v[80:81]
	s_mov_b32 m0, s12
	s_nop 0
	global_load_lds_dwordx4 v[168:169], off
	v_lshl_add_u64 v[168:169], s[0:1], 0, v[140:141]
	s_add_i32 m0, s12, 0x2000
	s_nop 0
	global_load_lds_dwordx4 v[168:169], off
	v_lshl_add_u64 v[168:169], v[172:173], 0, s[80:81]
	s_mov_b32 m0, s73
	s_nop 0
	global_load_lds_dwordx4 v[168:169], off
	v_lshl_add_u64 v[168:169], v[176:177], 0, s[80:81]
	s_mov_b32 m0, s74
	s_nop 0
	global_load_lds_dwordx4 v[168:169], off
	s_waitcnt vmcnt(8)
	s_waitcnt lgkmcnt(0)
	s_barrier
	s_waitcnt lgkmcnt(0)
	v_mfma_f32_16x16x32_bf16 v[60:63], v[146:149], v[198:201], v[60:63]
	v_mfma_f32_16x16x32_bf16 v[56:59], v[158:161], v[198:201], v[56:59]
	v_mfma_f32_16x16x32_bf16 v[44:47], v[146:149], v[206:209], v[44:47]
	v_mfma_f32_16x16x32_bf16 v[40:43], v[158:161], v[206:209], v[40:43]
	v_mfma_f32_16x16x32_bf16 v[28:31], v[146:149], v[214:217], v[28:31]
	v_mfma_f32_16x16x32_bf16 v[24:27], v[158:161], v[214:217], v[24:27]
	v_mfma_f32_16x16x32_bf16 v[12:15], v[146:149], v[222:225], v[12:15]
	v_mfma_f32_16x16x32_bf16 v[8:11], v[158:161], v[222:225], v[8:11]
	v_mfma_f32_16x16x32_bf16 v[60:63], v[154:157], v[202:205], v[60:63]
	v_mfma_f32_16x16x32_bf16 v[56:59], v[162:165], v[202:205], v[56:59]
	v_mfma_f32_16x16x32_bf16 v[44:47], v[154:157], v[210:213], v[44:47]
	v_mfma_f32_16x16x32_bf16 v[40:43], v[162:165], v[210:213], v[40:43]
	v_mfma_f32_16x16x32_bf16 v[28:31], v[154:157], v[218:221], v[28:31]
	v_mfma_f32_16x16x32_bf16 v[24:27], v[162:165], v[218:221], v[24:27]
	v_mfma_f32_16x16x32_bf16 v[12:15], v[154:157], v[226:229], v[12:15]
	v_mfma_f32_16x16x32_bf16 v[8:11], v[162:165], v[226:229], v[8:11]
	v_mfma_f32_16x16x32_bf16 v[52:55], v[182:185], v[198:201], v[52:55]
	v_mfma_f32_16x16x32_bf16 v[48:51], v[190:193], v[198:201], v[48:51]
	v_mfma_f32_16x16x32_bf16 v[36:39], v[182:185], v[206:209], v[36:39]
	v_mfma_f32_16x16x32_bf16 v[32:35], v[190:193], v[206:209], v[32:35]
	v_mfma_f32_16x16x32_bf16 v[20:23], v[182:185], v[214:217], v[20:23]
	v_mfma_f32_16x16x32_bf16 v[16:19], v[190:193], v[214:217], v[16:19]
	v_mfma_f32_16x16x32_bf16 v[4:7], v[182:185], v[222:225], v[4:7]
	v_mfma_f32_16x16x32_bf16 v[0:3], v[190:193], v[222:225], v[0:3]
	v_mfma_f32_16x16x32_bf16 v[52:55], v[186:189], v[202:205], v[52:55]
	v_mfma_f32_16x16x32_bf16 v[48:51], v[194:197], v[202:205], v[48:51]
	v_mfma_f32_16x16x32_bf16 v[36:39], v[186:189], v[210:213], v[36:39]
	v_mfma_f32_16x16x32_bf16 v[32:35], v[194:197], v[210:213], v[32:35]
	v_mfma_f32_16x16x32_bf16 v[20:23], v[186:189], v[218:221], v[20:23]
	v_mfma_f32_16x16x32_bf16 v[16:19], v[194:197], v[218:221], v[16:19]
	v_mfma_f32_16x16x32_bf16 v[4:7], v[186:189], v[226:229], v[4:7]
	v_mfma_f32_16x16x32_bf16 v[0:3], v[194:197], v[226:229], v[0:3]
	s_barrier
	s_add_i32 s30, s30, 2
	s_add_u32 s28, s28, 0x100
	s_addc_u32 s29, s29, 0
	s_cmp_gt_u32 s30, 41
	s_mov_b64 s[48:49], s[50:51]
	s_cbranch_scc0 .LBB0_728
	s_and_b64 vcc, exec, s[44:45]
	s_cbranch_vccz .LBB0_731
	s_barrier

; #define PG8_STAGE(bufoff, gbase, voff) do { _Pragma("unroll") for (int _i = 0; _i < 2; ++_i) \
;         __builtin_amdgcn_global_load_lds((const unsigned*)((const char*)(gbase) + (voff)[_i]), (LAS unsigned*)(lds + (bufoff) + ldsw + _i * 8192), 16, 0, 0); } while (0)
; #define PG8_LDA(dst, b, h) do { _Pragma("unroll") for (int m = 0; m < 4; ++m) _Pragma("unroll") for (int k = 0; k < 2; ++k) dst[m][k] = *(const LAS bf16x8*)(lds + PG8_SA(b, h) + aoff + m * 2048 + k * 1024); } while (0)
; #define PG8_LDB(dst, b, h) do { _Pragma("unroll") for (int n = 0; n < 2; ++n) _Pragma("unroll") for (int k = 0; k < 2; ++k) dst[n][k] = *(const LAS bf16x8*)(lds + PG8_SB(b, h) + boff + n * 2048 + k * 1024); } while (0)
; #define PG8_MMA(ai, bj, At, Bt) do { __builtin_amdgcn_s_setprio(1); _Pragma("unroll") for (int m = 0; m < 4; ++m) _Pragma("unroll") for (int n = 0; n < 2; ++n) _Pragma("unroll") for (int k = 0; k < 2; ++k) \
;         acc[ai][bj][m][n] = __builtin_amdgcn_mfma_f32_16x16x32_bf16(Bt[n][k], At[m][k], acc[ai][bj][m][n], 0, 0, 0); __builtin_amdgcn_s_setprio(0); } while (0)
; #define PG8_WAIT_V(n) asm volatile("s_waitcnt vmcnt(" #n ")" ::: "memory")
; #define PG8_WAIT_L(n) asm volatile("s_waitcnt lgkmcnt(" #n ")" ::: "memory")
; #define PG8_BAR __builtin_amdgcn_s_barrier()
; #define PG8_SCHED __builtin_amdgcn_sched_barrier(0)
; template <class Epi, bool ALIGN_EPI>
; __device__ __forceinline__ void gemm_phase(LAS unsigned char* lds, const Gemm g, const StaticOrder S, const Epi E) {
;     ...
;             const bool last = (t == nt - 2);
;             const char* a1 = cA + (size_t)(t + 1) * kstep;
;             const char* a2 = last ? nA : cA + (size_t)(t + 2) * kstep; const char* b2 = last ? nB : cB + (size_t)(t + 2) * kstep;
;             const char* a3 = a2 + kstep; const char* b3 = b2 + kstep;
;             PG8_LDB(B0, 0, 0); PG8_LDB(B1, 0, 1); PG8_SCHED; PG8_LDA(At, 0, 0); PG8_STAGE(PG8_SA(1, 1), a1 + hstepA, voffA);
;             PG8_WAIT_V(8); PG8_WAIT_L(0); PG8_BAR; PG8_MMA(0, 0, At, B0); PG8_MMA(0, 1, At, B1); PG8_BAR; PG8_SCHED;
;             PG8_LDA(At, 0, 1); PG8_STAGE(PG8_SB(0, 0), b2, voffB); PG8_STAGE(PG8_SB(0, 1), b2 + hstepB, voffB); PG8_STAGE(PG8_SA(0, 0), a2, voffA);
;             PG8_WAIT_V(8); PG8_WAIT_L(0); PG8_BAR; PG8_MMA(1, 0, At, B0); PG8_MMA(1, 1, At, B1); PG8_BAR; PG8_SCHED;
.LBB0_853:
	s_add_u32 s0, s2, 0xfffc0080
	s_addc_u32 s1, s3, -1
	s_add_i32 s12, 0, 0x10000
	s_cmp_eq_u32 s68, 12
	s_cselect_b32 s67, s34, s1
	s_cselect_b32 s66, s35, s0
	v_add_u32_e32 v130, s12, v163
	s_cselect_b32 s45, s51, s61
	s_cselect_b32 s44, s53, s58
	s_add_i32 s15, 0, 0x14000
	ds_read_b128 v[182:185], v130
	ds_read_b128 v[186:189], v130 offset:1024
	ds_read_b128 v[190:193], v130 offset:2048
	ds_read_b128 v[194:197], v130 offset:3072
	v_add_u32_e32 v130, s15, v163
	ds_read_b128 v[198:201], v130
	ds_read_b128 v[202:205], v130 offset:1024
	ds_read_b128 v[206:209], v130 offset:2048
	ds_read_b128 v[210:213], v130 offset:3072
	v_lshl_add_u64 v[172:173], s[2:3], 0, v[152:153]
	s_add_i32 m0, s24, 0xc000
	ds_read_b128 v[214:217], v165
	ds_read_b128 v[218:221], v165 offset:1024
	ds_read_b128 v[222:225], v165 offset:2048
	ds_read_b128 v[226:229], v165 offset:3072
	ds_read_b128 v[230:233], v165 offset:4096
	ds_read_b128 v[234:237], v165 offset:5120
	ds_read_b128 v[238:241], v165 offset:6144
	ds_read_b128 v[242:245], v165 offset:7168
	global_load_lds_dwordx4 v[172:173], off
	v_lshl_add_u64 v[172:173], s[2:3], 0, v[154:155]
	s_add_i32 m0, s24, 0xe000
	s_nop 0
	global_load_lds_dwordx4 v[172:173], off
	s_waitcnt vmcnt(8)
	s_waitcnt lgkmcnt(0)
	s_barrier
	s_waitcnt lgkmcnt(0)
	v_mfma_f32_16x16x32_bf16 v[126:129], v[182:185], v[214:217], v[126:129]
	v_mfma_f32_16x16x32_bf16 v[122:125], v[190:193], v[214:217], v[122:125]
	v_mfma_f32_16x16x32_bf16 v[114:117], v[182:185], v[222:225], v[114:117]
	v_mfma_f32_16x16x32_bf16 v[106:109], v[190:193], v[222:225], v[106:109]
	v_mfma_f32_16x16x32_bf16 v[98:101], v[182:185], v[230:233], v[98:101]
	v_mfma_f32_16x16x32_bf16 v[90:93], v[190:193], v[230:233], v[90:93]
	v_mfma_f32_16x16x32_bf16 v[82:85], v[182:185], v[238:241], v[82:85]
	v_mfma_f32_16x16x32_bf16 v[72:75], v[190:193], v[238:241], v[72:75]
	v_mfma_f32_16x16x32_bf16 v[126:129], v[186:189], v[218:221], v[126:129]
	v_mfma_f32_16x16x32_bf16 v[122:125], v[194:197], v[218:221], v[122:125]
	v_mfma_f32_16x16x32_bf16 v[114:117], v[186:189], v[226:229], v[114:117]
	v_mfma_f32_16x16x32_bf16 v[106:109], v[194:197], v[226:229], v[106:109]
	v_mfma_f32_16x16x32_bf16 v[98:101], v[186:189], v[234:237], v[98:101]
	v_mfma_f32_16x16x32_bf16 v[90:93], v[194:197], v[234:237], v[90:93]
	v_mfma_f32_16x16x32_bf16 v[82:85], v[186:189], v[242:245], v[82:85]
	v_mfma_f32_16x16x32_bf16 v[72:75], v[194:197], v[242:245], v[72:75]
	v_mfma_f32_16x16x32_bf16 v[118:121], v[198:201], v[214:217], v[118:121]
	v_mfma_f32_16x16x32_bf16 v[110:113], v[206:209], v[214:217], v[110:113]
	v_mfma_f32_16x16x32_bf16 v[102:105], v[198:201], v[222:225], v[102:105]
	v_mfma_f32_16x16x32_bf16 v[94:97], v[206:209], v[222:225], v[94:97]
	v_mfma_f32_16x16x32_bf16 v[86:89], v[198:201], v[230:233], v[86:89]
	v_mfma_f32_16x16x32_bf16 v[76:79], v[206:209], v[230:233], v[76:79]
	v_mfma_f32_16x16x32_bf16 v[68:71], v[198:201], v[238:241], v[68:71]
	v_mfma_f32_16x16x32_bf16 v[64:67], v[206:209], v[238:241], v[64:67]
	v_mfma_f32_16x16x32_bf16 v[118:121], v[202:205], v[218:221], v[118:121]
	v_mfma_f32_16x16x32_bf16 v[110:113], v[210:213], v[218:221], v[110:113]
	v_mfma_f32_16x16x32_bf16 v[102:105], v[202:205], v[226:229], v[102:105]
	v_mfma_f32_16x16x32_bf16 v[94:97], v[210:213], v[226:229], v[94:97]
	v_mfma_f32_16x16x32_bf16 v[86:89], v[202:205], v[234:237], v[86:89]
	v_mfma_f32_16x16x32_bf16 v[76:79], v[210:213], v[234:237], v[76:79]
	v_mfma_f32_16x16x32_bf16 v[68:71], v[202:205], v[242:245], v[68:71]
	v_mfma_f32_16x16x32_bf16 v[64:67], v[210:213], v[242:245], v[64:67]
	s_barrier
	s_add_i32 s0, s12, s23
	v_lshl_add_u64 v[172:173], s[44:45], 0, v[80:81]
	s_mov_b32 m0, s0
	ds_read_b128 v[214:217], v165 offset:16384
	ds_read_b128 v[218:221], v165 offset:17408
	ds_read_b128 v[222:225], v165 offset:18432
	ds_read_b128 v[226:229], v165 offset:19456
	ds_read_b128 v[230:233], v165 offset:20480
	ds_read_b128 v[234:237], v165 offset:21504
	ds_read_b128 v[238:241], v165 offset:22528
	ds_read_b128 v[242:245], v165 offset:23552
	global_load_lds_dwordx4 v[172:173], off
	s_add_i32 m0, s0, 0x2000
	s_add_u32 s0, s44, 0x40000
	v_lshl_add_u64 v[176:177], s[44:45], 0, v[136:137]
	s_addc_u32 s1, s45, 0
	s_add_i32 s12, s15, s23
	global_load_lds_dwordx4 v[176:177], off
	v_lshl_add_u64 v[178:179], s[0:1], 0, v[80:81]
	s_mov_b32 m0, s12
	v_lshl_add_u64 v[246:247], s[66:67], 0, v[138:139]
	global_load_lds_dwordx4 v[178:179], off
	v_lshl_add_u64 v[178:179], s[0:1], 0, v[136:137]
	s_add_i32 m0, s12, 0x2000
	s_nop 0
	global_load_lds_dwordx4 v[178:179], off
	v_lshl_add_u64 v[178:179], s[66:67], 0, v[140:141]
	s_mov_b32 m0, s24
	s_nop 0
	global_load_lds_dwordx4 v[178:179], off
	s_mov_b32 m0, s25
	s_nop 0
	global_load_lds_dwordx4 v[246:247], off
	s_waitcnt vmcnt(8)
	s_waitcnt lgkmcnt(0)
	s_barrier
; #define PG8_STAGE(bufoff, gbase, voff) do { _Pragma("unroll") for (int _i = 0; _i < 2; ++_i) \
;         __builtin_amdgcn_global_load_lds((const unsigned*)((const char*)(gbase) + (voff)[_i]), (LAS unsigned*)(lds + (bufoff) + ldsw + _i * 8192), 16, 0, 0); } while (0)
; #define PG8_LDA(dst, b, h) do { _Pragma("unroll") for (int m = 0; m < 4; ++m) _Pragma("unroll") for (int k = 0; k < 2; ++k) dst[m][k] = *(const LAS bf16x8*)(lds + PG8_SA(b, h) + aoff + m * 2048 + k * 1024); } while (0)
; #define PG8_LDB(dst, b, h) do { _Pragma("unroll") for (int n = 0; n < 2; ++n) _Pragma("unroll") for (int k = 0; k < 2; ++k) dst[n][k] = *(const LAS bf16x8*)(lds + PG8_SB(b, h) + boff + n * 2048 + k * 1024); } while (0)
; #define PG8_MMA(ai, bj, At, Bt) do { __builtin_amdgcn_s_setprio(1); _Pragma("unroll") for (int m = 0; m < 4; ++m) _Pragma("unroll") for (int n = 0; n < 2; ++n) _Pragma("unroll") for (int k = 0; k < 2; ++k) \
;         acc[ai][bj][m][n] = __builtin_amdgcn_mfma_f32_16x16x32_bf16(Bt[n][k], At[m][k], acc[ai][bj][m][n], 0, 0, 0); __builtin_amdgcn_s_setprio(0); } while (0)
; #define PG8_WAIT_V(n) asm volatile("s_waitcnt vmcnt(" #n ")" ::: "memory")
; #define PG8_WAIT_L(n) asm volatile("s_waitcnt lgkmcnt(" #n ")" ::: "memory")
; #define PG8_BAR __builtin_amdgcn_s_barrier()
; #define PG8_SCHED __builtin_amdgcn_sched_barrier(0)
; template <class Epi, bool ALIGN_EPI>
; __device__ __forceinline__ void gemm_phase(LAS unsigned char* lds, const Gemm g, const StaticOrder S, const Epi E) {
;     ...
;             PG8_WAIT_V(8); PG8_WAIT_L(0); PG8_BAR; PG8_MMA(1, 0, At, B0); PG8_MMA(1, 1, At, B1); PG8_BAR; PG8_SCHED;
;             PG8_LDB(B0, 1, 0); PG8_LDB(B1, 1, 1); PG8_SCHED; PG8_LDA(At, 1, 0); PG8_STAGE(PG8_SA(0, 1), a2 + hstepA, voffA);
;             PG8_WAIT_V(8); PG8_WAIT_L(0); PG8_BAR; PG8_MMA(0, 0, At, B0); PG8_MMA(0, 1, At, B1); PG8_BAR; PG8_SCHED;
	s_waitcnt lgkmcnt(0)
	v_mfma_f32_16x16x32_bf16 v[60:63], v[182:185], v[214:217], v[60:63]
	v_mfma_f32_16x16x32_bf16 v[56:59], v[190:193], v[214:217], v[56:59]
	v_mfma_f32_16x16x32_bf16 v[48:51], v[182:185], v[222:225], v[48:51]
	v_mfma_f32_16x16x32_bf16 v[40:43], v[190:193], v[222:225], v[40:43]
	v_mfma_f32_16x16x32_bf16 v[32:35], v[182:185], v[230:233], v[32:35]
	v_mfma_f32_16x16x32_bf16 v[24:27], v[190:193], v[230:233], v[24:27]
	v_mfma_f32_16x16x32_bf16 v[16:19], v[182:185], v[238:241], v[16:19]
	v_mfma_f32_16x16x32_bf16 v[8:11], v[190:193], v[238:241], v[8:11]
	v_mfma_f32_16x16x32_bf16 v[60:63], v[186:189], v[218:221], v[60:63]
	v_mfma_f32_16x16x32_bf16 v[56:59], v[194:197], v[218:221], v[56:59]
	v_mfma_f32_16x16x32_bf16 v[48:51], v[186:189], v[226:229], v[48:51]
	v_mfma_f32_16x16x32_bf16 v[40:43], v[194:197], v[226:229], v[40:43]
	v_mfma_f32_16x16x32_bf16 v[32:35], v[186:189], v[234:237], v[32:35]
	v_mfma_f32_16x16x32_bf16 v[24:27], v[194:197], v[234:237], v[24:27]
	v_mfma_f32_16x16x32_bf16 v[16:19], v[186:189], v[242:245], v[16:19]
	v_mfma_f32_16x16x32_bf16 v[8:11], v[194:197], v[242:245], v[8:11]
	v_mfma_f32_16x16x32_bf16 v[52:55], v[198:201], v[214:217], v[52:55]
	v_mfma_f32_16x16x32_bf16 v[44:47], v[206:209], v[214:217], v[44:47]
	v_mfma_f32_16x16x32_bf16 v[36:39], v[198:201], v[222:225], v[36:39]
	v_mfma_f32_16x16x32_bf16 v[28:31], v[206:209], v[222:225], v[28:31]
	v_mfma_f32_16x16x32_bf16 v[20:23], v[198:201], v[230:233], v[20:23]
	v_mfma_f32_16x16x32_bf16 v[12:15], v[206:209], v[230:233], v[12:15]
	v_mfma_f32_16x16x32_bf16 v[4:7], v[198:201], v[238:241], v[4:7]
	v_mfma_f32_16x16x32_bf16 v[0:3], v[206:209], v[238:241], v[0:3]
	v_mfma_f32_16x16x32_bf16 v[52:55], v[202:205], v[218:221], v[52:55]
	v_mfma_f32_16x16x32_bf16 v[44:47], v[210:213], v[218:221], v[44:47]
	v_mfma_f32_16x16x32_bf16 v[36:39], v[202:205], v[226:229], v[36:39]
	v_mfma_f32_16x16x32_bf16 v[28:31], v[210:213], v[226:229], v[28:31]
	v_mfma_f32_16x16x32_bf16 v[20:23], v[202:205], v[234:237], v[20:23]
	v_mfma_f32_16x16x32_bf16 v[12:15], v[210:213], v[234:237], v[12:15]
	v_mfma_f32_16x16x32_bf16 v[4:7], v[202:205], v[242:245], v[4:7]
	v_mfma_f32_16x16x32_bf16 v[0:3], v[210:213], v[242:245], v[0:3]
	s_barrier
	s_add_i32 s12, 0, 0x18000
	v_add_u32_e32 v130, s12, v163
	s_add_i32 s15, 0, 0x1c000
	ds_read_b128 v[182:185], v130
	ds_read_b128 v[186:189], v130 offset:1024
	ds_read_b128 v[190:193], v130 offset:2048
	ds_read_b128 v[194:197], v130 offset:3072
	v_add_u32_e32 v130, s15, v163
	ds_read_b128 v[198:201], v130
	ds_read_b128 v[202:205], v130 offset:1024
	ds_read_b128 v[206:209], v130 offset:2048
	ds_read_b128 v[210:213], v130 offset:3072
	s_add_u32 s0, s66, 0x40000
	s_addc_u32 s1, s67, 0
	s_mov_b32 m0, s26
	v_lshl_add_u64 v[248:249], s[0:1], 0, v[140:141]
	ds_read_b128 v[214:217], v165 offset:32768
	ds_read_b128 v[218:221], v165 offset:33792
	ds_read_b128 v[222:225], v165 offset:34816
	ds_read_b128 v[226:229], v165 offset:35840
	ds_read_b128 v[230:233], v165 offset:36864
	ds_read_b128 v[234:237], v165 offset:37888
	ds_read_b128 v[238:241], v165 offset:38912
	ds_read_b128 v[242:245], v165 offset:39936
	global_load_lds_dwordx4 v[248:249], off
	v_lshl_add_u64 v[248:249], s[0:1], 0, v[138:139]
	s_mov_b32 m0, s27
	s_nop 0
	global_load_lds_dwordx4 v[248:249], off
	s_waitcnt vmcnt(8)
	s_waitcnt lgkmcnt(0)
	s_barrier
	s_waitcnt lgkmcnt(0)
	v_mfma_f32_16x16x32_bf16 v[126:129], v[182:185], v[214:217], v[126:129]
	v_mfma_f32_16x16x32_bf16 v[122:125], v[190:193], v[214:217], v[122:125]
	v_mfma_f32_16x16x32_bf16 v[114:117], v[182:185], v[222:225], v[114:117]
	v_mfma_f32_16x16x32_bf16 v[106:109], v[190:193], v[222:225], v[106:109]
	v_mfma_f32_16x16x32_bf16 v[98:101], v[182:185], v[230:233], v[98:101]
	v_mfma_f32_16x16x32_bf16 v[90:93], v[190:193], v[230:233], v[90:93]
	v_mfma_f32_16x16x32_bf16 v[82:85], v[182:185], v[238:241], v[82:85]
	v_mfma_f32_16x16x32_bf16 v[72:75], v[190:193], v[238:241], v[72:75]
	v_mfma_f32_16x16x32_bf16 v[126:129], v[186:189], v[218:221], v[126:129]
	v_mfma_f32_16x16x32_bf16 v[122:125], v[194:197], v[218:221], v[122:125]
	v_mfma_f32_16x16x32_bf16 v[114:117], v[186:189], v[226:229], v[114:117]
	v_mfma_f32_16x16x32_bf16 v[106:109], v[194:197], v[226:229], v[106:109]
	v_mfma_f32_16x16x32_bf16 v[98:101], v[186:189], v[234:237], v[98:101]
	v_mfma_f32_16x16x32_bf16 v[90:93], v[194:197], v[234:237], v[90:93]
	v_mfma_f32_16x16x32_bf16 v[82:85], v[186:189], v[242:245], v[82:85]
	v_mfma_f32_16x16x32_bf16 v[72:75], v[194:197], v[242:245], v[72:75]
	v_mfma_f32_16x16x32_bf16 v[118:121], v[198:201], v[214:217], v[118:121]
	v_mfma_f32_16x16x32_bf16 v[110:113], v[206:209], v[214:217], v[110:113]
	v_mfma_f32_16x16x32_bf16 v[102:105], v[198:201], v[222:225], v[102:105]
	v_mfma_f32_16x16x32_bf16 v[94:97], v[206:209], v[222:225], v[94:97]
	v_mfma_f32_16x16x32_bf16 v[86:89], v[198:201], v[230:233], v[86:89]
	v_mfma_f32_16x16x32_bf16 v[76:79], v[206:209], v[230:233], v[76:79]
	v_mfma_f32_16x16x32_bf16 v[68:71], v[198:201], v[238:241], v[68:71]
	v_mfma_f32_16x16x32_bf16 v[64:67], v[206:209], v[238:241], v[64:67]
	v_mfma_f32_16x16x32_bf16 v[118:121], v[202:205], v[218:221], v[118:121]
	v_mfma_f32_16x16x32_bf16 v[110:113], v[210:213], v[218:221], v[110:113]
	v_mfma_f32_16x16x32_bf16 v[102:105], v[202:205], v[226:229], v[102:105]
	v_mfma_f32_16x16x32_bf16 v[94:97], v[210:213], v[226:229], v[94:97]
	v_mfma_f32_16x16x32_bf16 v[86:89], v[202:205], v[234:237], v[86:89]
	v_mfma_f32_16x16x32_bf16 v[76:79], v[210:213], v[234:237], v[76:79]
	v_mfma_f32_16x16x32_bf16 v[68:71], v[202:205], v[242:245], v[68:71]
	v_mfma_f32_16x16x32_bf16 v[64:67], v[210:213], v[242:245], v[64:67]
	s_barrier
; #define PG8_STAGE(bufoff, gbase, voff) do { _Pragma("unroll") for (int _i = 0; _i < 2; ++_i) \
;         __builtin_amdgcn_global_load_lds((const unsigned*)((const char*)(gbase) + (voff)[_i]), (LAS unsigned*)(lds + (bufoff) + ldsw + _i * 8192), 16, 0, 0); } while (0)
; #define PG8_LDA(dst, b, h) do { _Pragma("unroll") for (int m = 0; m < 4; ++m) _Pragma("unroll") for (int k = 0; k < 2; ++k) dst[m][k] = *(const LAS bf16x8*)(lds + PG8_SA(b, h) + aoff + m * 2048 + k * 1024); } while (0)
; #define PG8_MMA(ai, bj, At, Bt) do { __builtin_amdgcn_s_setprio(1); _Pragma("unroll") for (int m = 0; m < 4; ++m) _Pragma("unroll") for (int n = 0; n < 2; ++n) _Pragma("unroll") for (int k = 0; k < 2; ++k) \
;         acc[ai][bj][m][n] = __builtin_amdgcn_mfma_f32_16x16x32_bf16(Bt[n][k], At[m][k], acc[ai][bj][m][n], 0, 0, 0); __builtin_amdgcn_s_setprio(0); } while (0)
; #define PG8_WAIT_V(n) asm volatile("s_waitcnt vmcnt(" #n ")" ::: "memory")
; #define PG8_WAIT_L(n) asm volatile("s_waitcnt lgkmcnt(" #n ")" ::: "memory")
; #define PG8_BAR __builtin_amdgcn_s_barrier()
; #define PG8_SCHED __builtin_amdgcn_sched_barrier(0)
; template <class Epi, bool ALIGN_EPI>
; __device__ __forceinline__ void gemm_phase(LAS unsigned char* lds, const Gemm g, const StaticOrder S, const Epi E) {
;     ...
;             PG8_LDA(At, 1, 1); PG8_STAGE(PG8_SB(1, 0), b3, voffB); PG8_STAGE(PG8_SB(1, 1), b3 + hstepB, voffB); PG8_STAGE(PG8_SA(1, 0), a3, voffA);
;             PG8_WAIT_V(8); PG8_WAIT_L(0); PG8_BAR; PG8_MMA(1, 0, At, B0); PG8_MMA(1, 1, At, B1); PG8_BAR; PG8_SCHED;
;         }
;         if constexpr (ALIGN_EPI) { if (wr == 0) PG8_BAR; }
	s_add_i32 s0, s12, s23
	v_lshl_add_u64 v[172:173], v[172:173], 0, s[80:81]
	s_mov_b32 m0, s0
	ds_read_b128 v[214:217], v165 offset:49152
	ds_read_b128 v[218:221], v165 offset:50176
	ds_read_b128 v[222:225], v165 offset:51200
	ds_read_b128 v[226:229], v165 offset:52224
	ds_read_b128 v[230:233], v165 offset:53248
	ds_read_b128 v[234:237], v165 offset:54272
	ds_read_b128 v[238:241], v165 offset:55296
	ds_read_b128 v[242:245], v165 offset:56320
	global_load_lds_dwordx4 v[172:173], off
	s_add_i32 m0, s0, 0x2000
	s_add_u32 s0, s44, 0x40080
	v_lshl_add_u64 v[172:173], v[176:177], 0, s[80:81]
	s_addc_u32 s1, s45, 0
	s_add_i32 s12, s15, s23
	global_load_lds_dwordx4 v[172:173], off
	v_lshl_add_u64 v[172:173], s[0:1], 0, v[80:81]
	s_mov_b32 m0, s12
	s_nop 0
	global_load_lds_dwordx4 v[172:173], off
	v_lshl_add_u64 v[172:173], s[0:1], 0, v[136:137]
	s_add_i32 m0, s12, 0x2000
	s_nop 0
	global_load_lds_dwordx4 v[172:173], off
	v_lshl_add_u64 v[172:173], v[178:179], 0, s[80:81]
	s_mov_b32 m0, s29
	s_nop 0
	global_load_lds_dwordx4 v[172:173], off
	v_lshl_add_u64 v[172:173], v[246:247], 0, s[80:81]
	s_mov_b32 m0, s30
	s_nop 0
	global_load_lds_dwordx4 v[172:173], off
	s_waitcnt vmcnt(8)
	s_waitcnt lgkmcnt(0)
	s_barrier
	s_waitcnt lgkmcnt(0)
	v_mfma_f32_16x16x32_bf16 v[60:63], v[182:185], v[214:217], v[60:63]
	v_mfma_f32_16x16x32_bf16 v[56:59], v[190:193], v[214:217], v[56:59]
	v_mfma_f32_16x16x32_bf16 v[48:51], v[182:185], v[222:225], v[48:51]
	v_mfma_f32_16x16x32_bf16 v[40:43], v[190:193], v[222:225], v[40:43]
	v_mfma_f32_16x16x32_bf16 v[32:35], v[182:185], v[230:233], v[32:35]
	v_mfma_f32_16x16x32_bf16 v[24:27], v[190:193], v[230:233], v[24:27]
	v_mfma_f32_16x16x32_bf16 v[16:19], v[182:185], v[238:241], v[16:19]
	v_mfma_f32_16x16x32_bf16 v[8:11], v[190:193], v[238:241], v[8:11]
	v_mfma_f32_16x16x32_bf16 v[60:63], v[186:189], v[218:221], v[60:63]
	v_mfma_f32_16x16x32_bf16 v[56:59], v[194:197], v[218:221], v[56:59]
	v_mfma_f32_16x16x32_bf16 v[48:51], v[186:189], v[226:229], v[48:51]
	v_mfma_f32_16x16x32_bf16 v[40:43], v[194:197], v[226:229], v[40:43]
	v_mfma_f32_16x16x32_bf16 v[32:35], v[186:189], v[234:237], v[32:35]
	v_mfma_f32_16x16x32_bf16 v[24:27], v[194:197], v[234:237], v[24:27]
	v_mfma_f32_16x16x32_bf16 v[16:19], v[186:189], v[242:245], v[16:19]
	v_mfma_f32_16x16x32_bf16 v[8:11], v[194:197], v[242:245], v[8:11]
	v_mfma_f32_16x16x32_bf16 v[52:55], v[198:201], v[214:217], v[52:55]
	v_mfma_f32_16x16x32_bf16 v[44:47], v[206:209], v[214:217], v[44:47]
	v_mfma_f32_16x16x32_bf16 v[36:39], v[198:201], v[222:225], v[36:39]
	v_mfma_f32_16x16x32_bf16 v[28:31], v[206:209], v[222:225], v[28:31]
	v_mfma_f32_16x16x32_bf16 v[20:23], v[198:201], v[230:233], v[20:23]
	v_mfma_f32_16x16x32_bf16 v[12:15], v[206:209], v[230:233], v[12:15]
	v_mfma_f32_16x16x32_bf16 v[4:7], v[198:201], v[238:241], v[4:7]
	v_mfma_f32_16x16x32_bf16 v[0:3], v[206:209], v[238:241], v[0:3]
	v_mfma_f32_16x16x32_bf16 v[52:55], v[202:205], v[218:221], v[52:55]
	v_mfma_f32_16x16x32_bf16 v[44:47], v[210:213], v[218:221], v[44:47]
	v_mfma_f32_16x16x32_bf16 v[36:39], v[202:205], v[226:229], v[36:39]
	v_mfma_f32_16x16x32_bf16 v[28:31], v[210:213], v[226:229], v[28:31]
	v_mfma_f32_16x16x32_bf16 v[20:23], v[202:205], v[234:237], v[20:23]
	v_mfma_f32_16x16x32_bf16 v[12:15], v[210:213], v[234:237], v[12:15]
	v_mfma_f32_16x16x32_bf16 v[4:7], v[202:205], v[242:245], v[4:7]
	v_mfma_f32_16x16x32_bf16 v[0:3], v[210:213], v[242:245], v[0:3]
	s_barrier
	s_add_i32 s68, s68, 2
	s_add_u32 s2, s2, 0x100
	s_addc_u32 s3, s3, 0
	s_add_u32 s58, s58, 0x100
	s_addc_u32 s61, s61, 0
	s_cmp_gt_u32 s68, 13
	s_cbranch_scc0 .LBB0_853
	s_and_b64 vcc, exec, s[48:49]
	s_cbranch_vccz .LBB0_856
	s_barrier

; #define PG8_STAGE(bufoff, gbase, voff) do { _Pragma("unroll") for (int _i = 0; _i < 2; ++_i) \
;         __builtin_amdgcn_global_load_lds((const unsigned*)((const char*)(gbase) + (voff)[_i]), (LAS unsigned*)(lds + (bufoff) + ldsw + _i * 8192), 16, 0, 0); } while (0)
; #define PG8_LDA(dst, b, h) do { _Pragma("unroll") for (int m = 0; m < 4; ++m) _Pragma("unroll") for (int k = 0; k < 2; ++k) dst[m][k] = *(const LAS bf16x8*)(lds + PG8_SA(b, h) + aoff + m * 2048 + k * 1024); } while (0)
; #define PG8_LDB(dst, b, h) do { _Pragma("unroll") for (int n = 0; n < 2; ++n) _Pragma("unroll") for (int k = 0; k < 2; ++k) dst[n][k] = *(const LAS bf16x8*)(lds + PG8_SB(b, h) + boff + n * 2048 + k * 1024); } while (0)
; #define PG8_MMA(ai, bj, At, Bt) do { __builtin_amdgcn_s_setprio(1); _Pragma("unroll") for (int m = 0; m < 4; ++m) _Pragma("unroll") for (int n = 0; n < 2; ++n) _Pragma("unroll") for (int k = 0; k < 2; ++k) \
;         acc[ai][bj][m][n] = __builtin_amdgcn_mfma_f32_16x16x32_bf16(Bt[n][k], At[m][k], acc[ai][bj][m][n], 0, 0, 0); __builtin_amdgcn_s_setprio(0); } while (0)
; #define PG8_WAIT_V(n) asm volatile("s_waitcnt vmcnt(" #n ")" ::: "memory")
; #define PG8_WAIT_L(n) asm volatile("s_waitcnt lgkmcnt(" #n ")" ::: "memory")
; #define PG8_BAR __builtin_amdgcn_s_barrier()
; #define PG8_SCHED __builtin_amdgcn_sched_barrier(0)
; template <class Epi, bool ALIGN_EPI>
; __device__ __forceinline__ void gemm_phase(LAS unsigned char* lds, const Gemm g, const StaticOrder S, const Epi E) {
;     ...
;             const bool last = (t == nt - 2);
;             const char* a1 = cA + (size_t)(t + 1) * kstep;
;             const char* a2 = last ? nA : cA + (size_t)(t + 2) * kstep; const char* b2 = last ? nB : cB + (size_t)(t + 2) * kstep;
;             const char* a3 = a2 + kstep; const char* b3 = b2 + kstep;
;             PG8_LDB(B0, 0, 0); PG8_LDB(B1, 0, 1); PG8_SCHED; PG8_LDA(At, 0, 0); PG8_STAGE(PG8_SA(1, 1), a1 + hstepA, voffA);
;             PG8_WAIT_V(8); PG8_WAIT_L(0); PG8_BAR; PG8_MMA(0, 0, At, B0); PG8_MMA(0, 1, At, B1); PG8_BAR; PG8_SCHED;
;             PG8_LDA(At, 0, 1); PG8_STAGE(PG8_SB(0, 0), b2, voffB); PG8_STAGE(PG8_SB(0, 1), b2 + hstepB, voffB); PG8_STAGE(PG8_SA(0, 0), a2, voffA);
;             PG8_WAIT_V(8); PG8_WAIT_L(0); PG8_BAR; PG8_MMA(1, 0, At, B0); PG8_MMA(1, 1, At, B1); PG8_BAR; PG8_SCHED;
.LBB0_1431:
	s_add_u32 s44, s62, 0x100
	s_addc_u32 s45, s63, 0
	s_add_i32 s0, 0, 0x10000
	s_cmp_eq_u32 s71, 12
	s_cselect_b32 s67, s51, s45
	s_cselect_b32 s66, s50, s44
	v_add_u32_e32 v130, s0, v152
	s_cselect_b32 s65, s34, s55
	s_cselect_b32 s64, s35, s49
	s_add_i32 s12, 0, 0x14000
	ds_read_b128 v[146:149], v130
	ds_read_b128 v[154:157], v130 offset:1024
	ds_read_b128 v[158:161], v130 offset:2048
	ds_read_b128 v[162:165], v130 offset:3072
	v_add_u32_e32 v130, s12, v152
	ds_read_b128 v[168:171], v130
	ds_read_b128 v[176:179], v130 offset:1024
	ds_read_b128 v[182:185], v130 offset:2048
	ds_read_b128 v[186:189], v130 offset:3072
	v_lshl_add_u64 v[130:131], s[62:63], 0, v[142:143]
	s_add_i32 m0, s27, 0xc000
	ds_read_b128 v[190:193], v153
	ds_read_b128 v[194:197], v153 offset:1024
	ds_read_b128 v[198:201], v153 offset:2048
	ds_read_b128 v[202:205], v153 offset:3072
	ds_read_b128 v[206:209], v153 offset:4096
	ds_read_b128 v[210:213], v153 offset:5120
	ds_read_b128 v[214:217], v153 offset:6144
	ds_read_b128 v[218:221], v153 offset:7168
	global_load_lds_dwordx4 v[130:131], off
	v_lshl_add_u64 v[130:131], s[62:63], 0, v[144:145]
	s_add_i32 m0, s27, 0xe000
	s_nop 0
	global_load_lds_dwordx4 v[130:131], off
	s_waitcnt vmcnt(8)
	s_waitcnt lgkmcnt(0)
	s_barrier
	s_waitcnt lgkmcnt(0)
	v_mfma_f32_16x16x32_bf16 v[126:129], v[146:149], v[190:193], v[126:129]
	v_mfma_f32_16x16x32_bf16 v[122:125], v[158:161], v[190:193], v[122:125]
	v_mfma_f32_16x16x32_bf16 v[110:113], v[146:149], v[198:201], v[110:113]
	v_mfma_f32_16x16x32_bf16 v[106:109], v[158:161], v[198:201], v[106:109]
	v_mfma_f32_16x16x32_bf16 v[94:97], v[146:149], v[206:209], v[94:97]
	v_mfma_f32_16x16x32_bf16 v[90:93], v[158:161], v[206:209], v[90:93]
	v_mfma_f32_16x16x32_bf16 v[76:79], v[146:149], v[214:217], v[76:79]
	v_mfma_f32_16x16x32_bf16 v[72:75], v[158:161], v[214:217], v[72:75]
	v_mfma_f32_16x16x32_bf16 v[126:129], v[154:157], v[194:197], v[126:129]
	v_mfma_f32_16x16x32_bf16 v[122:125], v[162:165], v[194:197], v[122:125]
	v_mfma_f32_16x16x32_bf16 v[110:113], v[154:157], v[202:205], v[110:113]
	v_mfma_f32_16x16x32_bf16 v[106:109], v[162:165], v[202:205], v[106:109]
	v_mfma_f32_16x16x32_bf16 v[94:97], v[154:157], v[210:213], v[94:97]
	v_mfma_f32_16x16x32_bf16 v[90:93], v[162:165], v[210:213], v[90:93]
	v_mfma_f32_16x16x32_bf16 v[76:79], v[154:157], v[218:221], v[76:79]
	v_mfma_f32_16x16x32_bf16 v[72:75], v[162:165], v[218:221], v[72:75]
	v_mfma_f32_16x16x32_bf16 v[118:121], v[168:171], v[190:193], v[118:121]
	v_mfma_f32_16x16x32_bf16 v[114:117], v[182:185], v[190:193], v[114:117]
	v_mfma_f32_16x16x32_bf16 v[102:105], v[168:171], v[198:201], v[102:105]
	v_mfma_f32_16x16x32_bf16 v[98:101], v[182:185], v[198:201], v[98:101]
	v_mfma_f32_16x16x32_bf16 v[86:89], v[168:171], v[206:209], v[86:89]
	v_mfma_f32_16x16x32_bf16 v[82:85], v[182:185], v[206:209], v[82:85]
	v_mfma_f32_16x16x32_bf16 v[68:71], v[168:171], v[214:217], v[68:71]
	v_mfma_f32_16x16x32_bf16 v[64:67], v[182:185], v[214:217], v[64:67]
	v_mfma_f32_16x16x32_bf16 v[118:121], v[176:179], v[194:197], v[118:121]
	v_mfma_f32_16x16x32_bf16 v[114:117], v[186:189], v[194:197], v[114:117]
	v_mfma_f32_16x16x32_bf16 v[102:105], v[176:179], v[202:205], v[102:105]
	v_mfma_f32_16x16x32_bf16 v[98:101], v[186:189], v[202:205], v[98:101]
	v_mfma_f32_16x16x32_bf16 v[86:89], v[176:179], v[210:213], v[86:89]
	v_mfma_f32_16x16x32_bf16 v[82:85], v[186:189], v[210:213], v[82:85]
	v_mfma_f32_16x16x32_bf16 v[68:71], v[176:179], v[218:221], v[68:71]
	v_mfma_f32_16x16x32_bf16 v[64:67], v[186:189], v[218:221], v[64:67]
	s_barrier
	s_add_i32 s0, s0, s26
	v_lshl_add_u64 v[130:131], s[64:65], 0, v[80:81]
	s_mov_b32 m0, s0
	ds_read_b128 v[190:193], v153 offset:16384
	ds_read_b128 v[194:197], v153 offset:17408
	ds_read_b128 v[198:201], v153 offset:18432
	ds_read_b128 v[202:205], v153 offset:19456
	ds_read_b128 v[206:209], v153 offset:20480
	ds_read_b128 v[210:213], v153 offset:21504
	ds_read_b128 v[214:217], v153 offset:22528
	ds_read_b128 v[218:221], v153 offset:23552
	global_load_lds_dwordx4 v[130:131], off
	s_add_i32 m0, s0, 0x2000
	s_add_u32 s0, s64, 0x40000
	v_lshl_add_u64 v[134:135], s[64:65], 0, v[140:141]
	s_addc_u32 s1, s65, 0
	s_add_i32 s12, s12, s26
	global_load_lds_dwordx4 v[134:135], off
	v_lshl_add_u64 v[172:173], s[0:1], 0, v[80:81]
	s_mov_b32 m0, s12
	v_lshl_add_u64 v[222:223], s[66:67], 0, v[138:139]
	global_load_lds_dwordx4 v[172:173], off
	v_lshl_add_u64 v[172:173], s[0:1], 0, v[140:141]
	s_add_i32 m0, s12, 0x2000
	s_nop 0
	global_load_lds_dwordx4 v[172:173], off
	v_lshl_add_u64 v[172:173], s[66:67], 0, v[136:137]
	s_mov_b32 m0, s27
	s_nop 0
	global_load_lds_dwordx4 v[172:173], off
	s_mov_b32 m0, s28
	s_nop 0
	global_load_lds_dwordx4 v[222:223], off
	s_waitcnt vmcnt(8)
	s_waitcnt lgkmcnt(0)
	s_barrier
; #define PG8_STAGE(bufoff, gbase, voff) do { _Pragma("unroll") for (int _i = 0; _i < 2; ++_i) \
;         __builtin_amdgcn_global_load_lds((const unsigned*)((const char*)(gbase) + (voff)[_i]), (LAS unsigned*)(lds + (bufoff) + ldsw + _i * 8192), 16, 0, 0); } while (0)
; #define PG8_LDA(dst, b, h) do { _Pragma("unroll") for (int m = 0; m < 4; ++m) _Pragma("unroll") for (int k = 0; k < 2; ++k) dst[m][k] = *(const LAS bf16x8*)(lds + PG8_SA(b, h) + aoff + m * 2048 + k * 1024); } while (0)
; #define PG8_LDB(dst, b, h) do { _Pragma("unroll") for (int n = 0; n < 2; ++n) _Pragma("unroll") for (int k = 0; k < 2; ++k) dst[n][k] = *(const LAS bf16x8*)(lds + PG8_SB(b, h) + boff + n * 2048 + k * 1024); } while (0)
; #define PG8_MMA(ai, bj, At, Bt) do { __builtin_amdgcn_s_setprio(1); _Pragma("unroll") for (int m = 0; m < 4; ++m) _Pragma("unroll") for (int n = 0; n < 2; ++n) _Pragma("unroll") for (int k = 0; k < 2; ++k) \
;         acc[ai][bj][m][n] = __builtin_amdgcn_mfma_f32_16x16x32_bf16(Bt[n][k], At[m][k], acc[ai][bj][m][n], 0, 0, 0); __builtin_amdgcn_s_setprio(0); } while (0)
; #define PG8_WAIT_V(n) asm volatile("s_waitcnt vmcnt(" #n ")" ::: "memory")
; #define PG8_WAIT_L(n) asm volatile("s_waitcnt lgkmcnt(" #n ")" ::: "memory")
; #define PG8_BAR __builtin_amdgcn_s_barrier()
; #define PG8_SCHED __builtin_amdgcn_sched_barrier(0)
; template <class Epi, bool ALIGN_EPI>
; __device__ __forceinline__ void gemm_phase(LAS unsigned char* lds, const Gemm g, const StaticOrder S, const Epi E) {
;     ...
;             PG8_WAIT_V(8); PG8_WAIT_L(0); PG8_BAR; PG8_MMA(1, 0, At, B0); PG8_MMA(1, 1, At, B1); PG8_BAR; PG8_SCHED;
;             PG8_LDB(B0, 1, 0); PG8_LDB(B1, 1, 1); PG8_SCHED; PG8_LDA(At, 1, 0); PG8_STAGE(PG8_SA(0, 1), a2 + hstepA, voffA);
;             PG8_WAIT_V(8); PG8_WAIT_L(0); PG8_BAR; PG8_MMA(0, 0, At, B0); PG8_MMA(0, 1, At, B1); PG8_BAR; PG8_SCHED;
	s_waitcnt lgkmcnt(0)
	v_mfma_f32_16x16x32_bf16 v[60:63], v[146:149], v[190:193], v[60:63]
	v_mfma_f32_16x16x32_bf16 v[56:59], v[158:161], v[190:193], v[56:59]
	v_mfma_f32_16x16x32_bf16 v[44:47], v[146:149], v[198:201], v[44:47]
	v_mfma_f32_16x16x32_bf16 v[40:43], v[158:161], v[198:201], v[40:43]
	v_mfma_f32_16x16x32_bf16 v[28:31], v[146:149], v[206:209], v[28:31]
	v_mfma_f32_16x16x32_bf16 v[24:27], v[158:161], v[206:209], v[24:27]
	v_mfma_f32_16x16x32_bf16 v[12:15], v[146:149], v[214:217], v[12:15]
	v_mfma_f32_16x16x32_bf16 v[8:11], v[158:161], v[214:217], v[8:11]
	v_mfma_f32_16x16x32_bf16 v[60:63], v[154:157], v[194:197], v[60:63]
	v_mfma_f32_16x16x32_bf16 v[56:59], v[162:165], v[194:197], v[56:59]
	v_mfma_f32_16x16x32_bf16 v[44:47], v[154:157], v[202:205], v[44:47]
	v_mfma_f32_16x16x32_bf16 v[40:43], v[162:165], v[202:205], v[40:43]
	v_mfma_f32_16x16x32_bf16 v[28:31], v[154:157], v[210:213], v[28:31]
	v_mfma_f32_16x16x32_bf16 v[24:27], v[162:165], v[210:213], v[24:27]
	v_mfma_f32_16x16x32_bf16 v[12:15], v[154:157], v[218:221], v[12:15]
	v_mfma_f32_16x16x32_bf16 v[8:11], v[162:165], v[218:221], v[8:11]
	v_mfma_f32_16x16x32_bf16 v[52:55], v[168:171], v[190:193], v[52:55]
	v_mfma_f32_16x16x32_bf16 v[48:51], v[182:185], v[190:193], v[48:51]
	v_mfma_f32_16x16x32_bf16 v[36:39], v[168:171], v[198:201], v[36:39]
	v_mfma_f32_16x16x32_bf16 v[32:35], v[182:185], v[198:201], v[32:35]
	v_mfma_f32_16x16x32_bf16 v[20:23], v[168:171], v[206:209], v[20:23]
	v_mfma_f32_16x16x32_bf16 v[16:19], v[182:185], v[206:209], v[16:19]
	v_mfma_f32_16x16x32_bf16 v[4:7], v[168:171], v[214:217], v[4:7]
	v_mfma_f32_16x16x32_bf16 v[0:3], v[182:185], v[214:217], v[0:3]
	v_mfma_f32_16x16x32_bf16 v[52:55], v[176:179], v[194:197], v[52:55]
	v_mfma_f32_16x16x32_bf16 v[48:51], v[186:189], v[194:197], v[48:51]
	v_mfma_f32_16x16x32_bf16 v[36:39], v[176:179], v[202:205], v[36:39]
	v_mfma_f32_16x16x32_bf16 v[32:35], v[186:189], v[202:205], v[32:35]
	v_mfma_f32_16x16x32_bf16 v[20:23], v[176:179], v[210:213], v[20:23]
	v_mfma_f32_16x16x32_bf16 v[16:19], v[186:189], v[210:213], v[16:19]
	v_mfma_f32_16x16x32_bf16 v[4:7], v[176:179], v[218:221], v[4:7]
	v_mfma_f32_16x16x32_bf16 v[0:3], v[186:189], v[218:221], v[0:3]
	s_barrier
	s_add_i32 s12, 0, 0x18000
	s_add_i32 s15, 0, 0x1c000
	v_add_u32_e32 v162, s12, v152
	v_add_u32_e32 v166, s15, v152
	ds_read_b128 v[146:149], v162
	ds_read_b128 v[154:157], v162 offset:1024
	ds_read_b128 v[158:161], v162 offset:2048
	ds_read_b128 v[162:165], v162 offset:3072
	ds_read_b128 v[168:171], v166
	ds_read_b128 v[176:179], v166 offset:1024
	ds_read_b128 v[182:185], v166 offset:2048
	ds_read_b128 v[186:189], v166 offset:3072
	s_add_u32 s0, s66, 0xb0000
	s_addc_u32 s1, s67, 0
	s_mov_b32 m0, s29
	v_lshl_add_u64 v[224:225], s[0:1], 0, v[136:137]
	ds_read_b128 v[190:193], v153 offset:32768
	ds_read_b128 v[194:197], v153 offset:33792
	ds_read_b128 v[198:201], v153 offset:34816
	ds_read_b128 v[202:205], v153 offset:35840
	ds_read_b128 v[206:209], v153 offset:36864
	ds_read_b128 v[210:213], v153 offset:37888
	ds_read_b128 v[214:217], v153 offset:38912
	ds_read_b128 v[218:221], v153 offset:39936
	global_load_lds_dwordx4 v[224:225], off
	v_lshl_add_u64 v[224:225], s[0:1], 0, v[138:139]
	s_mov_b32 m0, s30
	s_nop 0
	global_load_lds_dwordx4 v[224:225], off
	s_waitcnt vmcnt(8)
	s_waitcnt lgkmcnt(0)
	s_barrier
	s_waitcnt lgkmcnt(0)
	v_mfma_f32_16x16x32_bf16 v[126:129], v[146:149], v[190:193], v[126:129]
	v_mfma_f32_16x16x32_bf16 v[122:125], v[158:161], v[190:193], v[122:125]
	v_mfma_f32_16x16x32_bf16 v[110:113], v[146:149], v[198:201], v[110:113]
	v_mfma_f32_16x16x32_bf16 v[106:109], v[158:161], v[198:201], v[106:109]
	v_mfma_f32_16x16x32_bf16 v[94:97], v[146:149], v[206:209], v[94:97]
	v_mfma_f32_16x16x32_bf16 v[90:93], v[158:161], v[206:209], v[90:93]
	v_mfma_f32_16x16x32_bf16 v[76:79], v[146:149], v[214:217], v[76:79]
	v_mfma_f32_16x16x32_bf16 v[72:75], v[158:161], v[214:217], v[72:75]
	v_mfma_f32_16x16x32_bf16 v[126:129], v[154:157], v[194:197], v[126:129]
	v_mfma_f32_16x16x32_bf16 v[122:125], v[162:165], v[194:197], v[122:125]
	v_mfma_f32_16x16x32_bf16 v[110:113], v[154:157], v[202:205], v[110:113]
	v_mfma_f32_16x16x32_bf16 v[106:109], v[162:165], v[202:205], v[106:109]
	v_mfma_f32_16x16x32_bf16 v[94:97], v[154:157], v[210:213], v[94:97]
	v_mfma_f32_16x16x32_bf16 v[90:93], v[162:165], v[210:213], v[90:93]
	v_mfma_f32_16x16x32_bf16 v[76:79], v[154:157], v[218:221], v[76:79]
	v_mfma_f32_16x16x32_bf16 v[72:75], v[162:165], v[218:221], v[72:75]
	v_mfma_f32_16x16x32_bf16 v[118:121], v[168:171], v[190:193], v[118:121]
	v_mfma_f32_16x16x32_bf16 v[114:117], v[182:185], v[190:193], v[114:117]
	v_mfma_f32_16x16x32_bf16 v[102:105], v[168:171], v[198:201], v[102:105]
	v_mfma_f32_16x16x32_bf16 v[98:101], v[182:185], v[198:201], v[98:101]
	v_mfma_f32_16x16x32_bf16 v[86:89], v[168:171], v[206:209], v[86:89]
	v_mfma_f32_16x16x32_bf16 v[82:85], v[182:185], v[206:209], v[82:85]
	v_mfma_f32_16x16x32_bf16 v[68:71], v[168:171], v[214:217], v[68:71]
	v_mfma_f32_16x16x32_bf16 v[64:67], v[182:185], v[214:217], v[64:67]
	v_mfma_f32_16x16x32_bf16 v[118:121], v[176:179], v[194:197], v[118:121]
	v_mfma_f32_16x16x32_bf16 v[114:117], v[186:189], v[194:197], v[114:117]
	v_mfma_f32_16x16x32_bf16 v[102:105], v[176:179], v[202:205], v[102:105]
	v_mfma_f32_16x16x32_bf16 v[98:101], v[186:189], v[202:205], v[98:101]
	v_mfma_f32_16x16x32_bf16 v[86:89], v[176:179], v[210:213], v[86:89]
	v_mfma_f32_16x16x32_bf16 v[82:85], v[186:189], v[210:213], v[82:85]
	v_mfma_f32_16x16x32_bf16 v[68:71], v[176:179], v[218:221], v[68:71]
	v_mfma_f32_16x16x32_bf16 v[64:67], v[186:189], v[218:221], v[64:67]
	s_barrier
; #define PG8_STAGE(bufoff, gbase, voff) do { _Pragma("unroll") for (int _i = 0; _i < 2; ++_i) \
;         __builtin_amdgcn_global_load_lds((const unsigned*)((const char*)(gbase) + (voff)[_i]), (LAS unsigned*)(lds + (bufoff) + ldsw + _i * 8192), 16, 0, 0); } while (0)
; #define PG8_LDA(dst, b, h) do { _Pragma("unroll") for (int m = 0; m < 4; ++m) _Pragma("unroll") for (int k = 0; k < 2; ++k) dst[m][k] = *(const LAS bf16x8*)(lds + PG8_SA(b, h) + aoff + m * 2048 + k * 1024); } while (0)
; #define PG8_MMA(ai, bj, At, Bt) do { __builtin_amdgcn_s_setprio(1); _Pragma("unroll") for (int m = 0; m < 4; ++m) _Pragma("unroll") for (int n = 0; n < 2; ++n) _Pragma("unroll") for (int k = 0; k < 2; ++k) \
;         acc[ai][bj][m][n] = __builtin_amdgcn_mfma_f32_16x16x32_bf16(Bt[n][k], At[m][k], acc[ai][bj][m][n], 0, 0, 0); __builtin_amdgcn_s_setprio(0); } while (0)
; #define PG8_WAIT_V(n) asm volatile("s_waitcnt vmcnt(" #n ")" ::: "memory")
; #define PG8_WAIT_L(n) asm volatile("s_waitcnt lgkmcnt(" #n ")" ::: "memory")
; #define PG8_BAR __builtin_amdgcn_s_barrier()
; #define PG8_SCHED __builtin_amdgcn_sched_barrier(0)
; template <class Epi, bool ALIGN_EPI>
; __device__ __forceinline__ void gemm_phase(LAS unsigned char* lds, const Gemm g, const StaticOrder S, const Epi E) {
;     ...
;             PG8_LDA(At, 1, 1); PG8_STAGE(PG8_SB(1, 0), b3, voffB); PG8_STAGE(PG8_SB(1, 1), b3 + hstepB, voffB); PG8_STAGE(PG8_SA(1, 0), a3, voffA);
;             PG8_WAIT_V(8); PG8_WAIT_L(0); PG8_BAR; PG8_MMA(1, 0, At, B0); PG8_MMA(1, 1, At, B1); PG8_BAR; PG8_SCHED;
;         }
;         if constexpr (ALIGN_EPI) { if (wr == 0) PG8_BAR; }
	s_add_i32 s0, s12, s26
	v_lshl_add_u64 v[130:131], v[130:131], 0, s[80:81]
	s_mov_b32 m0, s0
	ds_read_b128 v[190:193], v153 offset:49152
	ds_read_b128 v[194:197], v153 offset:50176
	ds_read_b128 v[198:201], v153 offset:51200
	ds_read_b128 v[202:205], v153 offset:52224
	ds_read_b128 v[206:209], v153 offset:53248
	ds_read_b128 v[210:213], v153 offset:54272
	ds_read_b128 v[214:217], v153 offset:55296
	ds_read_b128 v[218:221], v153 offset:56320
	global_load_lds_dwordx4 v[130:131], off
	s_add_i32 m0, s0, 0x2000
	s_add_u32 s0, s64, 0x40080
	v_lshl_add_u64 v[130:131], v[134:135], 0, s[80:81]
	s_addc_u32 s1, s65, 0
	s_add_i32 s12, s15, s26
	global_load_lds_dwordx4 v[130:131], off
	v_lshl_add_u64 v[130:131], s[0:1], 0, v[80:81]
	s_mov_b32 m0, s12
	s_nop 0
	global_load_lds_dwordx4 v[130:131], off
	v_lshl_add_u64 v[130:131], s[0:1], 0, v[140:141]
	s_add_i32 m0, s12, 0x2000
	s_nop 0
	global_load_lds_dwordx4 v[130:131], off
	v_lshl_add_u64 v[130:131], v[172:173], 0, s[80:81]
	s_mov_b32 m0, s61
	s_nop 0
	global_load_lds_dwordx4 v[130:131], off
	v_lshl_add_u64 v[130:131], v[222:223], 0, s[80:81]
	s_mov_b32 m0, s68
	s_nop 0
	global_load_lds_dwordx4 v[130:131], off
	s_waitcnt vmcnt(8)
	s_waitcnt lgkmcnt(0)
	s_barrier
	s_waitcnt lgkmcnt(0)
	v_mfma_f32_16x16x32_bf16 v[60:63], v[146:149], v[190:193], v[60:63]
	v_mfma_f32_16x16x32_bf16 v[56:59], v[158:161], v[190:193], v[56:59]
	v_mfma_f32_16x16x32_bf16 v[44:47], v[146:149], v[198:201], v[44:47]
	v_mfma_f32_16x16x32_bf16 v[40:43], v[158:161], v[198:201], v[40:43]
	v_mfma_f32_16x16x32_bf16 v[28:31], v[146:149], v[206:209], v[28:31]
	v_mfma_f32_16x16x32_bf16 v[24:27], v[158:161], v[206:209], v[24:27]
	v_mfma_f32_16x16x32_bf16 v[12:15], v[146:149], v[214:217], v[12:15]
	v_mfma_f32_16x16x32_bf16 v[8:11], v[158:161], v[214:217], v[8:11]
	v_mfma_f32_16x16x32_bf16 v[60:63], v[154:157], v[194:197], v[60:63]
	v_mfma_f32_16x16x32_bf16 v[56:59], v[162:165], v[194:197], v[56:59]
	v_mfma_f32_16x16x32_bf16 v[44:47], v[154:157], v[202:205], v[44:47]
	v_mfma_f32_16x16x32_bf16 v[40:43], v[162:165], v[202:205], v[40:43]
	v_mfma_f32_16x16x32_bf16 v[28:31], v[154:157], v[210:213], v[28:31]
	v_mfma_f32_16x16x32_bf16 v[24:27], v[162:165], v[210:213], v[24:27]
	v_mfma_f32_16x16x32_bf16 v[12:15], v[154:157], v[218:221], v[12:15]
	v_mfma_f32_16x16x32_bf16 v[8:11], v[162:165], v[218:221], v[8:11]
	v_mfma_f32_16x16x32_bf16 v[52:55], v[168:171], v[190:193], v[52:55]
	v_mfma_f32_16x16x32_bf16 v[48:51], v[182:185], v[190:193], v[48:51]
	v_mfma_f32_16x16x32_bf16 v[36:39], v[168:171], v[198:201], v[36:39]
	v_mfma_f32_16x16x32_bf16 v[32:35], v[182:185], v[198:201], v[32:35]
	v_mfma_f32_16x16x32_bf16 v[20:23], v[168:171], v[206:209], v[20:23]
	v_mfma_f32_16x16x32_bf16 v[16:19], v[182:185], v[206:209], v[16:19]
	v_mfma_f32_16x16x32_bf16 v[4:7], v[168:171], v[214:217], v[4:7]
	v_mfma_f32_16x16x32_bf16 v[0:3], v[182:185], v[214:217], v[0:3]
	v_mfma_f32_16x16x32_bf16 v[52:55], v[176:179], v[194:197], v[52:55]
	v_mfma_f32_16x16x32_bf16 v[48:51], v[186:189], v[194:197], v[48:51]
	v_mfma_f32_16x16x32_bf16 v[36:39], v[176:179], v[202:205], v[36:39]
	v_mfma_f32_16x16x32_bf16 v[32:35], v[186:189], v[202:205], v[32:35]
	v_mfma_f32_16x16x32_bf16 v[20:23], v[176:179], v[210:213], v[20:23]
	v_mfma_f32_16x16x32_bf16 v[16:19], v[186:189], v[210:213], v[16:19]
	v_mfma_f32_16x16x32_bf16 v[4:7], v[176:179], v[218:221], v[4:7]
	v_mfma_f32_16x16x32_bf16 v[0:3], v[186:189], v[218:221], v[0:3]
	s_barrier
	s_add_i32 s71, s71, 2
	s_add_u32 s49, s49, 0x100
	s_addc_u32 s55, s55, 0
	s_cmp_gt_u32 s71, 13
	s_mov_b64 s[62:63], s[44:45]
	s_cbranch_scc0 .LBB0_1431
	s_and_b64 vcc, exec, s[46:47]
	s_cbranch_vccz .LBB0_1434
	s_barrier

; #define PG8_STAGE(bufoff, gbase, voff) do { _Pragma("unroll") for (int _i = 0; _i < 2; ++_i) \
;         __builtin_amdgcn_global_load_lds((const unsigned*)((const char*)(gbase) + (voff)[_i]), (LAS unsigned*)(lds + (bufoff) + ldsw + _i * 8192), 16, 0, 0); } while (0)
; #define PG8_LDA(dst, b, h) do { _Pragma("unroll") for (int m = 0; m < 4; ++m) _Pragma("unroll") for (int k = 0; k < 2; ++k) dst[m][k] = *(const LAS bf16x8*)(lds + PG8_SA(b, h) + aoff + m * 2048 + k * 1024); } while (0)
; #define PG8_LDB(dst, b, h) do { _Pragma("unroll") for (int n = 0; n < 2; ++n) _Pragma("unroll") for (int k = 0; k < 2; ++k) dst[n][k] = *(const LAS bf16x8*)(lds + PG8_SB(b, h) + boff + n * 2048 + k * 1024); } while (0)
; #define PG8_MMA(ai, bj, At, Bt) do { __builtin_amdgcn_s_setprio(1); _Pragma("unroll") for (int m = 0; m < 4; ++m) _Pragma("unroll") for (int n = 0; n < 2; ++n) _Pragma("unroll") for (int k = 0; k < 2; ++k) \
;         acc[ai][bj][m][n] = __builtin_amdgcn_mfma_f32_16x16x32_bf16(Bt[n][k], At[m][k], acc[ai][bj][m][n], 0, 0, 0); __builtin_amdgcn_s_setprio(0); } while (0)
; #define PG8_WAIT_V(n) asm volatile("s_waitcnt vmcnt(" #n ")" ::: "memory")
; #define PG8_WAIT_L(n) asm volatile("s_waitcnt lgkmcnt(" #n ")" ::: "memory")
; #define PG8_BAR __builtin_amdgcn_s_barrier()
; #define PG8_SCHED __builtin_amdgcn_sched_barrier(0)
; template <class Epi, bool ALIGN_EPI>
; __device__ __forceinline__ void gemm_phase(LAS unsigned char* lds, const Gemm g, const StaticOrder S, const Epi E) {
;     ...
;             const bool last = (t == nt - 2);
;             const char* a1 = cA + (size_t)(t + 1) * kstep;
;             const char* a2 = last ? nA : cA + (size_t)(t + 2) * kstep; const char* b2 = last ? nB : cB + (size_t)(t + 2) * kstep;
;             const char* a3 = a2 + kstep; const char* b3 = b2 + kstep;
;             PG8_LDB(B0, 0, 0); PG8_LDB(B1, 0, 1); PG8_SCHED; PG8_LDA(At, 0, 0); PG8_STAGE(PG8_SA(1, 1), a1 + hstepA, voffA);
;             PG8_WAIT_V(8); PG8_WAIT_L(0); PG8_BAR; PG8_MMA(0, 0, At, B0); PG8_MMA(0, 1, At, B1); PG8_BAR; PG8_SCHED;
;             PG8_LDA(At, 0, 1); PG8_STAGE(PG8_SB(0, 0), b2, voffB); PG8_STAGE(PG8_SB(0, 1), b2 + hstepB, voffB); PG8_STAGE(PG8_SA(0, 0), a2, voffA);
;             PG8_WAIT_V(8); PG8_WAIT_L(0); PG8_BAR; PG8_MMA(1, 0, At, B0); PG8_MMA(1, 1, At, B1); PG8_BAR; PG8_SCHED;
.LBB0_1555:
	s_add_u32 s0, s2, 0xfffc0080
	s_addc_u32 s1, s3, -1
	s_add_i32 s12, 0, 0x10000
	s_cmp_eq_u32 s68, 12
	s_cselect_b32 s65, s34, s1
	s_cselect_b32 s64, s35, s0
	v_add_u32_e32 v130, s12, v163
	s_cselect_b32 s43, s49, s67
	s_cselect_b32 s42, s51, s66
	s_add_i32 s15, 0, 0x14000
	ds_read_b128 v[182:185], v130
	ds_read_b128 v[186:189], v130 offset:1024
	ds_read_b128 v[190:193], v130 offset:2048
	ds_read_b128 v[194:197], v130 offset:3072
	v_add_u32_e32 v130, s15, v163
	ds_read_b128 v[198:201], v130
	ds_read_b128 v[202:205], v130 offset:1024
	ds_read_b128 v[206:209], v130 offset:2048
	ds_read_b128 v[210:213], v130 offset:3072
	v_lshl_add_u64 v[172:173], s[2:3], 0, v[152:153]
	s_add_i32 m0, s24, 0xc000
	ds_read_b128 v[214:217], v165
	ds_read_b128 v[218:221], v165 offset:1024
	ds_read_b128 v[222:225], v165 offset:2048
	ds_read_b128 v[226:229], v165 offset:3072
	ds_read_b128 v[230:233], v165 offset:4096
	ds_read_b128 v[234:237], v165 offset:5120
	ds_read_b128 v[238:241], v165 offset:6144
	ds_read_b128 v[242:245], v165 offset:7168
	global_load_lds_dwordx4 v[172:173], off
	v_lshl_add_u64 v[172:173], s[2:3], 0, v[154:155]
	s_add_i32 m0, s24, 0xe000
	s_nop 0
	global_load_lds_dwordx4 v[172:173], off
	s_waitcnt vmcnt(8)
	s_waitcnt lgkmcnt(0)
	s_barrier
	s_waitcnt lgkmcnt(0)
	v_mfma_f32_16x16x32_bf16 v[126:129], v[182:185], v[214:217], v[126:129]
	v_mfma_f32_16x16x32_bf16 v[122:125], v[190:193], v[214:217], v[122:125]
	v_mfma_f32_16x16x32_bf16 v[114:117], v[182:185], v[222:225], v[114:117]
	v_mfma_f32_16x16x32_bf16 v[106:109], v[190:193], v[222:225], v[106:109]
	v_mfma_f32_16x16x32_bf16 v[98:101], v[182:185], v[230:233], v[98:101]
	v_mfma_f32_16x16x32_bf16 v[90:93], v[190:193], v[230:233], v[90:93]
	v_mfma_f32_16x16x32_bf16 v[82:85], v[182:185], v[238:241], v[82:85]
	v_mfma_f32_16x16x32_bf16 v[72:75], v[190:193], v[238:241], v[72:75]
	v_mfma_f32_16x16x32_bf16 v[126:129], v[186:189], v[218:221], v[126:129]
	v_mfma_f32_16x16x32_bf16 v[122:125], v[194:197], v[218:221], v[122:125]
	v_mfma_f32_16x16x32_bf16 v[114:117], v[186:189], v[226:229], v[114:117]
	v_mfma_f32_16x16x32_bf16 v[106:109], v[194:197], v[226:229], v[106:109]
	v_mfma_f32_16x16x32_bf16 v[98:101], v[186:189], v[234:237], v[98:101]
	v_mfma_f32_16x16x32_bf16 v[90:93], v[194:197], v[234:237], v[90:93]
	v_mfma_f32_16x16x32_bf16 v[82:85], v[186:189], v[242:245], v[82:85]
	v_mfma_f32_16x16x32_bf16 v[72:75], v[194:197], v[242:245], v[72:75]
	v_mfma_f32_16x16x32_bf16 v[118:121], v[198:201], v[214:217], v[118:121]
	v_mfma_f32_16x16x32_bf16 v[110:113], v[206:209], v[214:217], v[110:113]
	v_mfma_f32_16x16x32_bf16 v[102:105], v[198:201], v[222:225], v[102:105]
	v_mfma_f32_16x16x32_bf16 v[94:97], v[206:209], v[222:225], v[94:97]
	v_mfma_f32_16x16x32_bf16 v[86:89], v[198:201], v[230:233], v[86:89]
	v_mfma_f32_16x16x32_bf16 v[76:79], v[206:209], v[230:233], v[76:79]
	v_mfma_f32_16x16x32_bf16 v[68:71], v[198:201], v[238:241], v[68:71]
	v_mfma_f32_16x16x32_bf16 v[64:67], v[206:209], v[238:241], v[64:67]
	v_mfma_f32_16x16x32_bf16 v[118:121], v[202:205], v[218:221], v[118:121]
	v_mfma_f32_16x16x32_bf16 v[110:113], v[210:213], v[218:221], v[110:113]
	v_mfma_f32_16x16x32_bf16 v[102:105], v[202:205], v[226:229], v[102:105]
	v_mfma_f32_16x16x32_bf16 v[94:97], v[210:213], v[226:229], v[94:97]
	v_mfma_f32_16x16x32_bf16 v[86:89], v[202:205], v[234:237], v[86:89]
	v_mfma_f32_16x16x32_bf16 v[76:79], v[210:213], v[234:237], v[76:79]
	v_mfma_f32_16x16x32_bf16 v[68:71], v[202:205], v[242:245], v[68:71]
	v_mfma_f32_16x16x32_bf16 v[64:67], v[210:213], v[242:245], v[64:67]
	s_barrier
	s_add_i32 s0, s12, s23
	v_lshl_add_u64 v[172:173], s[42:43], 0, v[80:81]
	s_mov_b32 m0, s0
	ds_read_b128 v[214:217], v165 offset:16384
	ds_read_b128 v[218:221], v165 offset:17408
	ds_read_b128 v[222:225], v165 offset:18432
	ds_read_b128 v[226:229], v165 offset:19456
	ds_read_b128 v[230:233], v165 offset:20480
	ds_read_b128 v[234:237], v165 offset:21504
	ds_read_b128 v[238:241], v165 offset:22528
	ds_read_b128 v[242:245], v165 offset:23552
	global_load_lds_dwordx4 v[172:173], off
	s_add_i32 m0, s0, 0x2000
	s_add_u32 s0, s42, 0x40000
	v_lshl_add_u64 v[176:177], s[42:43], 0, v[136:137]
	s_addc_u32 s1, s43, 0
	s_add_i32 s12, s15, s23
	global_load_lds_dwordx4 v[176:177], off
	v_lshl_add_u64 v[178:179], s[0:1], 0, v[80:81]
	s_mov_b32 m0, s12
	v_lshl_add_u64 v[246:247], s[64:65], 0, v[138:139]
	global_load_lds_dwordx4 v[178:179], off
	v_lshl_add_u64 v[178:179], s[0:1], 0, v[136:137]
	s_add_i32 m0, s12, 0x2000
	s_nop 0
	global_load_lds_dwordx4 v[178:179], off
	v_lshl_add_u64 v[178:179], s[64:65], 0, v[140:141]
	s_mov_b32 m0, s24
	s_nop 0
	global_load_lds_dwordx4 v[178:179], off
	s_mov_b32 m0, s25
	s_nop 0
	global_load_lds_dwordx4 v[246:247], off
	s_waitcnt vmcnt(8)
	s_waitcnt lgkmcnt(0)
	s_barrier
; #define PG8_STAGE(bufoff, gbase, voff) do { _Pragma("unroll") for (int _i = 0; _i < 2; ++_i) \
;         __builtin_amdgcn_global_load_lds((const unsigned*)((const char*)(gbase) + (voff)[_i]), (LAS unsigned*)(lds + (bufoff) + ldsw + _i * 8192), 16, 0, 0); } while (0)
; #define PG8_LDA(dst, b, h) do { _Pragma("unroll") for (int m = 0; m < 4; ++m) _Pragma("unroll") for (int k = 0; k < 2; ++k) dst[m][k] = *(const LAS bf16x8*)(lds + PG8_SA(b, h) + aoff + m * 2048 + k * 1024); } while (0)
; #define PG8_LDB(dst, b, h) do { _Pragma("unroll") for (int n = 0; n < 2; ++n) _Pragma("unroll") for (int k = 0; k < 2; ++k) dst[n][k] = *(const LAS bf16x8*)(lds + PG8_SB(b, h) + boff + n * 2048 + k * 1024); } while (0)
; #define PG8_MMA(ai, bj, At, Bt) do { __builtin_amdgcn_s_setprio(1); _Pragma("unroll") for (int m = 0; m < 4; ++m) _Pragma("unroll") for (int n = 0; n < 2; ++n) _Pragma("unroll") for (int k = 0; k < 2; ++k) \
;         acc[ai][bj][m][n] = __builtin_amdgcn_mfma_f32_16x16x32_bf16(Bt[n][k], At[m][k], acc[ai][bj][m][n], 0, 0, 0); __builtin_amdgcn_s_setprio(0); } while (0)
; #define PG8_WAIT_V(n) asm volatile("s_waitcnt vmcnt(" #n ")" ::: "memory")
; #define PG8_WAIT_L(n) asm volatile("s_waitcnt lgkmcnt(" #n ")" ::: "memory")
; #define PG8_BAR __builtin_amdgcn_s_barrier()
; #define PG8_SCHED __builtin_amdgcn_sched_barrier(0)
; template <class Epi, bool ALIGN_EPI>
; __device__ __forceinline__ void gemm_phase(LAS unsigned char* lds, const Gemm g, const StaticOrder S, const Epi E) {
;     ...
;             PG8_WAIT_V(8); PG8_WAIT_L(0); PG8_BAR; PG8_MMA(1, 0, At, B0); PG8_MMA(1, 1, At, B1); PG8_BAR; PG8_SCHED;
;             PG8_LDB(B0, 1, 0); PG8_LDB(B1, 1, 1); PG8_SCHED; PG8_LDA(At, 1, 0); PG8_STAGE(PG8_SA(0, 1), a2 + hstepA, voffA);
;             PG8_WAIT_V(8); PG8_WAIT_L(0); PG8_BAR; PG8_MMA(0, 0, At, B0); PG8_MMA(0, 1, At, B1); PG8_BAR; PG8_SCHED;
	s_waitcnt lgkmcnt(0)
	v_mfma_f32_16x16x32_bf16 v[60:63], v[182:185], v[214:217], v[60:63]
	v_mfma_f32_16x16x32_bf16 v[56:59], v[190:193], v[214:217], v[56:59]
	v_mfma_f32_16x16x32_bf16 v[48:51], v[182:185], v[222:225], v[48:51]
	v_mfma_f32_16x16x32_bf16 v[40:43], v[190:193], v[222:225], v[40:43]
	v_mfma_f32_16x16x32_bf16 v[32:35], v[182:185], v[230:233], v[32:35]
	v_mfma_f32_16x16x32_bf16 v[24:27], v[190:193], v[230:233], v[24:27]
	v_mfma_f32_16x16x32_bf16 v[16:19], v[182:185], v[238:241], v[16:19]
	v_mfma_f32_16x16x32_bf16 v[8:11], v[190:193], v[238:241], v[8:11]
	v_mfma_f32_16x16x32_bf16 v[60:63], v[186:189], v[218:221], v[60:63]
	v_mfma_f32_16x16x32_bf16 v[56:59], v[194:197], v[218:221], v[56:59]
	v_mfma_f32_16x16x32_bf16 v[48:51], v[186:189], v[226:229], v[48:51]
	v_mfma_f32_16x16x32_bf16 v[40:43], v[194:197], v[226:229], v[40:43]
	v_mfma_f32_16x16x32_bf16 v[32:35], v[186:189], v[234:237], v[32:35]
	v_mfma_f32_16x16x32_bf16 v[24:27], v[194:197], v[234:237], v[24:27]
	v_mfma_f32_16x16x32_bf16 v[16:19], v[186:189], v[242:245], v[16:19]
	v_mfma_f32_16x16x32_bf16 v[8:11], v[194:197], v[242:245], v[8:11]
	v_mfma_f32_16x16x32_bf16 v[52:55], v[198:201], v[214:217], v[52:55]
	v_mfma_f32_16x16x32_bf16 v[44:47], v[206:209], v[214:217], v[44:47]
	v_mfma_f32_16x16x32_bf16 v[36:39], v[198:201], v[222:225], v[36:39]
	v_mfma_f32_16x16x32_bf16 v[28:31], v[206:209], v[222:225], v[28:31]
	v_mfma_f32_16x16x32_bf16 v[20:23], v[198:201], v[230:233], v[20:23]
	v_mfma_f32_16x16x32_bf16 v[12:15], v[206:209], v[230:233], v[12:15]
	v_mfma_f32_16x16x32_bf16 v[4:7], v[198:201], v[238:241], v[4:7]
	v_mfma_f32_16x16x32_bf16 v[0:3], v[206:209], v[238:241], v[0:3]
	v_mfma_f32_16x16x32_bf16 v[52:55], v[202:205], v[218:221], v[52:55]
	v_mfma_f32_16x16x32_bf16 v[44:47], v[210:213], v[218:221], v[44:47]
	v_mfma_f32_16x16x32_bf16 v[36:39], v[202:205], v[226:229], v[36:39]
	v_mfma_f32_16x16x32_bf16 v[28:31], v[210:213], v[226:229], v[28:31]
	v_mfma_f32_16x16x32_bf16 v[20:23], v[202:205], v[234:237], v[20:23]
	v_mfma_f32_16x16x32_bf16 v[12:15], v[210:213], v[234:237], v[12:15]
	v_mfma_f32_16x16x32_bf16 v[4:7], v[202:205], v[242:245], v[4:7]
	v_mfma_f32_16x16x32_bf16 v[0:3], v[210:213], v[242:245], v[0:3]
	s_barrier
	s_add_i32 s12, 0, 0x18000
	v_add_u32_e32 v130, s12, v163
	s_add_i32 s15, 0, 0x1c000
	ds_read_b128 v[182:185], v130
	ds_read_b128 v[186:189], v130 offset:1024
	ds_read_b128 v[190:193], v130 offset:2048
	ds_read_b128 v[194:197], v130 offset:3072
	v_add_u32_e32 v130, s15, v163
	ds_read_b128 v[198:201], v130
	ds_read_b128 v[202:205], v130 offset:1024
	ds_read_b128 v[206:209], v130 offset:2048
	ds_read_b128 v[210:213], v130 offset:3072
	s_add_u32 s0, s64, 0x40000
	s_addc_u32 s1, s65, 0
	s_mov_b32 m0, s26
	v_lshl_add_u64 v[248:249], s[0:1], 0, v[140:141]
	ds_read_b128 v[214:217], v165 offset:32768
	ds_read_b128 v[218:221], v165 offset:33792
	ds_read_b128 v[222:225], v165 offset:34816
	ds_read_b128 v[226:229], v165 offset:35840
	ds_read_b128 v[230:233], v165 offset:36864
	ds_read_b128 v[234:237], v165 offset:37888
	ds_read_b128 v[238:241], v165 offset:38912
	ds_read_b128 v[242:245], v165 offset:39936
	global_load_lds_dwordx4 v[248:249], off
	v_lshl_add_u64 v[248:249], s[0:1], 0, v[138:139]
	s_mov_b32 m0, s27
	s_nop 0
	global_load_lds_dwordx4 v[248:249], off
	s_waitcnt vmcnt(8)
	s_waitcnt lgkmcnt(0)
	s_barrier
	s_waitcnt lgkmcnt(0)
	v_mfma_f32_16x16x32_bf16 v[126:129], v[182:185], v[214:217], v[126:129]
	v_mfma_f32_16x16x32_bf16 v[122:125], v[190:193], v[214:217], v[122:125]
	v_mfma_f32_16x16x32_bf16 v[114:117], v[182:185], v[222:225], v[114:117]
	v_mfma_f32_16x16x32_bf16 v[106:109], v[190:193], v[222:225], v[106:109]
	v_mfma_f32_16x16x32_bf16 v[98:101], v[182:185], v[230:233], v[98:101]
	v_mfma_f32_16x16x32_bf16 v[90:93], v[190:193], v[230:233], v[90:93]
	v_mfma_f32_16x16x32_bf16 v[82:85], v[182:185], v[238:241], v[82:85]
	v_mfma_f32_16x16x32_bf16 v[72:75], v[190:193], v[238:241], v[72:75]
	v_mfma_f32_16x16x32_bf16 v[126:129], v[186:189], v[218:221], v[126:129]
	v_mfma_f32_16x16x32_bf16 v[122:125], v[194:197], v[218:221], v[122:125]
	v_mfma_f32_16x16x32_bf16 v[114:117], v[186:189], v[226:229], v[114:117]
	v_mfma_f32_16x16x32_bf16 v[106:109], v[194:197], v[226:229], v[106:109]
	v_mfma_f32_16x16x32_bf16 v[98:101], v[186:189], v[234:237], v[98:101]
	v_mfma_f32_16x16x32_bf16 v[90:93], v[194:197], v[234:237], v[90:93]
	v_mfma_f32_16x16x32_bf16 v[82:85], v[186:189], v[242:245], v[82:85]
	v_mfma_f32_16x16x32_bf16 v[72:75], v[194:197], v[242:245], v[72:75]
	v_mfma_f32_16x16x32_bf16 v[118:121], v[198:201], v[214:217], v[118:121]
	v_mfma_f32_16x16x32_bf16 v[110:113], v[206:209], v[214:217], v[110:113]
	v_mfma_f32_16x16x32_bf16 v[102:105], v[198:201], v[222:225], v[102:105]
	v_mfma_f32_16x16x32_bf16 v[94:97], v[206:209], v[222:225], v[94:97]
	v_mfma_f32_16x16x32_bf16 v[86:89], v[198:201], v[230:233], v[86:89]
	v_mfma_f32_16x16x32_bf16 v[76:79], v[206:209], v[230:233], v[76:79]
	v_mfma_f32_16x16x32_bf16 v[68:71], v[198:201], v[238:241], v[68:71]
	v_mfma_f32_16x16x32_bf16 v[64:67], v[206:209], v[238:241], v[64:67]
	v_mfma_f32_16x16x32_bf16 v[118:121], v[202:205], v[218:221], v[118:121]
	v_mfma_f32_16x16x32_bf16 v[110:113], v[210:213], v[218:221], v[110:113]
	v_mfma_f32_16x16x32_bf16 v[102:105], v[202:205], v[226:229], v[102:105]
	v_mfma_f32_16x16x32_bf16 v[94:97], v[210:213], v[226:229], v[94:97]
	v_mfma_f32_16x16x32_bf16 v[86:89], v[202:205], v[234:237], v[86:89]
	v_mfma_f32_16x16x32_bf16 v[76:79], v[210:213], v[234:237], v[76:79]
	v_mfma_f32_16x16x32_bf16 v[68:71], v[202:205], v[242:245], v[68:71]
	v_mfma_f32_16x16x32_bf16 v[64:67], v[210:213], v[242:245], v[64:67]
	s_barrier
; #define PG8_STAGE(bufoff, gbase, voff) do { _Pragma("unroll") for (int _i = 0; _i < 2; ++_i) \
;         __builtin_amdgcn_global_load_lds((const unsigned*)((const char*)(gbase) + (voff)[_i]), (LAS unsigned*)(lds + (bufoff) + ldsw + _i * 8192), 16, 0, 0); } while (0)
; #define PG8_LDA(dst, b, h) do { _Pragma("unroll") for (int m = 0; m < 4; ++m) _Pragma("unroll") for (int k = 0; k < 2; ++k) dst[m][k] = *(const LAS bf16x8*)(lds + PG8_SA(b, h) + aoff + m * 2048 + k * 1024); } while (0)
; #define PG8_MMA(ai, bj, At, Bt) do { __builtin_amdgcn_s_setprio(1); _Pragma("unroll") for (int m = 0; m < 4; ++m) _Pragma("unroll") for (int n = 0; n < 2; ++n) _Pragma("unroll") for (int k = 0; k < 2; ++k) \
;         acc[ai][bj][m][n] = __builtin_amdgcn_mfma_f32_16x16x32_bf16(Bt[n][k], At[m][k], acc[ai][bj][m][n], 0, 0, 0); __builtin_amdgcn_s_setprio(0); } while (0)
; #define PG8_WAIT_V(n) asm volatile("s_waitcnt vmcnt(" #n ")" ::: "memory")
; #define PG8_WAIT_L(n) asm volatile("s_waitcnt lgkmcnt(" #n ")" ::: "memory")
; #define PG8_BAR __builtin_amdgcn_s_barrier()
; #define PG8_SCHED __builtin_amdgcn_sched_barrier(0)
; template <class Epi, bool ALIGN_EPI>
; __device__ __forceinline__ void gemm_phase(LAS unsigned char* lds, const Gemm g, const StaticOrder S, const Epi E) {
;     ...
;             PG8_LDA(At, 1, 1); PG8_STAGE(PG8_SB(1, 0), b3, voffB); PG8_STAGE(PG8_SB(1, 1), b3 + hstepB, voffB); PG8_STAGE(PG8_SA(1, 0), a3, voffA);
;             PG8_WAIT_V(8); PG8_WAIT_L(0); PG8_BAR; PG8_MMA(1, 0, At, B0); PG8_MMA(1, 1, At, B1); PG8_BAR; PG8_SCHED;
;         }
;         if constexpr (ALIGN_EPI) { if (wr == 0) PG8_BAR; }
	s_add_i32 s0, s12, s23
	v_lshl_add_u64 v[172:173], v[172:173], 0, s[80:81]
	s_mov_b32 m0, s0
	ds_read_b128 v[214:217], v165 offset:49152
	ds_read_b128 v[218:221], v165 offset:50176
	ds_read_b128 v[222:225], v165 offset:51200
	ds_read_b128 v[226:229], v165 offset:52224
	ds_read_b128 v[230:233], v165 offset:53248
	ds_read_b128 v[234:237], v165 offset:54272
	ds_read_b128 v[238:241], v165 offset:55296
	ds_read_b128 v[242:245], v165 offset:56320
	global_load_lds_dwordx4 v[172:173], off
	s_add_i32 m0, s0, 0x2000
	s_add_u32 s0, s42, 0x40080
	v_lshl_add_u64 v[172:173], v[176:177], 0, s[80:81]
	s_addc_u32 s1, s43, 0
	s_add_i32 s12, s15, s23
	global_load_lds_dwordx4 v[172:173], off
	v_lshl_add_u64 v[172:173], s[0:1], 0, v[80:81]
	s_mov_b32 m0, s12
	s_nop 0
	global_load_lds_dwordx4 v[172:173], off
	v_lshl_add_u64 v[172:173], s[0:1], 0, v[136:137]
	s_add_i32 m0, s12, 0x2000
	s_nop 0
	global_load_lds_dwordx4 v[172:173], off
	v_lshl_add_u64 v[172:173], v[178:179], 0, s[80:81]
	s_mov_b32 m0, s29
	s_nop 0
	global_load_lds_dwordx4 v[172:173], off
	v_lshl_add_u64 v[172:173], v[246:247], 0, s[80:81]
	s_mov_b32 m0, s30
	s_nop 0
	global_load_lds_dwordx4 v[172:173], off
	s_waitcnt vmcnt(8)
	s_waitcnt lgkmcnt(0)
	s_barrier
	s_waitcnt lgkmcnt(0)
	v_mfma_f32_16x16x32_bf16 v[60:63], v[182:185], v[214:217], v[60:63]
	v_mfma_f32_16x16x32_bf16 v[56:59], v[190:193], v[214:217], v[56:59]
	v_mfma_f32_16x16x32_bf16 v[48:51], v[182:185], v[222:225], v[48:51]
	v_mfma_f32_16x16x32_bf16 v[40:43], v[190:193], v[222:225], v[40:43]
	v_mfma_f32_16x16x32_bf16 v[32:35], v[182:185], v[230:233], v[32:35]
	v_mfma_f32_16x16x32_bf16 v[24:27], v[190:193], v[230:233], v[24:27]
	v_mfma_f32_16x16x32_bf16 v[16:19], v[182:185], v[238:241], v[16:19]
	v_mfma_f32_16x16x32_bf16 v[8:11], v[190:193], v[238:241], v[8:11]
	v_mfma_f32_16x16x32_bf16 v[60:63], v[186:189], v[218:221], v[60:63]
	v_mfma_f32_16x16x32_bf16 v[56:59], v[194:197], v[218:221], v[56:59]
	v_mfma_f32_16x16x32_bf16 v[48:51], v[186:189], v[226:229], v[48:51]
	v_mfma_f32_16x16x32_bf16 v[40:43], v[194:197], v[226:229], v[40:43]
	v_mfma_f32_16x16x32_bf16 v[32:35], v[186:189], v[234:237], v[32:35]
	v_mfma_f32_16x16x32_bf16 v[24:27], v[194:197], v[234:237], v[24:27]
	v_mfma_f32_16x16x32_bf16 v[16:19], v[186:189], v[242:245], v[16:19]
	v_mfma_f32_16x16x32_bf16 v[8:11], v[194:197], v[242:245], v[8:11]
	v_mfma_f32_16x16x32_bf16 v[52:55], v[198:201], v[214:217], v[52:55]
	v_mfma_f32_16x16x32_bf16 v[44:47], v[206:209], v[214:217], v[44:47]
	v_mfma_f32_16x16x32_bf16 v[36:39], v[198:201], v[222:225], v[36:39]
	v_mfma_f32_16x16x32_bf16 v[28:31], v[206:209], v[222:225], v[28:31]
	v_mfma_f32_16x16x32_bf16 v[20:23], v[198:201], v[230:233], v[20:23]
	v_mfma_f32_16x16x32_bf16 v[12:15], v[206:209], v[230:233], v[12:15]
	v_mfma_f32_16x16x32_bf16 v[4:7], v[198:201], v[238:241], v[4:7]
	v_mfma_f32_16x16x32_bf16 v[0:3], v[206:209], v[238:241], v[0:3]
	v_mfma_f32_16x16x32_bf16 v[52:55], v[202:205], v[218:221], v[52:55]
	v_mfma_f32_16x16x32_bf16 v[44:47], v[210:213], v[218:221], v[44:47]
	v_mfma_f32_16x16x32_bf16 v[36:39], v[202:205], v[226:229], v[36:39]
	v_mfma_f32_16x16x32_bf16 v[28:31], v[210:213], v[226:229], v[28:31]
	v_mfma_f32_16x16x32_bf16 v[20:23], v[202:205], v[234:237], v[20:23]
	v_mfma_f32_16x16x32_bf16 v[12:15], v[210:213], v[234:237], v[12:15]
	v_mfma_f32_16x16x32_bf16 v[4:7], v[202:205], v[242:245], v[4:7]
	v_mfma_f32_16x16x32_bf16 v[0:3], v[210:213], v[242:245], v[0:3]
	s_barrier
	s_add_i32 s68, s68, 2
	s_add_u32 s2, s2, 0x100
	s_addc_u32 s3, s3, 0
	s_add_u32 s66, s66, 0x100
	s_addc_u32 s67, s67, 0
	s_cmp_gt_u32 s68, 13
	s_cbranch_scc0 .LBB0_1555
	s_and_b64 vcc, exec, s[46:47]
	s_cbranch_vccz .LBB0_1558
	s_barrier

; #define PG8_STAGE(bufoff, gbase, voff) do { _Pragma("unroll") for (int _i = 0; _i < 2; ++_i) \
;         __builtin_amdgcn_global_load_lds((const unsigned*)((const char*)(gbase) + (voff)[_i]), (LAS unsigned*)(lds + (bufoff) + ldsw + _i * 8192), 16, 0, 0); } while (0)
; #define PG8_LDA(dst, b, h) do { _Pragma("unroll") for (int m = 0; m < 4; ++m) _Pragma("unroll") for (int k = 0; k < 2; ++k) dst[m][k] = *(const LAS bf16x8*)(lds + PG8_SA(b, h) + aoff + m * 2048 + k * 1024); } while (0)
; #define PG8_LDB(dst, b, h) do { _Pragma("unroll") for (int n = 0; n < 2; ++n) _Pragma("unroll") for (int k = 0; k < 2; ++k) dst[n][k] = *(const LAS bf16x8*)(lds + PG8_SB(b, h) + boff + n * 2048 + k * 1024); } while (0)
; #define PG8_MMA(ai, bj, At, Bt) do { __builtin_amdgcn_s_setprio(1); _Pragma("unroll") for (int m = 0; m < 4; ++m) _Pragma("unroll") for (int n = 0; n < 2; ++n) _Pragma("unroll") for (int k = 0; k < 2; ++k) \
;         acc[ai][bj][m][n] = __builtin_amdgcn_mfma_f32_16x16x32_bf16(Bt[n][k], At[m][k], acc[ai][bj][m][n], 0, 0, 0); __builtin_amdgcn_s_setprio(0); } while (0)
; #define PG8_WAIT_V(n) asm volatile("s_waitcnt vmcnt(" #n ")" ::: "memory")
; #define PG8_WAIT_L(n) asm volatile("s_waitcnt lgkmcnt(" #n ")" ::: "memory")
; #define PG8_BAR __builtin_amdgcn_s_barrier()
; #define PG8_SCHED __builtin_amdgcn_sched_barrier(0)
; template <class Epi, bool ALIGN_EPI>
; __device__ __forceinline__ void gemm_phase(LAS unsigned char* lds, const Gemm g, const StaticOrder S, const Epi E) {
;     ...
;             const bool last = (t == nt - 2);
;             const char* a1 = cA + (size_t)(t + 1) * kstep;
;             const char* a2 = last ? nA : cA + (size_t)(t + 2) * kstep; const char* b2 = last ? nB : cB + (size_t)(t + 2) * kstep;
;             const char* a3 = a2 + kstep; const char* b3 = b2 + kstep;
;             PG8_LDB(B0, 0, 0); PG8_LDB(B1, 0, 1); PG8_SCHED; PG8_LDA(At, 0, 0); PG8_STAGE(PG8_SA(1, 1), a1 + hstepA, voffA);
;             PG8_WAIT_V(8); PG8_WAIT_L(0); PG8_BAR; PG8_MMA(0, 0, At, B0); PG8_MMA(0, 1, At, B1); PG8_BAR; PG8_SCHED;
;             PG8_LDA(At, 0, 1); PG8_STAGE(PG8_SB(0, 0), b2, voffB); PG8_STAGE(PG8_SB(0, 1), b2 + hstepB, voffB); PG8_STAGE(PG8_SA(0, 0), a2, voffA);
;             PG8_WAIT_V(8); PG8_WAIT_L(0); PG8_BAR; PG8_MMA(1, 0, At, B0); PG8_MMA(1, 1, At, B1); PG8_BAR; PG8_SCHED;
.LBB0_1757:
	s_add_u32 s50, s48, 0x100
	s_addc_u32 s51, s49, 0
	s_add_i32 s0, 0, 0x10000
	s_cmp_eq_u32 s28, 2
	s_cselect_b32 s55, s43, s51
	s_cselect_b32 s54, s42, s50
	v_add_u32_e32 v80, s0, v156
	s_cselect_b32 s53, s47, s27
	s_cselect_b32 s52, s46, s26
	s_add_i32 s12, 0, 0x14000
	ds_read_b128 v[148:151], v80
	ds_read_b128 v[158:161], v80 offset:1024
	ds_read_b128 v[162:165], v80 offset:2048
	ds_read_b128 v[182:185], v80 offset:3072
	v_add_u32_e32 v80, s12, v156
	ds_read_b128 v[186:189], v80
	ds_read_b128 v[190:193], v80 offset:1024
	ds_read_b128 v[194:197], v80 offset:2048
	ds_read_b128 v[198:201], v80 offset:3072
	v_lshl_add_u64 v[152:153], s[48:49], 0, v[144:145]
	s_add_i32 m0, s62, 0xc000
	ds_read_b128 v[202:205], v157
	ds_read_b128 v[206:209], v157 offset:1024
	ds_read_b128 v[210:213], v157 offset:2048
	ds_read_b128 v[214:217], v157 offset:3072
	ds_read_b128 v[218:221], v157 offset:4096
	ds_read_b128 v[222:225], v157 offset:5120
	ds_read_b128 v[226:229], v157 offset:6144
	ds_read_b128 v[230:233], v157 offset:7168
	global_load_lds_dwordx4 v[152:153], off
	v_lshl_add_u64 v[152:153], s[48:49], 0, v[146:147]
	s_add_i32 m0, s62, 0xe000
	s_nop 0
	global_load_lds_dwordx4 v[152:153], off
	s_waitcnt vmcnt(8)
	s_waitcnt lgkmcnt(0)
	s_barrier
	s_waitcnt lgkmcnt(0)
	v_mfma_f32_16x16x32_bf16 v[126:129], v[148:151], v[202:205], v[126:129]
	v_mfma_f32_16x16x32_bf16 v[122:125], v[162:165], v[202:205], v[122:125]
	v_mfma_f32_16x16x32_bf16 v[118:121], v[148:151], v[210:213], v[118:121]
	v_mfma_f32_16x16x32_bf16 v[114:117], v[162:165], v[210:213], v[114:117]
	v_mfma_f32_16x16x32_bf16 v[110:113], v[148:151], v[218:221], v[110:113]
	v_mfma_f32_16x16x32_bf16 v[106:109], v[162:165], v[218:221], v[106:109]
	v_mfma_f32_16x16x32_bf16 v[102:105], v[148:151], v[226:229], v[102:105]
	v_mfma_f32_16x16x32_bf16 v[98:101], v[162:165], v[226:229], v[98:101]
	v_mfma_f32_16x16x32_bf16 v[126:129], v[158:161], v[206:209], v[126:129]
	v_mfma_f32_16x16x32_bf16 v[122:125], v[182:185], v[206:209], v[122:125]
	v_mfma_f32_16x16x32_bf16 v[118:121], v[158:161], v[214:217], v[118:121]
	v_mfma_f32_16x16x32_bf16 v[114:117], v[182:185], v[214:217], v[114:117]
	v_mfma_f32_16x16x32_bf16 v[110:113], v[158:161], v[222:225], v[110:113]
	v_mfma_f32_16x16x32_bf16 v[106:109], v[182:185], v[222:225], v[106:109]
	v_mfma_f32_16x16x32_bf16 v[102:105], v[158:161], v[230:233], v[102:105]
	v_mfma_f32_16x16x32_bf16 v[98:101], v[182:185], v[230:233], v[98:101]
	v_mfma_f32_16x16x32_bf16 v[60:63], v[186:189], v[202:205], v[60:63]
	v_mfma_f32_16x16x32_bf16 v[56:59], v[194:197], v[202:205], v[56:59]
	v_mfma_f32_16x16x32_bf16 v[52:55], v[186:189], v[210:213], v[52:55]
	v_mfma_f32_16x16x32_bf16 v[48:51], v[194:197], v[210:213], v[48:51]
	v_mfma_f32_16x16x32_bf16 v[44:47], v[186:189], v[218:221], v[44:47]
	v_mfma_f32_16x16x32_bf16 v[40:43], v[194:197], v[218:221], v[40:43]
	v_mfma_f32_16x16x32_bf16 v[36:39], v[186:189], v[226:229], v[36:39]
	v_mfma_f32_16x16x32_bf16 v[32:35], v[194:197], v[226:229], v[32:35]
	v_mfma_f32_16x16x32_bf16 v[60:63], v[190:193], v[206:209], v[60:63]
	v_mfma_f32_16x16x32_bf16 v[56:59], v[198:201], v[206:209], v[56:59]
	v_mfma_f32_16x16x32_bf16 v[52:55], v[190:193], v[214:217], v[52:55]
	v_mfma_f32_16x16x32_bf16 v[48:51], v[198:201], v[214:217], v[48:51]
	v_mfma_f32_16x16x32_bf16 v[44:47], v[190:193], v[222:225], v[44:47]
	v_mfma_f32_16x16x32_bf16 v[40:43], v[198:201], v[222:225], v[40:43]
	v_mfma_f32_16x16x32_bf16 v[36:39], v[190:193], v[230:233], v[36:39]
	v_mfma_f32_16x16x32_bf16 v[32:35], v[198:201], v[230:233], v[32:35]
	s_barrier
	s_add_i32 s0, s0, s61
	v_lshl_add_u64 v[152:153], s[52:53], 0, v[138:139]
	s_mov_b32 m0, s0
	ds_read_b128 v[202:205], v157 offset:16384
	ds_read_b128 v[206:209], v157 offset:17408
	ds_read_b128 v[210:213], v157 offset:18432
	ds_read_b128 v[214:217], v157 offset:19456
	ds_read_b128 v[218:221], v157 offset:20480
	ds_read_b128 v[222:225], v157 offset:21504
	ds_read_b128 v[226:229], v157 offset:22528
	ds_read_b128 v[230:233], v157 offset:23552
	global_load_lds_dwordx4 v[152:153], off
	s_add_i32 m0, s0, 0x2000
	s_add_u32 s0, s52, 0x18000
	v_lshl_add_u64 v[168:169], s[52:53], 0, v[142:143]
	s_addc_u32 s1, s53, 0
	s_add_i32 s12, s12, s61
	global_load_lds_dwordx4 v[168:169], off
	v_lshl_add_u64 v[170:171], s[0:1], 0, v[138:139]
	s_mov_b32 m0, s12
	v_lshl_add_u64 v[172:173], s[54:55], 0, v[140:141]
	global_load_lds_dwordx4 v[170:171], off
	v_lshl_add_u64 v[170:171], s[0:1], 0, v[142:143]
	s_add_i32 m0, s12, 0x2000
	s_nop 0
	global_load_lds_dwordx4 v[170:171], off
	v_lshl_add_u64 v[170:171], s[54:55], 0, v[136:137]
	s_mov_b32 m0, s62
	s_nop 0
	global_load_lds_dwordx4 v[170:171], off
	s_mov_b32 m0, s63
	s_nop 0
	global_load_lds_dwordx4 v[172:173], off
	s_waitcnt vmcnt(8)
	s_waitcnt lgkmcnt(0)
	s_barrier
; #define PG8_STAGE(bufoff, gbase, voff) do { _Pragma("unroll") for (int _i = 0; _i < 2; ++_i) \
;         __builtin_amdgcn_global_load_lds((const unsigned*)((const char*)(gbase) + (voff)[_i]), (LAS unsigned*)(lds + (bufoff) + ldsw + _i * 8192), 16, 0, 0); } while (0)
; #define PG8_LDA(dst, b, h) do { _Pragma("unroll") for (int m = 0; m < 4; ++m) _Pragma("unroll") for (int k = 0; k < 2; ++k) dst[m][k] = *(const LAS bf16x8*)(lds + PG8_SA(b, h) + aoff + m * 2048 + k * 1024); } while (0)
; #define PG8_LDB(dst, b, h) do { _Pragma("unroll") for (int n = 0; n < 2; ++n) _Pragma("unroll") for (int k = 0; k < 2; ++k) dst[n][k] = *(const LAS bf16x8*)(lds + PG8_SB(b, h) + boff + n * 2048 + k * 1024); } while (0)
; #define PG8_MMA(ai, bj, At, Bt) do { __builtin_amdgcn_s_setprio(1); _Pragma("unroll") for (int m = 0; m < 4; ++m) _Pragma("unroll") for (int n = 0; n < 2; ++n) _Pragma("unroll") for (int k = 0; k < 2; ++k) \
;         acc[ai][bj][m][n] = __builtin_amdgcn_mfma_f32_16x16x32_bf16(Bt[n][k], At[m][k], acc[ai][bj][m][n], 0, 0, 0); __builtin_amdgcn_s_setprio(0); } while (0)
; #define PG8_WAIT_V(n) asm volatile("s_waitcnt vmcnt(" #n ")" ::: "memory")
; #define PG8_WAIT_L(n) asm volatile("s_waitcnt lgkmcnt(" #n ")" ::: "memory")
; #define PG8_BAR __builtin_amdgcn_s_barrier()
; #define PG8_SCHED __builtin_amdgcn_sched_barrier(0)
; template <class Epi, bool ALIGN_EPI>
; __device__ __forceinline__ void gemm_phase(LAS unsigned char* lds, const Gemm g, const StaticOrder S, const Epi E) {
;     ...
;             PG8_WAIT_V(8); PG8_WAIT_L(0); PG8_BAR; PG8_MMA(1, 0, At, B0); PG8_MMA(1, 1, At, B1); PG8_BAR; PG8_SCHED;
;             PG8_LDB(B0, 1, 0); PG8_LDB(B1, 1, 1); PG8_SCHED; PG8_LDA(At, 1, 0); PG8_STAGE(PG8_SA(0, 1), a2 + hstepA, voffA);
;             PG8_WAIT_V(8); PG8_WAIT_L(0); PG8_BAR; PG8_MMA(0, 0, At, B0); PG8_MMA(0, 1, At, B1); PG8_BAR; PG8_SCHED;
	s_waitcnt lgkmcnt(0)
	v_mfma_f32_16x16x32_bf16 v[94:97], v[148:151], v[202:205], v[94:97]
	v_mfma_f32_16x16x32_bf16 v[90:93], v[162:165], v[202:205], v[90:93]
	v_mfma_f32_16x16x32_bf16 v[86:89], v[148:151], v[210:213], v[86:89]
	v_mfma_f32_16x16x32_bf16 v[82:85], v[162:165], v[210:213], v[82:85]
	v_mfma_f32_16x16x32_bf16 v[76:79], v[148:151], v[218:221], v[76:79]
	v_mfma_f32_16x16x32_bf16 v[72:75], v[162:165], v[218:221], v[72:75]
	v_mfma_f32_16x16x32_bf16 v[68:71], v[148:151], v[226:229], v[68:71]
	v_mfma_f32_16x16x32_bf16 v[64:67], v[162:165], v[226:229], v[64:67]
	v_mfma_f32_16x16x32_bf16 v[94:97], v[158:161], v[206:209], v[94:97]
	v_mfma_f32_16x16x32_bf16 v[90:93], v[182:185], v[206:209], v[90:93]
	v_mfma_f32_16x16x32_bf16 v[86:89], v[158:161], v[214:217], v[86:89]
	v_mfma_f32_16x16x32_bf16 v[82:85], v[182:185], v[214:217], v[82:85]
	v_mfma_f32_16x16x32_bf16 v[76:79], v[158:161], v[222:225], v[76:79]
	v_mfma_f32_16x16x32_bf16 v[72:75], v[182:185], v[222:225], v[72:75]
	v_mfma_f32_16x16x32_bf16 v[68:71], v[158:161], v[230:233], v[68:71]
	v_mfma_f32_16x16x32_bf16 v[64:67], v[182:185], v[230:233], v[64:67]
	v_mfma_f32_16x16x32_bf16 v[28:31], v[186:189], v[202:205], v[28:31]
	v_mfma_f32_16x16x32_bf16 v[24:27], v[194:197], v[202:205], v[24:27]
	v_mfma_f32_16x16x32_bf16 v[20:23], v[186:189], v[210:213], v[20:23]
	v_mfma_f32_16x16x32_bf16 v[16:19], v[194:197], v[210:213], v[16:19]
	v_mfma_f32_16x16x32_bf16 v[12:15], v[186:189], v[218:221], v[12:15]
	v_mfma_f32_16x16x32_bf16 v[8:11], v[194:197], v[218:221], v[8:11]
	v_mfma_f32_16x16x32_bf16 v[4:7], v[186:189], v[226:229], v[4:7]
	v_mfma_f32_16x16x32_bf16 v[0:3], v[194:197], v[226:229], v[0:3]
	v_mfma_f32_16x16x32_bf16 v[28:31], v[190:193], v[206:209], v[28:31]
	v_mfma_f32_16x16x32_bf16 v[24:27], v[198:201], v[206:209], v[24:27]
	v_mfma_f32_16x16x32_bf16 v[20:23], v[190:193], v[214:217], v[20:23]
	v_mfma_f32_16x16x32_bf16 v[16:19], v[198:201], v[214:217], v[16:19]
	v_mfma_f32_16x16x32_bf16 v[12:15], v[190:193], v[222:225], v[12:15]
	v_mfma_f32_16x16x32_bf16 v[8:11], v[198:201], v[222:225], v[8:11]
	v_mfma_f32_16x16x32_bf16 v[4:7], v[190:193], v[230:233], v[4:7]
	v_mfma_f32_16x16x32_bf16 v[0:3], v[198:201], v[230:233], v[0:3]
	s_barrier
	s_add_i32 s12, 0, 0x18000
	v_add_u32_e32 v80, s12, v156
	s_add_i32 s15, 0, 0x1c000
	ds_read_b128 v[148:151], v80
	ds_read_b128 v[158:161], v80 offset:1024
	ds_read_b128 v[162:165], v80 offset:2048
	ds_read_b128 v[182:185], v80 offset:3072
	v_add_u32_e32 v80, s15, v156
	ds_read_b128 v[186:189], v80
	ds_read_b128 v[190:193], v80 offset:1024
	ds_read_b128 v[194:197], v80 offset:2048
	ds_read_b128 v[198:201], v80 offset:3072
	s_add_u32 s0, s54, 0xb0000
	s_addc_u32 s1, s55, 0
	s_mov_b32 m0, s64
	v_lshl_add_u64 v[176:177], s[0:1], 0, v[136:137]
	ds_read_b128 v[202:205], v157 offset:32768
	ds_read_b128 v[206:209], v157 offset:33792
	ds_read_b128 v[210:213], v157 offset:34816
	ds_read_b128 v[214:217], v157 offset:35840
	ds_read_b128 v[218:221], v157 offset:36864
	ds_read_b128 v[222:225], v157 offset:37888
	ds_read_b128 v[226:229], v157 offset:38912
	ds_read_b128 v[230:233], v157 offset:39936
	global_load_lds_dwordx4 v[176:177], off
	v_lshl_add_u64 v[176:177], s[0:1], 0, v[140:141]
	s_mov_b32 m0, s65
	s_nop 0
	global_load_lds_dwordx4 v[176:177], off
	s_waitcnt vmcnt(8)
	s_waitcnt lgkmcnt(0)
	s_barrier
	s_waitcnt lgkmcnt(0)
	v_mfma_f32_16x16x32_bf16 v[126:129], v[148:151], v[202:205], v[126:129]
	v_mfma_f32_16x16x32_bf16 v[122:125], v[162:165], v[202:205], v[122:125]
	v_mfma_f32_16x16x32_bf16 v[118:121], v[148:151], v[210:213], v[118:121]
	v_mfma_f32_16x16x32_bf16 v[114:117], v[162:165], v[210:213], v[114:117]
	v_mfma_f32_16x16x32_bf16 v[110:113], v[148:151], v[218:221], v[110:113]
	v_mfma_f32_16x16x32_bf16 v[106:109], v[162:165], v[218:221], v[106:109]
	v_mfma_f32_16x16x32_bf16 v[102:105], v[148:151], v[226:229], v[102:105]
	v_mfma_f32_16x16x32_bf16 v[98:101], v[162:165], v[226:229], v[98:101]
	v_mfma_f32_16x16x32_bf16 v[126:129], v[158:161], v[206:209], v[126:129]
	v_mfma_f32_16x16x32_bf16 v[122:125], v[182:185], v[206:209], v[122:125]
	v_mfma_f32_16x16x32_bf16 v[118:121], v[158:161], v[214:217], v[118:121]
	v_mfma_f32_16x16x32_bf16 v[114:117], v[182:185], v[214:217], v[114:117]
	v_mfma_f32_16x16x32_bf16 v[110:113], v[158:161], v[222:225], v[110:113]
	v_mfma_f32_16x16x32_bf16 v[106:109], v[182:185], v[222:225], v[106:109]
	v_mfma_f32_16x16x32_bf16 v[102:105], v[158:161], v[230:233], v[102:105]
	v_mfma_f32_16x16x32_bf16 v[98:101], v[182:185], v[230:233], v[98:101]
	v_mfma_f32_16x16x32_bf16 v[60:63], v[186:189], v[202:205], v[60:63]
	v_mfma_f32_16x16x32_bf16 v[56:59], v[194:197], v[202:205], v[56:59]
	v_mfma_f32_16x16x32_bf16 v[52:55], v[186:189], v[210:213], v[52:55]
	v_mfma_f32_16x16x32_bf16 v[48:51], v[194:197], v[210:213], v[48:51]
	v_mfma_f32_16x16x32_bf16 v[44:47], v[186:189], v[218:221], v[44:47]
	v_mfma_f32_16x16x32_bf16 v[40:43], v[194:197], v[218:221], v[40:43]
	v_mfma_f32_16x16x32_bf16 v[36:39], v[186:189], v[226:229], v[36:39]
	v_mfma_f32_16x16x32_bf16 v[32:35], v[194:197], v[226:229], v[32:35]
	v_mfma_f32_16x16x32_bf16 v[60:63], v[190:193], v[206:209], v[60:63]
	v_mfma_f32_16x16x32_bf16 v[56:59], v[198:201], v[206:209], v[56:59]
	v_mfma_f32_16x16x32_bf16 v[52:55], v[190:193], v[214:217], v[52:55]
	v_mfma_f32_16x16x32_bf16 v[48:51], v[198:201], v[214:217], v[48:51]
	v_mfma_f32_16x16x32_bf16 v[44:47], v[190:193], v[222:225], v[44:47]
	v_mfma_f32_16x16x32_bf16 v[40:43], v[198:201], v[222:225], v[40:43]
	v_mfma_f32_16x16x32_bf16 v[36:39], v[190:193], v[230:233], v[36:39]
	v_mfma_f32_16x16x32_bf16 v[32:35], v[198:201], v[230:233], v[32:35]
	s_barrier
; #define PG8_STAGE(bufoff, gbase, voff) do { _Pragma("unroll") for (int _i = 0; _i < 2; ++_i) \
;         __builtin_amdgcn_global_load_lds((const unsigned*)((const char*)(gbase) + (voff)[_i]), (LAS unsigned*)(lds + (bufoff) + ldsw + _i * 8192), 16, 0, 0); } while (0)
; #define PG8_LDA(dst, b, h) do { _Pragma("unroll") for (int m = 0; m < 4; ++m) _Pragma("unroll") for (int k = 0; k < 2; ++k) dst[m][k] = *(const LAS bf16x8*)(lds + PG8_SA(b, h) + aoff + m * 2048 + k * 1024); } while (0)
; #define PG8_MMA(ai, bj, At, Bt) do { __builtin_amdgcn_s_setprio(1); _Pragma("unroll") for (int m = 0; m < 4; ++m) _Pragma("unroll") for (int n = 0; n < 2; ++n) _Pragma("unroll") for (int k = 0; k < 2; ++k) \
;         acc[ai][bj][m][n] = __builtin_amdgcn_mfma_f32_16x16x32_bf16(Bt[n][k], At[m][k], acc[ai][bj][m][n], 0, 0, 0); __builtin_amdgcn_s_setprio(0); } while (0)
; #define PG8_WAIT_V(n) asm volatile("s_waitcnt vmcnt(" #n ")" ::: "memory")
; #define PG8_WAIT_L(n) asm volatile("s_waitcnt lgkmcnt(" #n ")" ::: "memory")
; #define PG8_BAR __builtin_amdgcn_s_barrier()
; #define PG8_SCHED __builtin_amdgcn_sched_barrier(0)
; template <class Epi, bool ALIGN_EPI>
; __device__ __forceinline__ void gemm_phase(LAS unsigned char* lds, const Gemm g, const StaticOrder S, const Epi E) {
;     ...
;             PG8_LDA(At, 1, 1); PG8_STAGE(PG8_SB(1, 0), b3, voffB); PG8_STAGE(PG8_SB(1, 1), b3 + hstepB, voffB); PG8_STAGE(PG8_SA(1, 0), a3, voffA);
;             PG8_WAIT_V(8); PG8_WAIT_L(0); PG8_BAR; PG8_MMA(1, 0, At, B0); PG8_MMA(1, 1, At, B1); PG8_BAR; PG8_SCHED;
;         }
;         if constexpr (ALIGN_EPI) { if (wr == 0) PG8_BAR; }
	s_add_i32 s0, s12, s61
	v_lshl_add_u64 v[152:153], v[152:153], 0, s[80:81]
	s_mov_b32 m0, s0
	ds_read_b128 v[202:205], v157 offset:49152
	ds_read_b128 v[206:209], v157 offset:50176
	ds_read_b128 v[210:213], v157 offset:51200
	ds_read_b128 v[214:217], v157 offset:52224
	ds_read_b128 v[218:221], v157 offset:53248
	ds_read_b128 v[222:225], v157 offset:54272
	ds_read_b128 v[226:229], v157 offset:55296
	ds_read_b128 v[230:233], v157 offset:56320
	global_load_lds_dwordx4 v[152:153], off
	s_add_i32 m0, s0, 0x2000
	s_add_u32 s0, s52, 0x18080
	v_lshl_add_u64 v[152:153], v[168:169], 0, s[80:81]
	s_addc_u32 s1, s53, 0
	s_add_i32 s12, s15, s61
	global_load_lds_dwordx4 v[152:153], off
	v_lshl_add_u64 v[152:153], s[0:1], 0, v[138:139]
	s_mov_b32 m0, s12
	s_nop 0
	global_load_lds_dwordx4 v[152:153], off
	v_lshl_add_u64 v[152:153], s[0:1], 0, v[142:143]
	s_add_i32 m0, s12, 0x2000
	s_nop 0
	global_load_lds_dwordx4 v[152:153], off
	v_lshl_add_u64 v[152:153], v[170:171], 0, s[80:81]
	s_mov_b32 m0, s68
	s_nop 0
	global_load_lds_dwordx4 v[152:153], off
	v_lshl_add_u64 v[152:153], v[172:173], 0, s[80:81]
	s_mov_b32 m0, s69
	s_nop 0
	global_load_lds_dwordx4 v[152:153], off
	s_waitcnt vmcnt(8)
	s_waitcnt lgkmcnt(0)
	s_barrier
	s_waitcnt lgkmcnt(0)
	v_mfma_f32_16x16x32_bf16 v[94:97], v[148:151], v[202:205], v[94:97]
	v_mfma_f32_16x16x32_bf16 v[90:93], v[162:165], v[202:205], v[90:93]
	v_mfma_f32_16x16x32_bf16 v[86:89], v[148:151], v[210:213], v[86:89]
	v_mfma_f32_16x16x32_bf16 v[82:85], v[162:165], v[210:213], v[82:85]
	v_mfma_f32_16x16x32_bf16 v[76:79], v[148:151], v[218:221], v[76:79]
	v_mfma_f32_16x16x32_bf16 v[72:75], v[162:165], v[218:221], v[72:75]
	v_mfma_f32_16x16x32_bf16 v[68:71], v[148:151], v[226:229], v[68:71]
	v_mfma_f32_16x16x32_bf16 v[64:67], v[162:165], v[226:229], v[64:67]
	v_mfma_f32_16x16x32_bf16 v[94:97], v[158:161], v[206:209], v[94:97]
	v_mfma_f32_16x16x32_bf16 v[90:93], v[182:185], v[206:209], v[90:93]
	v_mfma_f32_16x16x32_bf16 v[86:89], v[158:161], v[214:217], v[86:89]
	v_mfma_f32_16x16x32_bf16 v[82:85], v[182:185], v[214:217], v[82:85]
	v_mfma_f32_16x16x32_bf16 v[76:79], v[158:161], v[222:225], v[76:79]
	v_mfma_f32_16x16x32_bf16 v[72:75], v[182:185], v[222:225], v[72:75]
	v_mfma_f32_16x16x32_bf16 v[68:71], v[158:161], v[230:233], v[68:71]
	v_mfma_f32_16x16x32_bf16 v[64:67], v[182:185], v[230:233], v[64:67]
	v_mfma_f32_16x16x32_bf16 v[28:31], v[186:189], v[202:205], v[28:31]
	v_mfma_f32_16x16x32_bf16 v[24:27], v[194:197], v[202:205], v[24:27]
	v_mfma_f32_16x16x32_bf16 v[20:23], v[186:189], v[210:213], v[20:23]
	v_mfma_f32_16x16x32_bf16 v[16:19], v[194:197], v[210:213], v[16:19]
	v_mfma_f32_16x16x32_bf16 v[12:15], v[186:189], v[218:221], v[12:15]
	v_mfma_f32_16x16x32_bf16 v[8:11], v[194:197], v[218:221], v[8:11]
	v_mfma_f32_16x16x32_bf16 v[4:7], v[186:189], v[226:229], v[4:7]
	v_mfma_f32_16x16x32_bf16 v[0:3], v[194:197], v[226:229], v[0:3]
	v_mfma_f32_16x16x32_bf16 v[28:31], v[190:193], v[206:209], v[28:31]
	v_mfma_f32_16x16x32_bf16 v[24:27], v[198:201], v[206:209], v[24:27]
	v_mfma_f32_16x16x32_bf16 v[20:23], v[190:193], v[214:217], v[20:23]
	v_mfma_f32_16x16x32_bf16 v[16:19], v[198:201], v[214:217], v[16:19]
	v_mfma_f32_16x16x32_bf16 v[12:15], v[190:193], v[222:225], v[12:15]
	v_mfma_f32_16x16x32_bf16 v[8:11], v[198:201], v[222:225], v[8:11]
	v_mfma_f32_16x16x32_bf16 v[4:7], v[190:193], v[230:233], v[4:7]
	v_mfma_f32_16x16x32_bf16 v[0:3], v[198:201], v[230:233], v[0:3]
	s_barrier
	s_add_i32 s28, s28, 2
	s_add_u32 s26, s26, 0x100
	s_addc_u32 s27, s27, 0
	s_cmp_gt_u32 s28, 3
	s_mov_b64 s[48:49], s[50:51]
	s_cbranch_scc0 .LBB0_1757
	s_and_b64 vcc, exec, s[44:45]
	s_cbranch_vccz .LBB0_1760
	s_barrier

; #define PG8_STAGE(bufoff, gbase, voff) do { _Pragma("unroll") for (int _i = 0; _i < 2; ++_i) \
;         __builtin_amdgcn_global_load_lds((const unsigned*)((const char*)(gbase) + (voff)[_i]), (LAS unsigned*)(lds + (bufoff) + ldsw + _i * 8192), 16, 0, 0); } while (0)
; #define PG8_LDA(dst, b, h) do { _Pragma("unroll") for (int m = 0; m < 4; ++m) _Pragma("unroll") for (int k = 0; k < 2; ++k) dst[m][k] = *(const LAS bf16x8*)(lds + PG8_SA(b, h) + aoff + m * 2048 + k * 1024); } while (0)
; #define PG8_LDB(dst, b, h) do { _Pragma("unroll") for (int n = 0; n < 2; ++n) _Pragma("unroll") for (int k = 0; k < 2; ++k) dst[n][k] = *(const LAS bf16x8*)(lds + PG8_SB(b, h) + boff + n * 2048 + k * 1024); } while (0)
; #define PG8_MMA(ai, bj, At, Bt) do { __builtin_amdgcn_s_setprio(1); _Pragma("unroll") for (int m = 0; m < 4; ++m) _Pragma("unroll") for (int n = 0; n < 2; ++n) _Pragma("unroll") for (int k = 0; k < 2; ++k) \
;         acc[ai][bj][m][n] = __builtin_amdgcn_mfma_f32_16x16x32_bf16(Bt[n][k], At[m][k], acc[ai][bj][m][n], 0, 0, 0); __builtin_amdgcn_s_setprio(0); } while (0)
; #define PG8_WAIT_V(n) asm volatile("s_waitcnt vmcnt(" #n ")" ::: "memory")
; #define PG8_WAIT_L(n) asm volatile("s_waitcnt lgkmcnt(" #n ")" ::: "memory")
; #define PG8_BAR __builtin_amdgcn_s_barrier()
; #define PG8_SCHED __builtin_amdgcn_sched_barrier(0)
; template <class Epi, bool ALIGN_EPI>
; __device__ __forceinline__ void gemm_phase(LAS unsigned char* lds, const Gemm g, const StaticOrder S, const Epi E) {
;     ...
;             const bool last = (t == nt - 2);
;             const char* a1 = cA + (size_t)(t + 1) * kstep;
;             const char* a2 = last ? nA : cA + (size_t)(t + 2) * kstep; const char* b2 = last ? nB : cB + (size_t)(t + 2) * kstep;
;             const char* a3 = a2 + kstep; const char* b3 = b2 + kstep;
;             PG8_LDB(B0, 0, 0); PG8_LDB(B1, 0, 1); PG8_SCHED; PG8_LDA(At, 0, 0); PG8_STAGE(PG8_SA(1, 1), a1 + hstepA, voffA);
;             PG8_WAIT_V(8); PG8_WAIT_L(0); PG8_BAR; PG8_MMA(0, 0, At, B0); PG8_MMA(0, 1, At, B1); PG8_BAR; PG8_SCHED;
;             PG8_LDA(At, 0, 1); PG8_STAGE(PG8_SB(0, 0), b2, voffB); PG8_STAGE(PG8_SB(0, 1), b2 + hstepB, voffB); PG8_STAGE(PG8_SA(0, 0), a2, voffA);
;             PG8_WAIT_V(8); PG8_WAIT_L(0); PG8_BAR; PG8_MMA(1, 0, At, B0); PG8_MMA(1, 1, At, B1); PG8_BAR; PG8_SCHED;
.LBB0_1815:
	s_add_u32 s12, s54, s64
	s_addc_u32 s15, s55, s65
	s_add_u32 s16, s12, 0x100
	s_addc_u32 s18, s15, 0
	s_and_b64 s[0:1], s[62:63], exec
	s_cselect_b32 s67, s49, s18
	s_cselect_b32 s66, s48, s16
	s_add_u32 s0, s52, s64
	s_addc_u32 s1, s53, s65
	s_add_u32 s16, s0, 0x100
	s_addc_u32 s18, s1, 0
	s_add_i32 s83, 0, 0x10000
	s_and_b64 s[0:1], s[62:63], exec
	s_cselect_b32 s69, s47, s18
	s_cselect_b32 s68, s93, s16
	s_add_i32 s16, 0, 0x14000
	s_add_u32 s72, s12, 0xb0080
	s_addc_u32 s73, s15, 0
	s_add_i32 s0, s83, s24
	s_add_i32 m0, s21, 0xc000
	s_add_i32 s25, s21, 0xe000
	s_add_i32 s33, s0, 0x2000
	v_add_u32_e32 v130, s83, v146
	s_add_u32 s70, s68, 0x10000
	ds_read_b128 v[148:151], v130
	ds_read_b128 v[152:155], v130 offset:1024
	ds_read_b128 v[156:159], v130 offset:2048
	ds_read_b128 v[160:163], v130 offset:3072
	v_add_u32_e32 v130, s16, v146
	s_addc_u32 s71, s69, 0
	s_add_i32 s1, s16, s24
	ds_read_b128 v[182:185], v130
	ds_read_b128 v[186:189], v130 offset:1024
	ds_read_b128 v[190:193], v130 offset:2048
	ds_read_b128 v[194:197], v130 offset:3072
	s_add_i32 s82, s1, 0x2000
	s_add_i32 vcc_hi, 0, 0x18000
	s_add_i32 s12, 0, 0x1c000
	s_add_u32 s64, s66, 0xb0000
	s_addc_u32 s65, s67, 0
	s_add_i32 vcc_lo, vcc_hi, s24
	s_add_i32 s18, vcc_lo, 0x2000
	s_add_u32 s62, s68, 0x10080
	s_addc_u32 s63, s69, 0
	s_add_i32 s15, s12, s24
	s_add_i32 s16, s15, 0x2000
	v_lshl_add_u64 v[142:143], s[72:73], 0, v[136:137]
	ds_read_b128 v[198:201], v147
	ds_read_b128 v[202:205], v147 offset:1024
	ds_read_b128 v[206:209], v147 offset:2048
	ds_read_b128 v[210:213], v147 offset:3072
	ds_read_b128 v[214:217], v147 offset:4096
	ds_read_b128 v[218:221], v147 offset:5120
	ds_read_b128 v[222:225], v147 offset:6144
	ds_read_b128 v[226:229], v147 offset:7168
	global_load_lds_dwordx4 v[142:143], off
	v_lshl_add_u64 v[142:143], s[72:73], 0, v[138:139]
	s_mov_b32 m0, s25
	s_nop 0
	global_load_lds_dwordx4 v[142:143], off
	s_waitcnt vmcnt(8)
	s_waitcnt lgkmcnt(0)
	s_barrier
	s_waitcnt lgkmcnt(0)
	v_mfma_f32_16x16x32_bf16 v[126:129], v[148:151], v[198:201], v[126:129]
	v_mfma_f32_16x16x32_bf16 v[122:125], v[156:159], v[198:201], v[122:125]
	v_mfma_f32_16x16x32_bf16 v[118:121], v[148:151], v[206:209], v[118:121]
	v_mfma_f32_16x16x32_bf16 v[110:113], v[156:159], v[206:209], v[110:113]
	v_mfma_f32_16x16x32_bf16 v[102:105], v[148:151], v[214:217], v[102:105]
	v_mfma_f32_16x16x32_bf16 v[94:97], v[156:159], v[214:217], v[94:97]
	v_mfma_f32_16x16x32_bf16 v[86:89], v[148:151], v[222:225], v[86:89]
	v_mfma_f32_16x16x32_bf16 v[76:79], v[156:159], v[222:225], v[76:79]
	v_mfma_f32_16x16x32_bf16 v[126:129], v[152:155], v[202:205], v[126:129]
	v_mfma_f32_16x16x32_bf16 v[122:125], v[160:163], v[202:205], v[122:125]
	v_mfma_f32_16x16x32_bf16 v[118:121], v[152:155], v[210:213], v[118:121]
	v_mfma_f32_16x16x32_bf16 v[110:113], v[160:163], v[210:213], v[110:113]
	v_mfma_f32_16x16x32_bf16 v[102:105], v[152:155], v[218:221], v[102:105]
	v_mfma_f32_16x16x32_bf16 v[94:97], v[160:163], v[218:221], v[94:97]
	v_mfma_f32_16x16x32_bf16 v[86:89], v[152:155], v[226:229], v[86:89]
	v_mfma_f32_16x16x32_bf16 v[76:79], v[160:163], v[226:229], v[76:79]
	v_mfma_f32_16x16x32_bf16 v[114:117], v[182:185], v[198:201], v[114:117]
	v_mfma_f32_16x16x32_bf16 v[106:109], v[190:193], v[198:201], v[106:109]
	v_mfma_f32_16x16x32_bf16 v[98:101], v[182:185], v[206:209], v[98:101]
	v_mfma_f32_16x16x32_bf16 v[90:93], v[190:193], v[206:209], v[90:93]
	v_mfma_f32_16x16x32_bf16 v[82:85], v[182:185], v[214:217], v[82:85]
	v_mfma_f32_16x16x32_bf16 v[72:75], v[190:193], v[214:217], v[72:75]
	v_mfma_f32_16x16x32_bf16 v[68:71], v[182:185], v[222:225], v[68:71]
	v_mfma_f32_16x16x32_bf16 v[64:67], v[190:193], v[222:225], v[64:67]
	v_mfma_f32_16x16x32_bf16 v[114:117], v[186:189], v[202:205], v[114:117]
	v_mfma_f32_16x16x32_bf16 v[106:109], v[194:197], v[202:205], v[106:109]
	v_mfma_f32_16x16x32_bf16 v[98:101], v[186:189], v[210:213], v[98:101]
	v_mfma_f32_16x16x32_bf16 v[90:93], v[194:197], v[210:213], v[90:93]
	v_mfma_f32_16x16x32_bf16 v[82:85], v[186:189], v[218:221], v[82:85]
	v_mfma_f32_16x16x32_bf16 v[72:75], v[194:197], v[218:221], v[72:75]
	v_mfma_f32_16x16x32_bf16 v[68:71], v[186:189], v[226:229], v[68:71]
	v_mfma_f32_16x16x32_bf16 v[64:67], v[194:197], v[226:229], v[64:67]
	s_barrier
	s_mov_b32 m0, s0
	v_lshl_add_u64 v[142:143], s[68:69], 0, v[80:81]
	ds_read_b128 v[198:201], v147 offset:16384
	ds_read_b128 v[202:205], v147 offset:17408
	ds_read_b128 v[206:209], v147 offset:18432
	ds_read_b128 v[210:213], v147 offset:19456
	ds_read_b128 v[214:217], v147 offset:20480
	ds_read_b128 v[218:221], v147 offset:21504
	ds_read_b128 v[222:225], v147 offset:22528
	ds_read_b128 v[226:229], v147 offset:23552
	global_load_lds_dwordx4 v[142:143], off
	v_lshl_add_u64 v[164:165], s[68:69], 0, v[140:141]
	s_mov_b32 m0, s33
	v_lshl_add_u64 v[168:169], s[70:71], 0, v[80:81]
	global_load_lds_dwordx4 v[164:165], off
	s_mov_b32 m0, s1
	v_lshl_add_u64 v[170:171], s[66:67], 0, v[138:139]
	global_load_lds_dwordx4 v[168:169], off
	v_lshl_add_u64 v[168:169], s[70:71], 0, v[140:141]
	s_mov_b32 m0, s82
	s_nop 0
	global_load_lds_dwordx4 v[168:169], off
	v_lshl_add_u64 v[168:169], s[66:67], 0, v[136:137]
	s_mov_b32 m0, s21
	s_nop 0
	global_load_lds_dwordx4 v[168:169], off
	s_mov_b32 m0, s26
	s_nop 0
	global_load_lds_dwordx4 v[170:171], off
	s_waitcnt vmcnt(8)
	s_waitcnt lgkmcnt(0)
	s_barrier
; #define PG8_STAGE(bufoff, gbase, voff) do { _Pragma("unroll") for (int _i = 0; _i < 2; ++_i) \
;         __builtin_amdgcn_global_load_lds((const unsigned*)((const char*)(gbase) + (voff)[_i]), (LAS unsigned*)(lds + (bufoff) + ldsw + _i * 8192), 16, 0, 0); } while (0)
; #define PG8_LDA(dst, b, h) do { _Pragma("unroll") for (int m = 0; m < 4; ++m) _Pragma("unroll") for (int k = 0; k < 2; ++k) dst[m][k] = *(const LAS bf16x8*)(lds + PG8_SA(b, h) + aoff + m * 2048 + k * 1024); } while (0)
; #define PG8_LDB(dst, b, h) do { _Pragma("unroll") for (int n = 0; n < 2; ++n) _Pragma("unroll") for (int k = 0; k < 2; ++k) dst[n][k] = *(const LAS bf16x8*)(lds + PG8_SB(b, h) + boff + n * 2048 + k * 1024); } while (0)
; #define PG8_MMA(ai, bj, At, Bt) do { __builtin_amdgcn_s_setprio(1); _Pragma("unroll") for (int m = 0; m < 4; ++m) _Pragma("unroll") for (int n = 0; n < 2; ++n) _Pragma("unroll") for (int k = 0; k < 2; ++k) \
;         acc[ai][bj][m][n] = __builtin_amdgcn_mfma_f32_16x16x32_bf16(Bt[n][k], At[m][k], acc[ai][bj][m][n], 0, 0, 0); __builtin_amdgcn_s_setprio(0); } while (0)
; #define PG8_WAIT_V(n) asm volatile("s_waitcnt vmcnt(" #n ")" ::: "memory")
; #define PG8_WAIT_L(n) asm volatile("s_waitcnt lgkmcnt(" #n ")" ::: "memory")
; #define PG8_BAR __builtin_amdgcn_s_barrier()
; #define PG8_SCHED __builtin_amdgcn_sched_barrier(0)
; template <class Epi, bool ALIGN_EPI>
; __device__ __forceinline__ void gemm_phase(LAS unsigned char* lds, const Gemm g, const StaticOrder S, const Epi E) {
;     ...
;             PG8_WAIT_V(8); PG8_WAIT_L(0); PG8_BAR; PG8_MMA(0, 0, At, B0); PG8_MMA(0, 1, At, B1); PG8_BAR; PG8_SCHED;
;             PG8_LDA(At, 0, 1); PG8_STAGE(PG8_SB(0, 0), b2, voffB); PG8_STAGE(PG8_SB(0, 1), b2 + hstepB, voffB); PG8_STAGE(PG8_SA(0, 0), a2, voffA);
;             PG8_WAIT_V(8); PG8_WAIT_L(0); PG8_BAR; PG8_MMA(1, 0, At, B0); PG8_MMA(1, 1, At, B1); PG8_BAR; PG8_SCHED;
;             PG8_LDB(B0, 1, 0); PG8_LDB(B1, 1, 1); PG8_SCHED; PG8_LDA(At, 1, 0); PG8_STAGE(PG8_SA(0, 1), a2 + hstepA, voffA);
;             PG8_WAIT_V(8); PG8_WAIT_L(0); PG8_BAR; PG8_MMA(0, 0, At, B0); PG8_MMA(0, 1, At, B1); PG8_BAR; PG8_SCHED;
	s_waitcnt lgkmcnt(0)
	v_mfma_f32_16x16x32_bf16 v[60:63], v[148:151], v[198:201], v[60:63]
	v_mfma_f32_16x16x32_bf16 v[56:59], v[156:159], v[198:201], v[56:59]
	v_mfma_f32_16x16x32_bf16 v[52:55], v[148:151], v[206:209], v[52:55]
	v_mfma_f32_16x16x32_bf16 v[44:47], v[156:159], v[206:209], v[44:47]
	v_mfma_f32_16x16x32_bf16 v[36:39], v[148:151], v[214:217], v[36:39]
	v_mfma_f32_16x16x32_bf16 v[28:31], v[156:159], v[214:217], v[28:31]
	v_mfma_f32_16x16x32_bf16 v[20:23], v[148:151], v[222:225], v[20:23]
	v_mfma_f32_16x16x32_bf16 v[12:15], v[156:159], v[222:225], v[12:15]
	v_mfma_f32_16x16x32_bf16 v[60:63], v[152:155], v[202:205], v[60:63]
	v_mfma_f32_16x16x32_bf16 v[56:59], v[160:163], v[202:205], v[56:59]
	v_mfma_f32_16x16x32_bf16 v[52:55], v[152:155], v[210:213], v[52:55]
	v_mfma_f32_16x16x32_bf16 v[44:47], v[160:163], v[210:213], v[44:47]
	v_mfma_f32_16x16x32_bf16 v[36:39], v[152:155], v[218:221], v[36:39]
	v_mfma_f32_16x16x32_bf16 v[28:31], v[160:163], v[218:221], v[28:31]
	v_mfma_f32_16x16x32_bf16 v[20:23], v[152:155], v[226:229], v[20:23]
	v_mfma_f32_16x16x32_bf16 v[12:15], v[160:163], v[226:229], v[12:15]
	v_mfma_f32_16x16x32_bf16 v[48:51], v[182:185], v[198:201], v[48:51]
	v_mfma_f32_16x16x32_bf16 v[40:43], v[190:193], v[198:201], v[40:43]
	v_mfma_f32_16x16x32_bf16 v[32:35], v[182:185], v[206:209], v[32:35]
	v_mfma_f32_16x16x32_bf16 v[24:27], v[190:193], v[206:209], v[24:27]
	v_mfma_f32_16x16x32_bf16 v[16:19], v[182:185], v[214:217], v[16:19]
	v_mfma_f32_16x16x32_bf16 v[8:11], v[190:193], v[214:217], v[8:11]
	v_mfma_f32_16x16x32_bf16 v[4:7], v[182:185], v[222:225], v[4:7]
	v_mfma_f32_16x16x32_bf16 v[0:3], v[190:193], v[222:225], v[0:3]
	v_mfma_f32_16x16x32_bf16 v[48:51], v[186:189], v[202:205], v[48:51]
	v_mfma_f32_16x16x32_bf16 v[40:43], v[194:197], v[202:205], v[40:43]
	v_mfma_f32_16x16x32_bf16 v[32:35], v[186:189], v[210:213], v[32:35]
	v_mfma_f32_16x16x32_bf16 v[24:27], v[194:197], v[210:213], v[24:27]
	v_mfma_f32_16x16x32_bf16 v[16:19], v[186:189], v[218:221], v[16:19]
	v_mfma_f32_16x16x32_bf16 v[8:11], v[194:197], v[218:221], v[8:11]
	v_mfma_f32_16x16x32_bf16 v[4:7], v[186:189], v[226:229], v[4:7]
	v_mfma_f32_16x16x32_bf16 v[0:3], v[194:197], v[226:229], v[0:3]
	s_barrier
	v_add_u32_e32 v130, vcc_hi, v146
	ds_read_b128 v[148:151], v130
	ds_read_b128 v[152:155], v130 offset:1024
	ds_read_b128 v[156:159], v130 offset:2048
	ds_read_b128 v[160:163], v130 offset:3072
	v_add_u32_e32 v130, s12, v146
	ds_read_b128 v[182:185], v130
	ds_read_b128 v[186:189], v130 offset:1024
	ds_read_b128 v[190:193], v130 offset:2048
	ds_read_b128 v[194:197], v130 offset:3072
	s_mov_b32 m0, s27
	v_lshl_add_u64 v[172:173], s[64:65], 0, v[136:137]
	ds_read_b128 v[198:201], v147 offset:32768
	ds_read_b128 v[202:205], v147 offset:33792
	ds_read_b128 v[206:209], v147 offset:34816
	ds_read_b128 v[210:213], v147 offset:35840
	ds_read_b128 v[214:217], v147 offset:36864
	ds_read_b128 v[218:221], v147 offset:37888
	ds_read_b128 v[222:225], v147 offset:38912
	ds_read_b128 v[226:229], v147 offset:39936
	global_load_lds_dwordx4 v[172:173], off
	v_lshl_add_u64 v[172:173], s[64:65], 0, v[138:139]
	s_mov_b32 m0, s28
	s_nop 0
	global_load_lds_dwordx4 v[172:173], off
	s_waitcnt vmcnt(8)
	s_waitcnt lgkmcnt(0)
	s_barrier
	s_waitcnt lgkmcnt(0)
	v_mfma_f32_16x16x32_bf16 v[126:129], v[148:151], v[198:201], v[126:129]
	v_mfma_f32_16x16x32_bf16 v[122:125], v[156:159], v[198:201], v[122:125]
	v_mfma_f32_16x16x32_bf16 v[118:121], v[148:151], v[206:209], v[118:121]
	v_mfma_f32_16x16x32_bf16 v[110:113], v[156:159], v[206:209], v[110:113]
	v_mfma_f32_16x16x32_bf16 v[102:105], v[148:151], v[214:217], v[102:105]
	v_mfma_f32_16x16x32_bf16 v[94:97], v[156:159], v[214:217], v[94:97]
	v_mfma_f32_16x16x32_bf16 v[86:89], v[148:151], v[222:225], v[86:89]
	v_mfma_f32_16x16x32_bf16 v[76:79], v[156:159], v[222:225], v[76:79]
	v_mfma_f32_16x16x32_bf16 v[126:129], v[152:155], v[202:205], v[126:129]
	v_mfma_f32_16x16x32_bf16 v[122:125], v[160:163], v[202:205], v[122:125]
	v_mfma_f32_16x16x32_bf16 v[118:121], v[152:155], v[210:213], v[118:121]
	v_mfma_f32_16x16x32_bf16 v[110:113], v[160:163], v[210:213], v[110:113]
	v_mfma_f32_16x16x32_bf16 v[102:105], v[152:155], v[218:221], v[102:105]
	v_mfma_f32_16x16x32_bf16 v[94:97], v[160:163], v[218:221], v[94:97]
	v_mfma_f32_16x16x32_bf16 v[86:89], v[152:155], v[226:229], v[86:89]
	v_mfma_f32_16x16x32_bf16 v[76:79], v[160:163], v[226:229], v[76:79]
	v_mfma_f32_16x16x32_bf16 v[114:117], v[182:185], v[198:201], v[114:117]
	v_mfma_f32_16x16x32_bf16 v[106:109], v[190:193], v[198:201], v[106:109]
	v_mfma_f32_16x16x32_bf16 v[98:101], v[182:185], v[206:209], v[98:101]
	v_mfma_f32_16x16x32_bf16 v[90:93], v[190:193], v[206:209], v[90:93]
	v_mfma_f32_16x16x32_bf16 v[82:85], v[182:185], v[214:217], v[82:85]
	v_mfma_f32_16x16x32_bf16 v[72:75], v[190:193], v[214:217], v[72:75]
	v_mfma_f32_16x16x32_bf16 v[68:71], v[182:185], v[222:225], v[68:71]
	v_mfma_f32_16x16x32_bf16 v[64:67], v[190:193], v[222:225], v[64:67]
	v_mfma_f32_16x16x32_bf16 v[114:117], v[186:189], v[202:205], v[114:117]
	v_mfma_f32_16x16x32_bf16 v[106:109], v[194:197], v[202:205], v[106:109]
	v_mfma_f32_16x16x32_bf16 v[98:101], v[186:189], v[210:213], v[98:101]
	v_mfma_f32_16x16x32_bf16 v[90:93], v[194:197], v[210:213], v[90:93]
	v_mfma_f32_16x16x32_bf16 v[82:85], v[186:189], v[218:221], v[82:85]
	v_mfma_f32_16x16x32_bf16 v[72:75], v[194:197], v[218:221], v[72:75]
	v_mfma_f32_16x16x32_bf16 v[68:71], v[186:189], v[226:229], v[68:71]
	v_mfma_f32_16x16x32_bf16 v[64:67], v[194:197], v[226:229], v[64:67]
	s_barrier
; #define PG8_STAGE(bufoff, gbase, voff) do { _Pragma("unroll") for (int _i = 0; _i < 2; ++_i) \
;         __builtin_amdgcn_global_load_lds((const unsigned*)((const char*)(gbase) + (voff)[_i]), (LAS unsigned*)(lds + (bufoff) + ldsw + _i * 8192), 16, 0, 0); } while (0)
; #define PG8_LDA(dst, b, h) do { _Pragma("unroll") for (int m = 0; m < 4; ++m) _Pragma("unroll") for (int k = 0; k < 2; ++k) dst[m][k] = *(const LAS bf16x8*)(lds + PG8_SA(b, h) + aoff + m * 2048 + k * 1024); } while (0)
; #define PG8_MMA(ai, bj, At, Bt) do { __builtin_amdgcn_s_setprio(1); _Pragma("unroll") for (int m = 0; m < 4; ++m) _Pragma("unroll") for (int n = 0; n < 2; ++n) _Pragma("unroll") for (int k = 0; k < 2; ++k) \
;         acc[ai][bj][m][n] = __builtin_amdgcn_mfma_f32_16x16x32_bf16(Bt[n][k], At[m][k], acc[ai][bj][m][n], 0, 0, 0); __builtin_amdgcn_s_setprio(0); } while (0)
; #define PG8_WAIT_V(n) asm volatile("s_waitcnt vmcnt(" #n ")" ::: "memory")
; #define PG8_WAIT_L(n) asm volatile("s_waitcnt lgkmcnt(" #n ")" ::: "memory")
; #define PG8_BAR __builtin_amdgcn_s_barrier()
; #define PG8_SCHED __builtin_amdgcn_sched_barrier(0)
; template <class Epi, bool ALIGN_EPI>
; __device__ __forceinline__ void gemm_phase(LAS unsigned char* lds, const Gemm g, const StaticOrder S, const Epi E) {
;     ...
;             PG8_WAIT_V(8); PG8_WAIT_L(0); PG8_BAR; PG8_MMA(0, 0, At, B0); PG8_MMA(0, 1, At, B1); PG8_BAR; PG8_SCHED;
;             PG8_LDA(At, 1, 1); PG8_STAGE(PG8_SB(1, 0), b3, voffB); PG8_STAGE(PG8_SB(1, 1), b3 + hstepB, voffB); PG8_STAGE(PG8_SA(1, 0), a3, voffA);
;             PG8_WAIT_V(8); PG8_WAIT_L(0); PG8_BAR; PG8_MMA(1, 0, At, B0); PG8_MMA(1, 1, At, B1); PG8_BAR; PG8_SCHED;
;         }
;         if constexpr (ALIGN_EPI) { if (wr == 0) PG8_BAR; }
	s_mov_b32 m0, vcc_lo
	v_lshl_add_u64 v[142:143], v[142:143], 0, s[80:81]
	ds_read_b128 v[198:201], v147 offset:49152
	ds_read_b128 v[202:205], v147 offset:50176
	ds_read_b128 v[206:209], v147 offset:51200
	ds_read_b128 v[210:213], v147 offset:52224
	ds_read_b128 v[214:217], v147 offset:53248
	ds_read_b128 v[218:221], v147 offset:54272
	ds_read_b128 v[222:225], v147 offset:55296
	ds_read_b128 v[226:229], v147 offset:56320
	global_load_lds_dwordx4 v[142:143], off
	v_lshl_add_u64 v[142:143], v[164:165], 0, s[80:81]
	s_mov_b32 m0, s18
	s_nop 0
	global_load_lds_dwordx4 v[142:143], off
	v_lshl_add_u64 v[142:143], s[62:63], 0, v[80:81]
	s_mov_b32 m0, s15
	s_nop 0
	global_load_lds_dwordx4 v[142:143], off
	v_lshl_add_u64 v[142:143], s[62:63], 0, v[140:141]
	s_mov_b32 m0, s16
	s_nop 0
	global_load_lds_dwordx4 v[142:143], off
	v_lshl_add_u64 v[142:143], v[168:169], 0, s[80:81]
	s_mov_b32 m0, s31
	s_nop 0
	global_load_lds_dwordx4 v[142:143], off
	v_lshl_add_u64 v[142:143], v[170:171], 0, s[80:81]
	s_mov_b32 m0, s61
	s_nop 0
	global_load_lds_dwordx4 v[142:143], off
	s_waitcnt vmcnt(8)
	s_waitcnt lgkmcnt(0)
	s_barrier
	s_waitcnt lgkmcnt(0)
	v_mfma_f32_16x16x32_bf16 v[60:63], v[148:151], v[198:201], v[60:63]
	v_mfma_f32_16x16x32_bf16 v[56:59], v[156:159], v[198:201], v[56:59]
	v_mfma_f32_16x16x32_bf16 v[52:55], v[148:151], v[206:209], v[52:55]
	v_mfma_f32_16x16x32_bf16 v[44:47], v[156:159], v[206:209], v[44:47]
	v_mfma_f32_16x16x32_bf16 v[36:39], v[148:151], v[214:217], v[36:39]
	v_mfma_f32_16x16x32_bf16 v[28:31], v[156:159], v[214:217], v[28:31]
	v_mfma_f32_16x16x32_bf16 v[20:23], v[148:151], v[222:225], v[20:23]
	v_mfma_f32_16x16x32_bf16 v[12:15], v[156:159], v[222:225], v[12:15]
	v_mfma_f32_16x16x32_bf16 v[60:63], v[152:155], v[202:205], v[60:63]
	v_mfma_f32_16x16x32_bf16 v[56:59], v[160:163], v[202:205], v[56:59]
	v_mfma_f32_16x16x32_bf16 v[52:55], v[152:155], v[210:213], v[52:55]
	v_mfma_f32_16x16x32_bf16 v[44:47], v[160:163], v[210:213], v[44:47]
	v_mfma_f32_16x16x32_bf16 v[36:39], v[152:155], v[218:221], v[36:39]
	v_mfma_f32_16x16x32_bf16 v[28:31], v[160:163], v[218:221], v[28:31]
	v_mfma_f32_16x16x32_bf16 v[20:23], v[152:155], v[226:229], v[20:23]
	v_mfma_f32_16x16x32_bf16 v[12:15], v[160:163], v[226:229], v[12:15]
	v_mfma_f32_16x16x32_bf16 v[48:51], v[182:185], v[198:201], v[48:51]
	v_mfma_f32_16x16x32_bf16 v[40:43], v[190:193], v[198:201], v[40:43]
	v_mfma_f32_16x16x32_bf16 v[32:35], v[182:185], v[206:209], v[32:35]
	v_mfma_f32_16x16x32_bf16 v[24:27], v[190:193], v[206:209], v[24:27]
	v_mfma_f32_16x16x32_bf16 v[16:19], v[182:185], v[214:217], v[16:19]
	v_mfma_f32_16x16x32_bf16 v[8:11], v[190:193], v[214:217], v[8:11]
	v_mfma_f32_16x16x32_bf16 v[4:7], v[182:185], v[222:225], v[4:7]
	v_mfma_f32_16x16x32_bf16 v[0:3], v[190:193], v[222:225], v[0:3]
	v_mfma_f32_16x16x32_bf16 v[48:51], v[186:189], v[202:205], v[48:51]
	v_mfma_f32_16x16x32_bf16 v[40:43], v[194:197], v[202:205], v[40:43]
	v_mfma_f32_16x16x32_bf16 v[32:35], v[186:189], v[210:213], v[32:35]
	v_mfma_f32_16x16x32_bf16 v[24:27], v[194:197], v[210:213], v[24:27]
	v_mfma_f32_16x16x32_bf16 v[16:19], v[186:189], v[218:221], v[16:19]
	v_mfma_f32_16x16x32_bf16 v[8:11], v[194:197], v[218:221], v[8:11]
	v_mfma_f32_16x16x32_bf16 v[4:7], v[186:189], v[226:229], v[4:7]
	v_mfma_f32_16x16x32_bf16 v[0:3], v[194:197], v[226:229], v[0:3]
	s_barrier
	s_andn2_b64 vcc, exec, s[42:43]
	s_mov_b64 s[62:63], -1
	s_mov_b64 s[42:43], 0
	s_mov_b64 s[64:65], 0x100
	s_cbranch_vccz .LBB0_1815
	s_and_b64 vcc, exec, s[44:45]
	s_cbranch_vccz .LBB0_1818
	s_barrier

; #define PG8_STAGE(bufoff, gbase, voff) do { _Pragma("unroll") for (int _i = 0; _i < 2; ++_i) \
;         __builtin_amdgcn_global_load_lds((const unsigned*)((const char*)(gbase) + (voff)[_i]), (LAS unsigned*)(lds + (bufoff) + ldsw + _i * 8192), 16, 0, 0); } while (0)
; #define PG8_LDA(dst, b, h) do { _Pragma("unroll") for (int m = 0; m < 4; ++m) _Pragma("unroll") for (int k = 0; k < 2; ++k) dst[m][k] = *(const LAS bf16x8*)(lds + PG8_SA(b, h) + aoff + m * 2048 + k * 1024); } while (0)
; #define PG8_LDB(dst, b, h) do { _Pragma("unroll") for (int n = 0; n < 2; ++n) _Pragma("unroll") for (int k = 0; k < 2; ++k) dst[n][k] = *(const LAS bf16x8*)(lds + PG8_SB(b, h) + boff + n * 2048 + k * 1024); } while (0)
; #define PG8_MMA(ai, bj, At, Bt) do { __builtin_amdgcn_s_setprio(1); _Pragma("unroll") for (int m = 0; m < 4; ++m) _Pragma("unroll") for (int n = 0; n < 2; ++n) _Pragma("unroll") for (int k = 0; k < 2; ++k) \
;         acc[ai][bj][m][n] = __builtin_amdgcn_mfma_f32_16x16x32_bf16(Bt[n][k], At[m][k], acc[ai][bj][m][n], 0, 0, 0); __builtin_amdgcn_s_setprio(0); } while (0)
; #define PG8_WAIT_V(n) asm volatile("s_waitcnt vmcnt(" #n ")" ::: "memory")
; #define PG8_WAIT_L(n) asm volatile("s_waitcnt lgkmcnt(" #n ")" ::: "memory")
; #define PG8_BAR __builtin_amdgcn_s_barrier()
; #define PG8_SCHED __builtin_amdgcn_sched_barrier(0)
; template <class Epi, bool ALIGN_EPI>
; __device__ __forceinline__ void gemm_phase(LAS unsigned char* lds, const Gemm g, const StaticOrder S, const Epi E) {
;     ...
;         for (int t = 0; t < nt; t += 2) {
;             const bool last = (t == nt - 2);
;             const char* a1 = cA + (size_t)(t + 1) * kstep;
;             const char* a2 = last ? nA : cA + (size_t)(t + 2) * kstep; const char* b2 = last ? nB : cB + (size_t)(t + 2) * kstep;
;             const char* a3 = a2 + kstep; const char* b3 = b2 + kstep;
;             PG8_LDB(B0, 0, 0); PG8_LDB(B1, 0, 1); PG8_SCHED; PG8_LDA(At, 0, 0); PG8_STAGE(PG8_SA(1, 1), a1 + hstepA, voffA);
;             PG8_WAIT_V(8); PG8_WAIT_L(0); PG8_BAR; PG8_MMA(0, 0, At, B0); PG8_MMA(0, 1, At, B1); PG8_BAR; PG8_SCHED;
;             PG8_LDA(At, 0, 1); PG8_STAGE(PG8_SB(0, 0), b2, voffB); PG8_STAGE(PG8_SB(0, 1), b2 + hstepB, voffB); PG8_STAGE(PG8_SA(0, 0), a2, voffA);
;             PG8_WAIT_V(8); PG8_WAIT_L(0); PG8_BAR; PG8_MMA(1, 0, At, B0); PG8_MMA(1, 1, At, B1); PG8_BAR; PG8_SCHED;
.LBB0_2015:
	s_add_u32 s42, s54, 0x100
	s_addc_u32 s43, s55, 0
	s_add_i32 s0, 0, 0x10000
	s_cmp_eq_u32 s71, 12
	s_cselect_b32 s65, s49, s43
	s_cselect_b32 s64, s48, s42
	v_add_u32_e32 v130, s0, v152
	s_cselect_b32 s63, s34, s53
	s_cselect_b32 s62, s35, s47
	s_add_i32 s12, 0, 0x14000
	ds_read_b128 v[146:149], v130
	ds_read_b128 v[154:157], v130 offset:1024
	ds_read_b128 v[158:161], v130 offset:2048
	ds_read_b128 v[162:165], v130 offset:3072
	v_add_u32_e32 v130, s12, v152
	ds_read_b128 v[182:185], v130
	ds_read_b128 v[186:189], v130 offset:1024
	ds_read_b128 v[190:193], v130 offset:2048
	ds_read_b128 v[194:197], v130 offset:3072
	v_lshl_add_u64 v[168:169], s[54:55], 0, v[142:143]
	s_add_i32 m0, s27, 0xc000
	ds_read_b128 v[198:201], v153
	ds_read_b128 v[202:205], v153 offset:1024
	ds_read_b128 v[206:209], v153 offset:2048
	ds_read_b128 v[210:213], v153 offset:3072
	ds_read_b128 v[214:217], v153 offset:4096
	ds_read_b128 v[218:221], v153 offset:5120
	ds_read_b128 v[222:225], v153 offset:6144
	ds_read_b128 v[226:229], v153 offset:7168
	global_load_lds_dwordx4 v[168:169], off
	v_lshl_add_u64 v[168:169], s[54:55], 0, v[144:145]
	s_add_i32 m0, s27, 0xe000
	s_nop 0
	global_load_lds_dwordx4 v[168:169], off
	s_waitcnt vmcnt(8)
	s_waitcnt lgkmcnt(0)
	s_barrier
	s_waitcnt lgkmcnt(0)
	v_mfma_f32_16x16x32_bf16 v[126:129], v[146:149], v[198:201], v[126:129]
	v_mfma_f32_16x16x32_bf16 v[122:125], v[158:161], v[198:201], v[122:125]
	v_mfma_f32_16x16x32_bf16 v[110:113], v[146:149], v[206:209], v[110:113]
	v_mfma_f32_16x16x32_bf16 v[106:109], v[158:161], v[206:209], v[106:109]
	v_mfma_f32_16x16x32_bf16 v[94:97], v[146:149], v[214:217], v[94:97]
	v_mfma_f32_16x16x32_bf16 v[90:93], v[158:161], v[214:217], v[90:93]
	v_mfma_f32_16x16x32_bf16 v[76:79], v[146:149], v[222:225], v[76:79]
	v_mfma_f32_16x16x32_bf16 v[72:75], v[158:161], v[222:225], v[72:75]
	v_mfma_f32_16x16x32_bf16 v[126:129], v[154:157], v[202:205], v[126:129]
	v_mfma_f32_16x16x32_bf16 v[122:125], v[162:165], v[202:205], v[122:125]
	v_mfma_f32_16x16x32_bf16 v[110:113], v[154:157], v[210:213], v[110:113]
	v_mfma_f32_16x16x32_bf16 v[106:109], v[162:165], v[210:213], v[106:109]
	v_mfma_f32_16x16x32_bf16 v[94:97], v[154:157], v[218:221], v[94:97]
	v_mfma_f32_16x16x32_bf16 v[90:93], v[162:165], v[218:221], v[90:93]
	v_mfma_f32_16x16x32_bf16 v[76:79], v[154:157], v[226:229], v[76:79]
	v_mfma_f32_16x16x32_bf16 v[72:75], v[162:165], v[226:229], v[72:75]
	v_mfma_f32_16x16x32_bf16 v[118:121], v[182:185], v[198:201], v[118:121]
	v_mfma_f32_16x16x32_bf16 v[114:117], v[190:193], v[198:201], v[114:117]
	v_mfma_f32_16x16x32_bf16 v[102:105], v[182:185], v[206:209], v[102:105]
	v_mfma_f32_16x16x32_bf16 v[98:101], v[190:193], v[206:209], v[98:101]
	v_mfma_f32_16x16x32_bf16 v[86:89], v[182:185], v[214:217], v[86:89]
	v_mfma_f32_16x16x32_bf16 v[82:85], v[190:193], v[214:217], v[82:85]
	v_mfma_f32_16x16x32_bf16 v[68:71], v[182:185], v[222:225], v[68:71]
	v_mfma_f32_16x16x32_bf16 v[64:67], v[190:193], v[222:225], v[64:67]
	v_mfma_f32_16x16x32_bf16 v[118:121], v[186:189], v[202:205], v[118:121]
	v_mfma_f32_16x16x32_bf16 v[114:117], v[194:197], v[202:205], v[114:117]
	v_mfma_f32_16x16x32_bf16 v[102:105], v[186:189], v[210:213], v[102:105]
	v_mfma_f32_16x16x32_bf16 v[98:101], v[194:197], v[210:213], v[98:101]
	v_mfma_f32_16x16x32_bf16 v[86:89], v[186:189], v[218:221], v[86:89]
	v_mfma_f32_16x16x32_bf16 v[82:85], v[194:197], v[218:221], v[82:85]
	v_mfma_f32_16x16x32_bf16 v[68:71], v[186:189], v[226:229], v[68:71]
	v_mfma_f32_16x16x32_bf16 v[64:67], v[194:197], v[226:229], v[64:67]
	s_barrier
	s_add_i32 s0, s0, s26
	v_lshl_add_u64 v[168:169], s[62:63], 0, v[80:81]
	s_mov_b32 m0, s0
	ds_read_b128 v[198:201], v153 offset:16384
	ds_read_b128 v[202:205], v153 offset:17408
	ds_read_b128 v[206:209], v153 offset:18432
	ds_read_b128 v[210:213], v153 offset:19456
	ds_read_b128 v[214:217], v153 offset:20480
	ds_read_b128 v[218:221], v153 offset:21504
	ds_read_b128 v[222:225], v153 offset:22528
	ds_read_b128 v[226:229], v153 offset:23552
	global_load_lds_dwordx4 v[168:169], off
	s_add_i32 m0, s0, 0x2000
	s_add_u32 s0, s62, 0x40000
	v_lshl_add_u64 v[170:171], s[62:63], 0, v[140:141]
	s_addc_u32 s1, s63, 0
	s_add_i32 s12, s12, s26
	global_load_lds_dwordx4 v[170:171], off
	v_lshl_add_u64 v[172:173], s[0:1], 0, v[80:81]
	s_mov_b32 m0, s12
	v_lshl_add_u64 v[176:177], s[64:65], 0, v[138:139]
	global_load_lds_dwordx4 v[172:173], off
	v_lshl_add_u64 v[172:173], s[0:1], 0, v[140:141]
	s_add_i32 m0, s12, 0x2000
	s_nop 0
	global_load_lds_dwordx4 v[172:173], off
	v_lshl_add_u64 v[172:173], s[64:65], 0, v[136:137]
	s_mov_b32 m0, s27
	s_nop 0
	global_load_lds_dwordx4 v[172:173], off
	s_mov_b32 m0, s28
	s_nop 0
	global_load_lds_dwordx4 v[176:177], off
	s_waitcnt vmcnt(8)
	s_waitcnt lgkmcnt(0)
	s_barrier
; #define PG8_STAGE(bufoff, gbase, voff) do { _Pragma("unroll") for (int _i = 0; _i < 2; ++_i) \
;         __builtin_amdgcn_global_load_lds((const unsigned*)((const char*)(gbase) + (voff)[_i]), (LAS unsigned*)(lds + (bufoff) + ldsw + _i * 8192), 16, 0, 0); } while (0)
; #define PG8_LDA(dst, b, h) do { _Pragma("unroll") for (int m = 0; m < 4; ++m) _Pragma("unroll") for (int k = 0; k < 2; ++k) dst[m][k] = *(const LAS bf16x8*)(lds + PG8_SA(b, h) + aoff + m * 2048 + k * 1024); } while (0)
; #define PG8_LDB(dst, b, h) do { _Pragma("unroll") for (int n = 0; n < 2; ++n) _Pragma("unroll") for (int k = 0; k < 2; ++k) dst[n][k] = *(const LAS bf16x8*)(lds + PG8_SB(b, h) + boff + n * 2048 + k * 1024); } while (0)
; #define PG8_MMA(ai, bj, At, Bt) do { __builtin_amdgcn_s_setprio(1); _Pragma("unroll") for (int m = 0; m < 4; ++m) _Pragma("unroll") for (int n = 0; n < 2; ++n) _Pragma("unroll") for (int k = 0; k < 2; ++k) \
;         acc[ai][bj][m][n] = __builtin_amdgcn_mfma_f32_16x16x32_bf16(Bt[n][k], At[m][k], acc[ai][bj][m][n], 0, 0, 0); __builtin_amdgcn_s_setprio(0); } while (0)
; #define PG8_WAIT_V(n) asm volatile("s_waitcnt vmcnt(" #n ")" ::: "memory")
; #define PG8_WAIT_L(n) asm volatile("s_waitcnt lgkmcnt(" #n ")" ::: "memory")
; #define PG8_BAR __builtin_amdgcn_s_barrier()
; #define PG8_SCHED __builtin_amdgcn_sched_barrier(0)
; template <class Epi, bool ALIGN_EPI>
; __device__ __forceinline__ void gemm_phase(LAS unsigned char* lds, const Gemm g, const StaticOrder S, const Epi E) {
;     ...
;             PG8_WAIT_V(8); PG8_WAIT_L(0); PG8_BAR; PG8_MMA(1, 0, At, B0); PG8_MMA(1, 1, At, B1); PG8_BAR; PG8_SCHED;
;             PG8_LDB(B0, 1, 0); PG8_LDB(B1, 1, 1); PG8_SCHED; PG8_LDA(At, 1, 0); PG8_STAGE(PG8_SA(0, 1), a2 + hstepA, voffA);
;             PG8_WAIT_V(8); PG8_WAIT_L(0); PG8_BAR; PG8_MMA(0, 0, At, B0); PG8_MMA(0, 1, At, B1); PG8_BAR; PG8_SCHED;
	s_waitcnt lgkmcnt(0)
	v_mfma_f32_16x16x32_bf16 v[60:63], v[146:149], v[198:201], v[60:63]
	v_mfma_f32_16x16x32_bf16 v[56:59], v[158:161], v[198:201], v[56:59]
	v_mfma_f32_16x16x32_bf16 v[44:47], v[146:149], v[206:209], v[44:47]
	v_mfma_f32_16x16x32_bf16 v[40:43], v[158:161], v[206:209], v[40:43]
	v_mfma_f32_16x16x32_bf16 v[28:31], v[146:149], v[214:217], v[28:31]
	v_mfma_f32_16x16x32_bf16 v[24:27], v[158:161], v[214:217], v[24:27]
	v_mfma_f32_16x16x32_bf16 v[12:15], v[146:149], v[222:225], v[12:15]
	v_mfma_f32_16x16x32_bf16 v[8:11], v[158:161], v[222:225], v[8:11]
	v_mfma_f32_16x16x32_bf16 v[60:63], v[154:157], v[202:205], v[60:63]
	v_mfma_f32_16x16x32_bf16 v[56:59], v[162:165], v[202:205], v[56:59]
	v_mfma_f32_16x16x32_bf16 v[44:47], v[154:157], v[210:213], v[44:47]
	v_mfma_f32_16x16x32_bf16 v[40:43], v[162:165], v[210:213], v[40:43]
	v_mfma_f32_16x16x32_bf16 v[28:31], v[154:157], v[218:221], v[28:31]
	v_mfma_f32_16x16x32_bf16 v[24:27], v[162:165], v[218:221], v[24:27]
	v_mfma_f32_16x16x32_bf16 v[12:15], v[154:157], v[226:229], v[12:15]
	v_mfma_f32_16x16x32_bf16 v[8:11], v[162:165], v[226:229], v[8:11]
	v_mfma_f32_16x16x32_bf16 v[52:55], v[182:185], v[198:201], v[52:55]
	v_mfma_f32_16x16x32_bf16 v[48:51], v[190:193], v[198:201], v[48:51]
	v_mfma_f32_16x16x32_bf16 v[36:39], v[182:185], v[206:209], v[36:39]
	v_mfma_f32_16x16x32_bf16 v[32:35], v[190:193], v[206:209], v[32:35]
	v_mfma_f32_16x16x32_bf16 v[20:23], v[182:185], v[214:217], v[20:23]
	v_mfma_f32_16x16x32_bf16 v[16:19], v[190:193], v[214:217], v[16:19]
	v_mfma_f32_16x16x32_bf16 v[4:7], v[182:185], v[222:225], v[4:7]
	v_mfma_f32_16x16x32_bf16 v[0:3], v[190:193], v[222:225], v[0:3]
	v_mfma_f32_16x16x32_bf16 v[52:55], v[186:189], v[202:205], v[52:55]
	v_mfma_f32_16x16x32_bf16 v[48:51], v[194:197], v[202:205], v[48:51]
	v_mfma_f32_16x16x32_bf16 v[36:39], v[186:189], v[210:213], v[36:39]
	v_mfma_f32_16x16x32_bf16 v[32:35], v[194:197], v[210:213], v[32:35]
	v_mfma_f32_16x16x32_bf16 v[20:23], v[186:189], v[218:221], v[20:23]
	v_mfma_f32_16x16x32_bf16 v[16:19], v[194:197], v[218:221], v[16:19]
	v_mfma_f32_16x16x32_bf16 v[4:7], v[186:189], v[226:229], v[4:7]
	v_mfma_f32_16x16x32_bf16 v[0:3], v[194:197], v[226:229], v[0:3]
	s_barrier
	s_add_i32 s12, 0, 0x18000
	v_add_u32_e32 v130, s12, v152
	s_add_i32 s15, 0, 0x1c000
	ds_read_b128 v[146:149], v130
	ds_read_b128 v[154:157], v130 offset:1024
	ds_read_b128 v[158:161], v130 offset:2048
	ds_read_b128 v[162:165], v130 offset:3072
	v_add_u32_e32 v130, s15, v152
	ds_read_b128 v[182:185], v130
	ds_read_b128 v[186:189], v130 offset:1024
	ds_read_b128 v[190:193], v130 offset:2048
	ds_read_b128 v[194:197], v130 offset:3072
	s_add_u32 s0, s64, 0xb0000
	s_addc_u32 s1, s65, 0
	s_mov_b32 m0, s29
	v_lshl_add_u64 v[178:179], s[0:1], 0, v[136:137]
	ds_read_b128 v[198:201], v153 offset:32768
	ds_read_b128 v[202:205], v153 offset:33792
	ds_read_b128 v[206:209], v153 offset:34816
	ds_read_b128 v[210:213], v153 offset:35840
	ds_read_b128 v[214:217], v153 offset:36864
	ds_read_b128 v[218:221], v153 offset:37888
	ds_read_b128 v[222:225], v153 offset:38912
	ds_read_b128 v[226:229], v153 offset:39936
	global_load_lds_dwordx4 v[178:179], off
	v_lshl_add_u64 v[178:179], s[0:1], 0, v[138:139]
	s_mov_b32 m0, s30
	s_nop 0
	global_load_lds_dwordx4 v[178:179], off
	s_waitcnt vmcnt(8)
	s_waitcnt lgkmcnt(0)
	s_barrier
	s_waitcnt lgkmcnt(0)
	v_mfma_f32_16x16x32_bf16 v[126:129], v[146:149], v[198:201], v[126:129]
	v_mfma_f32_16x16x32_bf16 v[122:125], v[158:161], v[198:201], v[122:125]
	v_mfma_f32_16x16x32_bf16 v[110:113], v[146:149], v[206:209], v[110:113]
	v_mfma_f32_16x16x32_bf16 v[106:109], v[158:161], v[206:209], v[106:109]
	v_mfma_f32_16x16x32_bf16 v[94:97], v[146:149], v[214:217], v[94:97]
	v_mfma_f32_16x16x32_bf16 v[90:93], v[158:161], v[214:217], v[90:93]
	v_mfma_f32_16x16x32_bf16 v[76:79], v[146:149], v[222:225], v[76:79]
	v_mfma_f32_16x16x32_bf16 v[72:75], v[158:161], v[222:225], v[72:75]
	v_mfma_f32_16x16x32_bf16 v[126:129], v[154:157], v[202:205], v[126:129]
	v_mfma_f32_16x16x32_bf16 v[122:125], v[162:165], v[202:205], v[122:125]
	v_mfma_f32_16x16x32_bf16 v[110:113], v[154:157], v[210:213], v[110:113]
	v_mfma_f32_16x16x32_bf16 v[106:109], v[162:165], v[210:213], v[106:109]
	v_mfma_f32_16x16x32_bf16 v[94:97], v[154:157], v[218:221], v[94:97]
	v_mfma_f32_16x16x32_bf16 v[90:93], v[162:165], v[218:221], v[90:93]
	v_mfma_f32_16x16x32_bf16 v[76:79], v[154:157], v[226:229], v[76:79]
	v_mfma_f32_16x16x32_bf16 v[72:75], v[162:165], v[226:229], v[72:75]
	v_mfma_f32_16x16x32_bf16 v[118:121], v[182:185], v[198:201], v[118:121]
	v_mfma_f32_16x16x32_bf16 v[114:117], v[190:193], v[198:201], v[114:117]
	v_mfma_f32_16x16x32_bf16 v[102:105], v[182:185], v[206:209], v[102:105]
	v_mfma_f32_16x16x32_bf16 v[98:101], v[190:193], v[206:209], v[98:101]
	v_mfma_f32_16x16x32_bf16 v[86:89], v[182:185], v[214:217], v[86:89]
	v_mfma_f32_16x16x32_bf16 v[82:85], v[190:193], v[214:217], v[82:85]
	v_mfma_f32_16x16x32_bf16 v[68:71], v[182:185], v[222:225], v[68:71]
	v_mfma_f32_16x16x32_bf16 v[64:67], v[190:193], v[222:225], v[64:67]
	v_mfma_f32_16x16x32_bf16 v[118:121], v[186:189], v[202:205], v[118:121]
	v_mfma_f32_16x16x32_bf16 v[114:117], v[194:197], v[202:205], v[114:117]
	v_mfma_f32_16x16x32_bf16 v[102:105], v[186:189], v[210:213], v[102:105]
	v_mfma_f32_16x16x32_bf16 v[98:101], v[194:197], v[210:213], v[98:101]
	v_mfma_f32_16x16x32_bf16 v[86:89], v[186:189], v[218:221], v[86:89]
	v_mfma_f32_16x16x32_bf16 v[82:85], v[194:197], v[218:221], v[82:85]
	v_mfma_f32_16x16x32_bf16 v[68:71], v[186:189], v[226:229], v[68:71]
	v_mfma_f32_16x16x32_bf16 v[64:67], v[194:197], v[226:229], v[64:67]
	s_barrier
; #define PG8_STAGE(bufoff, gbase, voff) do { _Pragma("unroll") for (int _i = 0; _i < 2; ++_i) \
;         __builtin_amdgcn_global_load_lds((const unsigned*)((const char*)(gbase) + (voff)[_i]), (LAS unsigned*)(lds + (bufoff) + ldsw + _i * 8192), 16, 0, 0); } while (0)
; #define PG8_LDA(dst, b, h) do { _Pragma("unroll") for (int m = 0; m < 4; ++m) _Pragma("unroll") for (int k = 0; k < 2; ++k) dst[m][k] = *(const LAS bf16x8*)(lds + PG8_SA(b, h) + aoff + m * 2048 + k * 1024); } while (0)
; #define PG8_MMA(ai, bj, At, Bt) do { __builtin_amdgcn_s_setprio(1); _Pragma("unroll") for (int m = 0; m < 4; ++m) _Pragma("unroll") for (int n = 0; n < 2; ++n) _Pragma("unroll") for (int k = 0; k < 2; ++k) \
;         acc[ai][bj][m][n] = __builtin_amdgcn_mfma_f32_16x16x32_bf16(Bt[n][k], At[m][k], acc[ai][bj][m][n], 0, 0, 0); __builtin_amdgcn_s_setprio(0); } while (0)
; #define PG8_WAIT_V(n) asm volatile("s_waitcnt vmcnt(" #n ")" ::: "memory")
; #define PG8_WAIT_L(n) asm volatile("s_waitcnt lgkmcnt(" #n ")" ::: "memory")
; #define PG8_BAR __builtin_amdgcn_s_barrier()
; #define PG8_SCHED __builtin_amdgcn_sched_barrier(0)
; template <class Epi, bool ALIGN_EPI>
; __device__ __forceinline__ void gemm_phase(LAS unsigned char* lds, const Gemm g, const StaticOrder S, const Epi E) {
;     ...
;             PG8_LDA(At, 1, 1); PG8_STAGE(PG8_SB(1, 0), b3, voffB); PG8_STAGE(PG8_SB(1, 1), b3 + hstepB, voffB); PG8_STAGE(PG8_SA(1, 0), a3, voffA);
;             PG8_WAIT_V(8); PG8_WAIT_L(0); PG8_BAR; PG8_MMA(1, 0, At, B0); PG8_MMA(1, 1, At, B1); PG8_BAR; PG8_SCHED;
;         }
;         if constexpr (ALIGN_EPI) { if (wr == 0) PG8_BAR; }
	s_add_i32 s0, s12, s26
	v_lshl_add_u64 v[168:169], v[168:169], 0, s[80:81]
	s_mov_b32 m0, s0
	ds_read_b128 v[198:201], v153 offset:49152
	ds_read_b128 v[202:205], v153 offset:50176
	ds_read_b128 v[206:209], v153 offset:51200
	ds_read_b128 v[210:213], v153 offset:52224
	ds_read_b128 v[214:217], v153 offset:53248
	ds_read_b128 v[218:221], v153 offset:54272
	ds_read_b128 v[222:225], v153 offset:55296
	ds_read_b128 v[226:229], v153 offset:56320
	global_load_lds_dwordx4 v[168:169], off
	s_add_i32 m0, s0, 0x2000
	s_add_u32 s0, s62, 0x40080
	v_lshl_add_u64 v[168:169], v[170:171], 0, s[80:81]
	s_addc_u32 s1, s63, 0
	s_add_i32 s12, s15, s26
	global_load_lds_dwordx4 v[168:169], off
	v_lshl_add_u64 v[168:169], s[0:1], 0, v[80:81]
	s_mov_b32 m0, s12
	s_nop 0
	global_load_lds_dwordx4 v[168:169], off
	v_lshl_add_u64 v[168:169], s[0:1], 0, v[140:141]
	s_add_i32 m0, s12, 0x2000
	s_nop 0
	global_load_lds_dwordx4 v[168:169], off
	v_lshl_add_u64 v[168:169], v[172:173], 0, s[80:81]
	s_mov_b32 m0, s67
	s_nop 0
	global_load_lds_dwordx4 v[168:169], off
	v_lshl_add_u64 v[168:169], v[176:177], 0, s[80:81]
	s_mov_b32 m0, s68
	s_nop 0
	global_load_lds_dwordx4 v[168:169], off
	s_waitcnt vmcnt(8)
	s_waitcnt lgkmcnt(0)
	s_barrier
	s_waitcnt lgkmcnt(0)
	v_mfma_f32_16x16x32_bf16 v[60:63], v[146:149], v[198:201], v[60:63]
	v_mfma_f32_16x16x32_bf16 v[56:59], v[158:161], v[198:201], v[56:59]
	v_mfma_f32_16x16x32_bf16 v[44:47], v[146:149], v[206:209], v[44:47]
	v_mfma_f32_16x16x32_bf16 v[40:43], v[158:161], v[206:209], v[40:43]
	v_mfma_f32_16x16x32_bf16 v[28:31], v[146:149], v[214:217], v[28:31]
	v_mfma_f32_16x16x32_bf16 v[24:27], v[158:161], v[214:217], v[24:27]
	v_mfma_f32_16x16x32_bf16 v[12:15], v[146:149], v[222:225], v[12:15]
	v_mfma_f32_16x16x32_bf16 v[8:11], v[158:161], v[222:225], v[8:11]
	v_mfma_f32_16x16x32_bf16 v[60:63], v[154:157], v[202:205], v[60:63]
	v_mfma_f32_16x16x32_bf16 v[56:59], v[162:165], v[202:205], v[56:59]
	v_mfma_f32_16x16x32_bf16 v[44:47], v[154:157], v[210:213], v[44:47]
	v_mfma_f32_16x16x32_bf16 v[40:43], v[162:165], v[210:213], v[40:43]
	v_mfma_f32_16x16x32_bf16 v[28:31], v[154:157], v[218:221], v[28:31]
	v_mfma_f32_16x16x32_bf16 v[24:27], v[162:165], v[218:221], v[24:27]
	v_mfma_f32_16x16x32_bf16 v[12:15], v[154:157], v[226:229], v[12:15]
	v_mfma_f32_16x16x32_bf16 v[8:11], v[162:165], v[226:229], v[8:11]
	v_mfma_f32_16x16x32_bf16 v[52:55], v[182:185], v[198:201], v[52:55]
	v_mfma_f32_16x16x32_bf16 v[48:51], v[190:193], v[198:201], v[48:51]
	v_mfma_f32_16x16x32_bf16 v[36:39], v[182:185], v[206:209], v[36:39]
	v_mfma_f32_16x16x32_bf16 v[32:35], v[190:193], v[206:209], v[32:35]
	v_mfma_f32_16x16x32_bf16 v[20:23], v[182:185], v[214:217], v[20:23]
	v_mfma_f32_16x16x32_bf16 v[16:19], v[190:193], v[214:217], v[16:19]
	v_mfma_f32_16x16x32_bf16 v[4:7], v[182:185], v[222:225], v[4:7]
	v_mfma_f32_16x16x32_bf16 v[0:3], v[190:193], v[222:225], v[0:3]
	v_mfma_f32_16x16x32_bf16 v[52:55], v[186:189], v[202:205], v[52:55]
	v_mfma_f32_16x16x32_bf16 v[48:51], v[194:197], v[202:205], v[48:51]
	v_mfma_f32_16x16x32_bf16 v[36:39], v[186:189], v[210:213], v[36:39]
	v_mfma_f32_16x16x32_bf16 v[32:35], v[194:197], v[210:213], v[32:35]
	v_mfma_f32_16x16x32_bf16 v[20:23], v[186:189], v[218:221], v[20:23]
	v_mfma_f32_16x16x32_bf16 v[16:19], v[194:197], v[218:221], v[16:19]
	v_mfma_f32_16x16x32_bf16 v[4:7], v[186:189], v[226:229], v[4:7]
	v_mfma_f32_16x16x32_bf16 v[0:3], v[194:197], v[226:229], v[0:3]
	s_barrier
	s_add_i32 s71, s71, 2
	s_add_u32 s47, s47, 0x100
	s_addc_u32 s53, s53, 0
	s_cmp_gt_u32 s71, 13
	s_mov_b64 s[54:55], s[42:43]
	s_cbranch_scc0 .LBB0_2015
	s_and_b64 vcc, exec, s[44:45]
	s_cbranch_vccz .LBB0_2018
	s_barrier
